# removed 90 xnack-replay s_nop pads between VMEM ops and 8 no-op setprio 0/1 toggles inside the GEMM MFMA clusters
# baseline (speedup 1.0000x reference)
; __global__ void __launch_bounds__(512, 2) mk_fwd(Args a) {
;     ...
;             for (int task = gw; task < 11 * 129; task += NGW) {
;                 const int cch = task % 11, l0 = (task / 11) * 64, l1 = (l0 + 64 < LSEQ) ? l0 + 64 : LSEQ;
;                 const int c = cch * 512 + lane * 8;
;                 f32x4 wt[3][2][2];
; #pragma unroll
;                 for (int t = 0; t < 3; ++t)
; #pragma unroll
;                     for (int p = 0; p < 2; ++p) { wt[t][p][0] = *(const f32x4*)(cw + t * NUP + p * DFF + c); wt[t][p][1] = *(const f32x4*)(cw + t * NUP + p * DFF + c + 4); }
.LBB0_83:
	s_mul_hi_i32 s0, s6, 0x2e8ba2e9
	s_lshr_b32 s1, s0, 31
	s_ashr_i32 s0, s0, 1
	s_add_i32 s0, s0, s1
	s_lshl_b32 s8, s0, 6
	s_min_i32 s7, s8, 0x1fd0
	s_add_i32 s7, s7, 64
	s_cmp_ge_i32 s8, s7
	s_cbranch_scc1 .LBB0_82
	s_mul_i32 s0, s0, 11
	s_sub_i32 s0, s6, s0
	s_waitcnt vmcnt(0) lgkmcnt(0)
	v_lshl_add_u32 v48, s0, 9, v116
	v_ashrrev_i32_e32 v49, 31, v48
	v_lshl_add_u64 v[40:41], v[48:49], 2, s[2:3]
	s_mov_b64 s[0:1], 0x5800
	v_lshl_add_u64 v[12:13], v[40:41], 0, s[0:1]
	v_add_co_u32_e32 v8, vcc, 0x5000, v40
	s_mov_b64 s[0:1], 0xb000
	s_nop 0
	v_addc_co_u32_e32 v9, vcc, 0, v41, vcc
	v_lshl_add_u64 v[20:21], v[40:41], 0, s[0:1]
	s_mov_b32 s0, 0xb000
	v_add_co_u32_e32 v16, vcc, s0, v40
	s_mov_b64 s[0:1], 0x10800
	s_nop 0
	v_addc_co_u32_e32 v17, vcc, 0, v41, vcc
	v_lshl_add_u64 v[28:29], v[40:41], 0, s[0:1]
	v_add_co_u32_e32 v24, vcc, s73, v40
	s_mov_b64 s[0:1], 0x16000
	s_nop 0
	v_addc_co_u32_e32 v25, vcc, 0, v41, vcc
	v_lshl_add_u64 v[36:37], v[40:41], 0, s[0:1]
	s_mov_b32 s0, 0x16000
	v_add_co_u32_e32 v32, vcc, s0, v40
	s_mov_b64 s[0:1], 0x1b800
	s_nop 0
	v_addc_co_u32_e32 v33, vcc, 0, v41, vcc
	global_load_dwordx4 v[0:3], v[40:41], off offset:16
	global_load_dwordx4 v[4:7], v[40:41], off
	v_lshl_add_u64 v[44:45], v[40:41], 0, s[0:1]
	v_add_co_u32_e32 v40, vcc, 0x1b000, v40
	global_load_dwordx4 v[8:11], v[8:9], off offset:2048
	global_load_dwordx4 v[12:15], v[12:13], off offset:16
	v_addc_co_u32_e32 v41, vcc, 0, v41, vcc
	global_load_dwordx4 v[16:19], v[16:17], off
	global_load_dwordx4 v[20:23], v[20:21], off offset:16
	global_load_dwordx4 v[24:27], v[24:25], off offset:2048
	global_load_dwordx4 v[28:31], v[28:29], off offset:16
	global_load_dwordx4 v[32:35], v[32:33], off
	global_load_dwordx4 v[36:39], v[36:37], off offset:16
	global_load_dwordx4 v[40:43], v[40:41], off offset:2048
	global_load_dwordx4 v[44:47], v[44:45], off offset:16
	v_readlane_b32 s0, v254, 40
	v_lshlrev_b64 v[48:49], 1, v[48:49]
	v_readlane_b32 s1, v254, 41
	v_lshl_add_u64 v[88:89], s[84:85], 0, v[48:49]
	s_ashr_i32 s9, s8, 31
	v_lshl_add_u64 v[90:91], s[0:1], 0, v[48:49]
	s_branch .LBB0_86

; __global__ void __launch_bounds__(512, 2) mk_fwd(Args a) {
;     ...
;                 for (int lb = l0; lb < l1; lb += 4) {
;                     u32x4 x[6][2];
; #pragma unroll
;                     for (int i = 0; i < 6; ++i) { const int lg = lb - 1 + i; const bool ok = lg >= 0 && lg < LSEQ; const bf16_t* p = U + (size_t)(ok ? phys_of(lg) : 0) * NUP + c;
;                         x[i][0] = *(const u32x4*)p; x[i][1] = *(const u32x4*)(p + DFF);
;                         if (!ok) { x[i][0] = (u32x4){0u, 0u, 0u, 0u}; x[i][1] = (u32x4){0u, 0u, 0u, 0u}; } }
.LBB0_88:
	s_waitcnt vmcnt(0) lgkmcnt(0)
	v_lshl_add_u64 v[48:49], s[0:1], 1, v[88:89]
	v_add_co_u32_e32 v52, vcc, 0x2000, v48
	s_cmpk_lt_u32 s8, 0x2010
	s_nop 0
	v_addc_co_u32_e32 v53, vcc, 0, v49, vcc
	flat_load_dwordx4 v[48:51], v[48:49]
	flat_load_dwordx4 v[52:55], v[52:53] offset:3072
	s_cselect_b64 s[0:1], -1, 0
	s_cmpk_gt_u32 s8, 0x200f
	s_cbranch_scc1 .LBB0_90
	s_cmp_gt_u32 s8, 15
	s_cselect_b32 s13, -16, 0x2000
	s_add_i32 s13, s8, s13
	s_mul_i32 s36, s13, 0x2c00
	s_ashr_i32 s37, s36, 31

; __device__ __forceinline__ float bf_lo(unsigned w) { return __uint_as_float(w << 16); }
; __global__ void __launch_bounds__(512, 2) mk_fwd(Args a) {
;     ...
;                 for (int lb = l0; lb < l1; lb += 4) {
;                     u32x4 x[6][2];
; #pragma unroll
;                     for (int i = 0; i < 6; ++i) { const int lg = lb - 1 + i; const bool ok = lg >= 0 && lg < LSEQ; const bf16_t* p = U + (size_t)(ok ? phys_of(lg) : 0) * NUP + c;
;                         x[i][0] = *(const u32x4*)p; x[i][1] = *(const u32x4*)(p + DFF);
;                         if (!ok) { x[i][0] = (u32x4){0u, 0u, 0u, 0u}; x[i][1] = (u32x4){0u, 0u, 0u, 0u}; } }
; #pragma unroll
;                     for (int i = 0; i < 4; ++i) { const int lg = lb + i; if (lg < l1) {
;                         f32x4 av[2], bv[2];
; #pragma unroll
;                         for (int hh = 0; hh < 2; ++hh) {
;                             f32x4 x0, x1, x2, y0, y1, y2;
;                             const unsigned a0 = hh ? x[i][0].z : x[i][0].x, a1 = hh ? x[i][0].w : x[i][0].y, b0 = hh ? x[i + 1][0].z : x[i + 1][0].x, b1 = hh ? x[i + 1][0].w : x[i + 1][0].y, c0 = hh ? x[i + 2][0].z : x[i + 2][0].x, c1 = hh ? x[i + 2][0].w : x[i + 2][0].y;
;                             x0 = (f32x4){bf_lo(a0), bf_hi(a0), bf_lo(a1), bf_hi(a1)}; x1 = (f32x4){bf_lo(b0), bf_hi(b0), bf_lo(b1), bf_hi(b1)}; x2 = (f32x4){bf_lo(c0), bf_hi(c0), bf_lo(c1), bf_hi(c1)};
;                             const unsigned d0 = hh ? x[i][1].z : x[i][1].x, d1 = hh ? x[i][1].w : x[i][1].y, e0 = hh ? x[i + 1][1].z : x[i + 1][1].x, e1 = hh ? x[i + 1][1].w : x[i + 1][1].y, f0 = hh ? x[i + 2][1].z : x[i + 2][1].x, f1 = hh ? x[i + 2][1].w : x[i + 2][1].y;
;                             y0 = (f32x4){bf_lo(d0), bf_hi(d0), bf_lo(d1), bf_hi(d1)}; y1 = (f32x4){bf_lo(e0), bf_hi(e0), bf_lo(e1), bf_hi(e1)}; y2 = (f32x4){bf_lo(f0), bf_hi(f0), bf_lo(f1), bf_hi(f1)};
;                             av[hh] = wt[0][0][hh] * x0 + wt[1][0][hh] * x1 + wt[2][0][hh] * x2;
;                             bv[hh] = wt[0][1][hh] * y0 + wt[1][1][hh] * y1 + wt[2][1][hh] * y2; }
;                         u32x4 o;
;                         o.x = cvt_pk_bf16(av[0][0] * sigm(av[0][0]) * bv[0][0], av[0][1] * sigm(av[0][1]) * bv[0][1]); o.y = cvt_pk_bf16(av[0][2] * sigm(av[0][2]) * bv[0][2], av[0][3] * sigm(av[0][3]) * bv[0][3]);
.LBB0_96:
	v_lshl_add_u64 v[56:57], s[36:37], 1, v[88:89]
	v_add_co_u32_e32 v60, vcc, 0x2000, v56
	s_add_u32 s36, s8, 4
	s_nop 0
	v_addc_co_u32_e32 v61, vcc, 0, v57, vcc
	flat_load_dwordx4 v[56:59], v[56:57]
	flat_load_dwordx4 v[60:63], v[60:61] offset:3072
	s_addc_u32 s37, s9, 0
	s_cmpk_lt_u32 s36, 0x2010
	s_cselect_b64 vcc, -1, 0
	s_cmpk_gt_u32 s36, 0x200f
	s_cbranch_scc1 .LBB0_98
	s_cmp_gt_u32 s36, 15
	s_cselect_b32 s13, -16, 0x2000
	s_add_i32 s13, s8, s13
	s_mulk_i32 s13, 0x2c00
	s_add_i32 s48, s13, 0xb000
	s_ashr_i32 s49, s48, 31
.LBB0_98:
	s_waitcnt vmcnt(0) lgkmcnt(0)
	v_cndmask_b32_e64 v122, 0, v86, s[0:1]
	v_cndmask_b32_e64 v86, 0, v75, s[0:1]
	v_cndmask_b32_e64 v75, 0, v68, s[0:1]
	v_cndmask_b32_e64 v92, 0, v67, s[0:1]
	v_cndmask_b32_e64 v68, 0, v65, s[0:1]
	v_cndmask_b32_e64 v67, 0, v49, s[38:39]
	v_cndmask_b32_e64 v65, 0, v48, s[38:39]
	v_lshl_add_u64 v[48:49], s[48:49], 1, v[88:89]
	v_cndmask_b32_e64 v115, 0, v71, s[0:1]
	v_cndmask_b32_e64 v113, 0, v70, s[0:1]
	v_cndmask_b32_e64 v97, 0, v55, s[38:39]
	v_cndmask_b32_e64 v96, 0, v54, s[38:39]
	v_cndmask_b32_e64 v71, 0, v53, s[38:39]
	v_cndmask_b32_e64 v70, 0, v52, s[38:39]
	v_cndmask_b32_e64 v94, 0, v51, s[38:39]
	v_cndmask_b32_e64 v95, 0, v50, s[38:39]
	v_add_co_u32_e64 v52, s[38:39], s19, v48
	v_cndmask_b32_e64 v117, 0, v87, s[0:1]
	s_nop 0
	v_addc_co_u32_e64 v53, s[38:39], 0, v49, s[38:39]
	flat_load_dwordx4 v[48:51], v[48:49]
	flat_load_dwordx4 v[52:55], v[52:53] offset:3072
	v_cndmask_b32_e64 v87, 0, v74, s[0:1]
	v_cndmask_b32_e64 v74, 0, v69, s[0:1]
	v_cndmask_b32_e64 v69, 0, v64, s[0:1]
	v_lshlrev_b32_e32 v100, 16, v69
	v_and_b32_e32 v101, 0xffff0000, v69
	v_cndmask_b32_e64 v125, 0, v83, s[0:1]
	v_cndmask_b32_e64 v126, 0, v82, s[0:1]
	v_lshlrev_b32_e32 v64, 16, v65
	v_and_b32_e32 v65, 0xffff0000, v65
	v_lshlrev_b32_e32 v104, 16, v75
	v_and_b32_e32 v105, 0xffff0000, v75
	v_pk_mul_f32 v[82:83], v[16:17], v[100:101]
	v_cndmask_b32_e64 v72, 0, v72, s[0:1]
	v_lshlrev_b32_e32 v102, 16, v68
	v_and_b32_e32 v103, 0xffff0000, v68
	v_lshlrev_b32_e32 v68, 16, v70
	v_and_b32_e32 v69, 0xffff0000, v70
	v_pk_fma_f32 v[64:65], v[4:5], v[64:65], v[82:83]
	v_pk_mul_f32 v[82:83], v[24:25], v[104:105]
	v_lshlrev_b32_e32 v110, 16, v92
	v_and_b32_e32 v111, 0xffff0000, v92
	v_cndmask_b32_e64 v123, 0, v85, s[0:1]
	v_cndmask_b32_e64 v124, 0, v84, s[0:1]
	v_cndmask_b32_e64 v85, 0, v79, s[0:1]
	v_cndmask_b32_e64 v84, 0, v78, s[0:1]
	v_cndmask_b32_e64 v93, 0, v66, s[0:1]
	v_lshlrev_b32_e32 v78, 16, v72
	v_and_b32_e32 v79, 0xffff0000, v72
	v_pk_fma_f32 v[68:69], v[8:9], v[68:69], v[82:83]
	v_lshlrev_b32_e32 v82, 16, v94
	v_and_b32_e32 v83, 0xffff0000, v94
	v_lshlrev_b32_e32 v114, 16, v115
	v_and_b32_e32 v115, 0xffff0000, v115
	v_pk_mul_f32 v[118:119], v[22:23], v[110:111]
	v_pk_fma_f32 v[64:65], v[32:33], v[78:79], v[64:65]
	v_lshlrev_b32_e32 v108, 16, v93
	v_and_b32_e32 v109, 0xffff0000, v93
	v_lshlrev_b32_e32 v92, 16, v96
	v_and_b32_e32 v93, 0xffff0000, v96
	v_lshlrev_b32_e32 v96, 16, v97
	v_and_b32_e32 v97, 0xffff0000, v97
	v_pk_fma_f32 v[82:83], v[2:3], v[82:83], v[118:119]
	v_pk_mul_f32 v[118:119], v[30:31], v[114:115]
	v_cndmask_b32_e64 v127, 0, v81, s[0:1]
	v_pk_fma_f32 v[96:97], v[14:15], v[96:97], v[118:119]
	v_mul_f32_e32 v118, 0xbfb8aa3b, v64
	v_exp_f32_e32 v118, v118
	v_mul_f32_e32 v119, 0xbfb8aa3b, v65
	v_exp_f32_e32 v119, v119
	v_cndmask_b32_e64 v128, 0, v80, s[0:1]
	v_add_f32_e32 v118, 1.0, v118
	v_rcp_f32_e32 v118, v118
	v_cndmask_b32_e64 v80, 0, v77, s[0:1]
	v_cndmask_b32_e64 v81, 0, v76, s[0:1]
	v_cndmask_b32_e64 v73, 0, v73, s[0:1]
	v_lshlrev_b32_e32 v66, 16, v67
	v_and_b32_e32 v67, 0xffff0000, v67
	v_lshlrev_b32_e32 v76, 16, v73
	v_and_b32_e32 v77, 0xffff0000, v73
	v_lshlrev_b32_e32 v106, 16, v74
	v_and_b32_e32 v107, 0xffff0000, v74
	v_lshlrev_b32_e32 v74, 16, v81
	v_and_b32_e32 v75, 0xffff0000, v81
	v_lshlrev_b32_e32 v72, 16, v80
	v_and_b32_e32 v73, 0xffff0000, v80
	v_pk_mul_f32 v[80:81], v[18:19], v[102:103]
	v_pk_fma_f32 v[68:69], v[40:41], v[74:75], v[68:69]
	v_pk_fma_f32 v[66:67], v[6:7], v[66:67], v[80:81]
	v_add_f32_e32 v119, 1.0, v119
	v_pk_fma_f32 v[66:67], v[34:35], v[76:77], v[66:67]
	v_mul_f32_e32 v64, v64, v118
	v_rcp_f32_e32 v119, v119
	v_mul_f32_e32 v64, v68, v64
	v_mul_f32_e32 v68, 0xbfb8aa3b, v66
	v_mul_f32_e32 v118, 0xbfb8aa3b, v67
	v_exp_f32_e32 v68, v68
	v_exp_f32_e32 v118, v118
	v_mul_f32_e32 v65, v65, v119
	v_mul_f32_e32 v65, v69, v65
	v_add_f32_e32 v68, 1.0, v68
	v_add_f32_e32 v69, 1.0, v118
	v_lshlrev_b32_e32 v70, 16, v71
	v_and_b32_e32 v71, 0xffff0000, v71
	v_pk_mul_f32 v[80:81], v[26:27], v[106:107]
	v_rcp_f32_e32 v68, v68
	v_rcp_f32_e32 v69, v69
	v_pk_fma_f32 v[70:71], v[10:11], v[70:71], v[80:81]
	v_lshlrev_b32_e32 v80, 16, v95
	v_and_b32_e32 v81, 0xffff0000, v95
	v_pk_mul_f32 v[120:121], v[20:21], v[108:109]
	v_lshlrev_b32_e32 v98, 16, v87
	v_and_b32_e32 v99, 0xffff0000, v87
	v_pk_fma_f32 v[80:81], v[0:1], v[80:81], v[120:121]
	v_cvt_pk_bf16_f32 v64, v64, v65
	v_mul_f32_e32 v65, v66, v68
	v_pk_fma_f32 v[80:81], v[36:37], v[98:99], v[80:81]
	v_mul_f32_e32 v66, v67, v69
	v_mul_f32_e32 v67, 0xbfb8aa3b, v80
	v_mul_f32_e32 v68, 0xbfb8aa3b, v81
	v_exp_f32_e32 v67, v67
	v_exp_f32_e32 v68, v68
	v_pk_fma_f32 v[70:71], v[42:43], v[72:73], v[70:71]
	v_lshlrev_b32_e32 v94, 16, v86
	v_add_f32_e32 v67, 1.0, v67
	v_add_f32_e32 v68, 1.0, v68
; __device__ __forceinline__ unsigned cvt_pk_bf16(float lo, float hi) { unsigned r; asm volatile("v_cvt_pk_bf16_f32 %0, %1, %2" : "=v"(r) : "v"(lo), "v"(hi)); return r; }
; __device__ __forceinline__ float bf_lo(unsigned w) { return __uint_as_float(w << 16); }
; __device__ __forceinline__ float bf_hi(unsigned w) { return __uint_as_float(w & 0xffff0000u); }
; __global__ void __launch_bounds__(512, 2) mk_fwd(Args a) {
;     ...
;                     for (int i = 0; i < 4; ++i) { const int lg = lb + i; if (lg < l1) {
;                         f32x4 av[2], bv[2];
; #pragma unroll
;                         for (int hh = 0; hh < 2; ++hh) {
;                             f32x4 x0, x1, x2, y0, y1, y2;
;                             const unsigned a0 = hh ? x[i][0].z : x[i][0].x, a1 = hh ? x[i][0].w : x[i][0].y, b0 = hh ? x[i + 1][0].z : x[i + 1][0].x, b1 = hh ? x[i + 1][0].w : x[i + 1][0].y, c0 = hh ? x[i + 2][0].z : x[i + 2][0].x, c1 = hh ? x[i + 2][0].w : x[i + 2][0].y;
;                             x0 = (f32x4){bf_lo(a0), bf_hi(a0), bf_lo(a1), bf_hi(a1)}; x1 = (f32x4){bf_lo(b0), bf_hi(b0), bf_lo(b1), bf_hi(b1)}; x2 = (f32x4){bf_lo(c0), bf_hi(c0), bf_lo(c1), bf_hi(c1)};
;                             const unsigned d0 = hh ? x[i][1].z : x[i][1].x, d1 = hh ? x[i][1].w : x[i][1].y, e0 = hh ? x[i + 1][1].z : x[i + 1][1].x, e1 = hh ? x[i + 1][1].w : x[i + 1][1].y, f0 = hh ? x[i + 2][1].z : x[i + 2][1].x, f1 = hh ? x[i + 2][1].w : x[i + 2][1].y;
;                             y0 = (f32x4){bf_lo(d0), bf_hi(d0), bf_lo(d1), bf_hi(d1)}; y1 = (f32x4){bf_lo(e0), bf_hi(e0), bf_lo(e1), bf_hi(e1)}; y2 = (f32x4){bf_lo(f0), bf_hi(f0), bf_lo(f1), bf_hi(f1)};
;                             av[hh] = wt[0][0][hh] * x0 + wt[1][0][hh] * x1 + wt[2][0][hh] * x2;
;                             bv[hh] = wt[0][1][hh] * y0 + wt[1][1][hh] * y1 + wt[2][1][hh] * y2; }
;                         u32x4 o;
;                         o.x = cvt_pk_bf16(av[0][0] * sigm(av[0][0]) * bv[0][0], av[0][1] * sigm(av[0][1]) * bv[0][1]); o.y = cvt_pk_bf16(av[0][2] * sigm(av[0][2]) * bv[0][2], av[0][3] * sigm(av[0][3]) * bv[0][3]);
;                         o.z = cvt_pk_bf16(av[1][0] * sigm(av[1][0]) * bv[1][0], av[1][1] * sigm(av[1][1]) * bv[1][1]); o.w = cvt_pk_bf16(av[1][2] * sigm(av[1][2]) * bv[1][2], av[1][3] * sigm(av[1][3]) * bv[1][3]);
;                         *(u32x4*)(GT + (size_t)phys_of(lg) * DFF + c) = o; } }
	v_rcp_f32_e32 v67, v67
	v_rcp_f32_e32 v68, v68
	v_and_b32_e32 v95, 0xffff0000, v86
	v_pk_fma_f32 v[82:83], v[38:39], v[94:95], v[82:83]
	v_mul_f32_e32 v65, v70, v65
	v_mul_f32_e32 v66, v71, v66
	v_cvt_pk_bf16_f32 v65, v65, v66
	v_mul_f32_e32 v66, v80, v67
	v_mul_f32_e32 v67, v81, v68
	v_mul_f32_e32 v68, 0xbfb8aa3b, v82
	v_mul_f32_e32 v69, 0xbfb8aa3b, v83
	v_exp_f32_e32 v68, v68
	v_exp_f32_e32 v69, v69
	v_lshlrev_b32_e32 v112, 16, v113
	v_and_b32_e32 v113, 0xffff0000, v113
	v_add_f32_e32 v68, 1.0, v68
	v_add_f32_e32 v69, 1.0, v69
	v_pk_mul_f32 v[120:121], v[28:29], v[112:113]
	v_rcp_f32_e32 v68, v68
	v_rcp_f32_e32 v69, v69
	v_lshlrev_b32_e32 v86, 16, v84
	v_and_b32_e32 v87, 0xffff0000, v84
	v_pk_fma_f32 v[92:93], v[12:13], v[92:93], v[120:121]
	s_cmp_gt_i32 s8, 15
	v_pk_fma_f32 v[92:93], v[44:45], v[86:87], v[92:93]
	v_lshlrev_b32_e32 v84, 16, v85
	v_and_b32_e32 v85, 0xffff0000, v85
	v_mul_f32_e32 v66, v92, v66
	v_mul_f32_e32 v67, v93, v67
	s_cselect_b32 s18, -16, 0x2000
	v_pk_fma_f32 v[96:97], v[46:47], v[84:85], v[96:97]
	v_cvt_pk_bf16_f32 v66, v66, v67
	v_mul_f32_e32 v67, v82, v68
	v_mul_f32_e32 v68, v83, v69
	s_cselect_b32 s13, -1, 0
	s_add_u32 s18, s8, s18
	v_mul_f32_e32 v67, v96, v67
	v_mul_f32_e32 v68, v97, v68
	s_addc_u32 s13, s9, s13
	v_cvt_pk_bf16_f32 v67, v67, v68
	s_mulk_i32 s13, 0x2c00
	v_mad_u64_u32 v[68:69], s[28:29], s18, v204, v[90:91]
	v_add_u32_e32 v69, s13, v69
	s_add_i32 s13, s8, 1
	global_store_dwordx4 v[68:69], v[64:67], off
	s_cmp_ge_i32 s13, s7
	v_lshlrev_b32_e32 v96, 16, v128
	v_and_b32_e32 v97, 0xffff0000, v128
	v_lshlrev_b32_e32 v92, 16, v127
	v_and_b32_e32 v93, 0xffff0000, v127
	v_lshlrev_b32_e32 v82, 16, v124
	v_and_b32_e32 v83, 0xffff0000, v124
	v_lshlrev_b32_e32 v80, 16, v123
	v_and_b32_e32 v81, 0xffff0000, v123
	v_lshlrev_b32_e32 v70, 16, v126
	v_and_b32_e32 v71, 0xffff0000, v126
	v_lshlrev_b32_e32 v68, 16, v125
	v_and_b32_e32 v69, 0xffff0000, v125
	v_lshlrev_b32_e32 v66, 16, v122
	v_and_b32_e32 v67, 0xffff0000, v122
	v_lshlrev_b32_e32 v64, 16, v117
	v_and_b32_e32 v65, 0xffff0000, v117
	s_cbranch_scc1 .LBB0_100
	v_pk_mul_f32 v[120:121], v[16:17], v[78:79]
	v_pk_mul_f32 v[118:119], v[18:19], v[76:77]
	v_pk_fma_f32 v[100:101], v[4:5], v[100:101], v[120:121]
	v_pk_fma_f32 v[102:103], v[6:7], v[102:103], v[118:119]
	v_pk_fma_f32 v[100:101], v[32:33], v[96:97], v[100:101]
	v_pk_mul_f32 v[118:119], v[26:27], v[72:73]
	v_mul_f32_e32 v117, 0xbfb8aa3b, v100
	v_exp_f32_e32 v117, v117
	v_pk_fma_f32 v[106:107], v[10:11], v[106:107], v[118:119]
	v_pk_mul_f32 v[118:119], v[22:23], v[94:95]
	v_pk_mul_f32 v[120:121], v[24:25], v[74:75]
	v_pk_fma_f32 v[110:111], v[2:3], v[110:111], v[118:119]
	v_pk_mul_f32 v[118:119], v[30:31], v[84:85]
	v_add_f32_e32 v117, 1.0, v117
	v_pk_fma_f32 v[114:115], v[14:15], v[114:115], v[118:119]
	v_mul_f32_e32 v118, 0xbfb8aa3b, v101
	v_exp_f32_e32 v118, v118
	v_rcp_f32_e32 v117, v117
	v_pk_fma_f32 v[104:105], v[8:9], v[104:105], v[120:121]
	v_pk_fma_f32 v[102:103], v[34:35], v[92:93], v[102:103]
	v_pk_fma_f32 v[104:105], v[40:41], v[82:83], v[104:105]
	v_add_f32_e32 v118, 1.0, v118
	v_mul_f32_e32 v100, v100, v117
	v_rcp_f32_e32 v118, v118
	v_mul_f32_e32 v100, v104, v100
	v_mul_f32_e32 v104, 0xbfb8aa3b, v102
	v_mul_f32_e32 v117, 0xbfb8aa3b, v103
	v_exp_f32_e32 v104, v104
	v_exp_f32_e32 v117, v117
	v_mul_f32_e32 v101, v101, v118
	v_mul_f32_e32 v101, v105, v101
	v_add_f32_e32 v104, 1.0, v104
	v_add_f32_e32 v105, 1.0, v117
	v_rcp_f32_e32 v104, v104
	v_rcp_f32_e32 v105, v105
	v_pk_mul_f32 v[120:121], v[20:21], v[98:99]
	v_cvt_pk_bf16_f32 v100, v100, v101
	v_mul_f32_e32 v101, v102, v104
	v_pk_fma_f32 v[108:109], v[0:1], v[108:109], v[120:121]
	v_mul_f32_e32 v102, v103, v105
	v_pk_fma_f32 v[108:109], v[36:37], v[70:71], v[108:109]
	v_pk_fma_f32 v[106:107], v[42:43], v[80:81], v[106:107]
	v_mul_f32_e32 v103, 0xbfb8aa3b, v108
	v_mul_f32_e32 v104, 0xbfb8aa3b, v109
	v_exp_f32_e32 v103, v103
	v_exp_f32_e32 v104, v104
	v_pk_fma_f32 v[110:111], v[38:39], v[68:69], v[110:111]
	v_mul_f32_e32 v101, v106, v101
	v_add_f32_e32 v103, 1.0, v103
	v_add_f32_e32 v104, 1.0, v104
	v_rcp_f32_e32 v103, v103
	v_rcp_f32_e32 v104, v104
	v_mul_f32_e32 v102, v107, v102
	v_cvt_pk_bf16_f32 v101, v101, v102
	v_mul_f32_e32 v102, v108, v103
	v_mul_f32_e32 v103, v109, v104
	v_mul_f32_e32 v104, 0xbfb8aa3b, v110
	v_mul_f32_e32 v105, 0xbfb8aa3b, v111
	v_exp_f32_e32 v104, v104
	v_exp_f32_e32 v105, v105
	v_pk_mul_f32 v[120:121], v[28:29], v[86:87]
	s_cmp_gt_i32 s8, 14
	v_add_f32_e32 v104, 1.0, v104
	v_add_f32_e32 v105, 1.0, v105
	v_rcp_f32_e32 v104, v104
	v_rcp_f32_e32 v105, v105
	v_pk_fma_f32 v[112:113], v[12:13], v[112:113], v[120:121]
	s_cselect_b32 s18, -16, 0x2000
	v_pk_fma_f32 v[112:113], v[44:45], v[66:67], v[112:113]
	s_cselect_b32 s13, -1, 0
	s_add_u32 s18, s8, s18
	v_mul_f32_e32 v102, v112, v102
	v_mul_f32_e32 v103, v113, v103
	s_addc_u32 s13, s9, s13
	v_pk_fma_f32 v[114:115], v[46:47], v[64:65], v[114:115]
	v_cvt_pk_bf16_f32 v102, v102, v103
	v_mul_f32_e32 v103, v110, v104
	v_mul_f32_e32 v104, v111, v105
	s_add_u32 s18, s18, 1
	v_mul_f32_e32 v103, v114, v103
	v_mul_f32_e32 v104, v115, v104
	s_addc_u32 s13, s13, 0
	v_cvt_pk_bf16_f32 v103, v103, v104
	s_mulk_i32 s13, 0x2c00
	v_mad_u64_u32 v[104:105], s[28:29], s18, v204, v[90:91]
	v_add_u32_e32 v105, s13, v105
	global_store_dwordx4 v[104:105], v[100:103], off

; __device__ __forceinline__ u32x4 pack8(f32x4 v0, f32x4 v1) { u32x4 w; w.x = cvt_pk_bf16(v0[0], v0[1]); w.y = cvt_pk_bf16(v0[2], v0[3]); w.z = cvt_pk_bf16(v1[0], v1[1]); w.w = cvt_pk_bf16(v1[2], v1[3]); return w; }
; __global__ void __launch_bounds__(512, 2) mk_fwd(Args a) {
;     ...
;                 for (int r = gw; r < LSEQ; r += NGW) {
;                     f32x4 v[8]; float s = 0.f; const float* hr = H + (size_t)r * DM;
; #pragma unroll
;                     for (int j = 0; j < 8; ++j) { v[j] = *(const f32x4*)(hr + (lane + 64 * (j >> 1)) * 8 + (j & 1) * 4); s += (v[j].x * v[j].x + v[j].y * v[j].y) + (v[j].z * v[j].z + v[j].w * v[j].w); }
;                     const float rs = __builtin_amdgcn_rsqf(wave_sum(s, lane) * (1.f / DM) + EPS);
; #pragma unroll
;                     for (int j = 0; j < 4; ++j) { const int c = (lane + 64 * j) * 8; const f32x4 g0 = *(const f32x4*)(gm + c), g1 = *(const f32x4*)(gm + c + 4);
;                         *(u32x4*)(X + (size_t)r * DM + c) = pg8::pack8(v[2 * j] * rs * g0, v[2 * j + 1] * rs * g1); }
;                 }
.LBB0_110:
	s_nop 0
	v_lshl_add_u64 v[0:1], s[64:65], 0, v[44:45]
	v_add_co_u32_e32 v0, vcc, 0x9901000, v0
	s_add_i32 s0, s0, s72
	s_nop 0
	v_addc_co_u32_e32 v1, vcc, 0, v1, vcc
	global_load_dwordx4 v[28:31], v[0:1], off
	global_load_dwordx4 v[24:27], v[0:1], off offset:16
	v_lshl_add_u64 v[44:45], v[44:45], 0, s[4:5]
	s_cmpk_gt_i32 s0, 0x200f
	s_waitcnt vmcnt(0) lgkmcnt(0)
	v_mov_b32_e32 v4, v29
	v_mov_b32_e32 v5, v25
	v_mov_b32_e32 v2, v28
	v_mov_b32_e32 v3, v24
	v_pk_mul_f32 v[4:5], v[4:5], v[4:5]
	v_mov_b32_e32 v6, v31
	v_mov_b32_e32 v7, v27
	v_pk_fma_f32 v[2:3], v[2:3], v[2:3], v[4:5]
	v_mov_b32_e32 v4, v30
	v_mov_b32_e32 v5, v26
	v_pk_mul_f32 v[6:7], v[6:7], v[6:7]
	s_nop 0
	v_pk_fma_f32 v[4:5], v[4:5], v[4:5], v[6:7]
	s_nop 0
	v_pk_add_f32 v[12:13], v[2:3], v[4:5]
	global_load_dwordx4 v[4:7], v[0:1], off offset:2048
	v_pk_add_f32 v[12:13], v[12:13], v[12:13] op_sel:[0,1] op_sel_hi:[1,0]
	s_waitcnt vmcnt(0) lgkmcnt(0)
	v_pk_mul_f32 v[2:3], v[6:7], v[6:7]
	v_pk_mul_f32 v[8:9], v[4:5], v[4:5]
	s_nop 0
	v_pk_mov_b32 v[10:11], v[8:9], v[2:3] op_sel:[1,0]
	v_mov_b32_e32 v9, v3
	v_pk_add_f32 v[14:15], v[10:11], v[8:9]
	v_lshl_add_u64 v[8:9], s[64:65], 0, v[42:43]
	v_add_co_u32_e32 v16, vcc, s6, v8
	global_load_dwordx4 v[0:3], v[0:1], off offset:2064
	s_nop 0
	v_addc_co_u32_e32 v17, vcc, 0, v9, vcc
	global_load_dwordx4 v[8:11], v[16:17], off
	v_pk_add_f32 v[14:15], v[14:15], v[14:15] op_sel:[0,1] op_sel_hi:[1,0]
	v_lshl_add_u64 v[42:43], v[42:43], 0, s[4:5]
	s_waitcnt vmcnt(0) lgkmcnt(0)
	v_mul_f32_e32 v18, v8, v8
	v_mul_f32_e32 v19, v9, v9
	v_mov_b32_e32 v13, v18
	v_mov_b32_e32 v15, v19
	v_pk_add_f32 v[12:13], v[12:13], v[14:15]
	v_mul_f32_e32 v14, v1, v1
	v_mul_f32_e32 v18, v3, v3
	v_mul_f32_e32 v20, v10, v10
	v_mul_f32_e32 v21, v11, v11
	v_pk_fma_f32 v[14:15], v[0:1], v[0:1], v[14:15] op_sel_hi:[1,1,0]
	v_pk_fma_f32 v[18:19], v[2:3], v[2:3], v[18:19] op_sel_hi:[1,1,0]
	v_mov_b32_e32 v15, v20
	v_mov_b32_e32 v19, v21
	v_pk_add_f32 v[14:15], v[14:15], v[18:19]
	s_nop 0
	v_pk_add_f32 v[54:55], v[12:13], v[14:15]
	global_load_dwordx4 v[12:15], v[16:17], off offset:16
	v_pk_add_f32 v[54:55], v[54:55], v[54:55] op_sel:[0,1] op_sel_hi:[1,0]
	s_waitcnt vmcnt(0) lgkmcnt(0)
	v_pk_mul_f32 v[16:17], v[14:15], v[14:15]
	v_pk_mul_f32 v[18:19], v[12:13], v[12:13]
	s_nop 0
	v_pk_mov_b32 v[20:21], v[18:19], v[16:17] op_sel:[1,0]
	v_mov_b32_e32 v19, v17
	v_lshl_add_u64 v[16:17], s[64:65], 0, v[40:41]
	v_add_co_u32_e32 v16, vcc, s6, v16
	v_pk_add_f32 v[56:57], v[20:21], v[18:19]
	s_nop 0
	v_addc_co_u32_e32 v17, vcc, 0, v17, vcc
	global_load_dwordx4 v[20:23], v[16:17], off
	global_load_dwordx4 v[16:19], v[16:17], off offset:16
	v_pk_add_f32 v[56:57], v[56:57], v[56:57] op_sel:[0,1] op_sel_hi:[1,0]
	v_lshl_add_u64 v[40:41], v[40:41], 0, s[4:5]
	s_waitcnt vmcnt(0) lgkmcnt(0)
	v_mul_f32_e32 v46, v16, v16
	v_mul_f32_e32 v53, v17, v17
	v_mov_b32_e32 v55, v46
	v_mov_b32_e32 v57, v53
	v_mul_f32_e32 v46, v21, v21
	v_mul_f32_e32 v58, v18, v18
	v_pk_add_f32 v[54:55], v[54:55], v[56:57]
	v_pk_fma_f32 v[56:57], v[20:21], v[20:21], v[46:47] op_sel_hi:[1,1,0]
	v_mul_f32_e32 v46, v23, v23
	v_mul_f32_e32 v60, v19, v19
	v_mov_b32_e32 v57, v58
	v_pk_fma_f32 v[58:59], v[22:23], v[22:23], v[46:47] op_sel_hi:[1,1,0]
	s_nop 0
	v_mov_b32_e32 v59, v60
	v_pk_add_f32 v[56:57], v[56:57], v[58:59]
	s_nop 0
	v_pk_add_f32 v[54:55], v[54:55], v[56:57]
	s_nop 0
	v_add_f32_e32 v46, v54, v55
	global_load_dwordx4 v[54:57], v[32:33], off offset:16
	global_load_dwordx4 v[58:61], v[32:33], off
	ds_bpermute_b32 v53, v47, v46
	s_waitcnt lgkmcnt(0)
	v_add_f32_e32 v46, v46, v53
	ds_bpermute_b32 v53, v48, v46
	s_waitcnt lgkmcnt(0)
	v_add_f32_e32 v46, v46, v53
	ds_bpermute_b32 v53, v49, v46
	s_waitcnt lgkmcnt(0)
	v_add_f32_e32 v46, v46, v53
	ds_bpermute_b32 v53, v50, v46
	s_waitcnt lgkmcnt(0)
	v_add_f32_e32 v46, v46, v53
	ds_bpermute_b32 v53, v51, v46
	s_waitcnt lgkmcnt(0)
	v_add_f32_e32 v46, v46, v53
	ds_bpermute_b32 v53, v52, v46
	s_waitcnt lgkmcnt(0)
	v_add_f32_e32 v46, v46, v53
	v_fmamk_f32 v46, v46, 0x3a000000, v202
	v_rsq_f32_e32 v46, v46
	s_nop 0
	v_pk_mul_f32 v[28:29], v[46:47], v[28:29] op_sel_hi:[0,1]
	v_pk_mul_f32 v[24:25], v[46:47], v[24:25] op_sel_hi:[0,1]
	v_pk_mul_f32 v[26:27], v[46:47], v[26:27] op_sel_hi:[0,1]
	v_pk_mul_f32 v[30:31], v[46:47], v[30:31] op_sel_hi:[0,1]
	v_pk_mul_f32 v[0:1], v[46:47], v[0:1] op_sel_hi:[0,1]
	v_pk_mul_f32 v[2:3], v[46:47], v[2:3] op_sel_hi:[0,1]
	v_pk_mul_f32 v[4:5], v[46:47], v[4:5] op_sel_hi:[0,1]
	v_pk_mul_f32 v[6:7], v[46:47], v[6:7] op_sel_hi:[0,1]
	v_pk_mul_f32 v[8:9], v[46:47], v[8:9] op_sel_hi:[0,1]
	v_pk_mul_f32 v[10:11], v[46:47], v[10:11] op_sel_hi:[0,1]
	s_waitcnt vmcnt(1)
	v_pk_mul_f32 v[56:57], v[56:57], v[26:27]
	s_waitcnt vmcnt(0)
	v_pk_mul_f32 v[28:29], v[58:59], v[28:29]
	v_pk_mul_f32 v[26:27], v[54:55], v[24:25]
	v_cvt_pk_bf16_f32 v24, v28, v29
	v_lshl_add_u64 v[28:29], s[64:65], 0, v[38:39]
	v_add_co_u32_e32 v28, vcc, s7, v28
	v_pk_mul_f32 v[30:31], v[60:61], v[30:31]
	s_nop 0
	v_addc_co_u32_e32 v29, vcc, 0, v29, vcc
	v_cvt_pk_bf16_f32 v25, v30, v31
	v_cvt_pk_bf16_f32 v26, v26, v27
	v_cvt_pk_bf16_f32 v27, v56, v57
	global_store_dwordx4 v[28:29], v[24:27], off
	global_load_dwordx4 v[24:27], v[32:33], off offset:2064
	global_load_dwordx4 v[54:57], v[32:33], off offset:2048
	v_lshl_add_u64 v[38:39], v[38:39], 0, s[2:3]
	s_waitcnt vmcnt(0)
	v_pk_mul_f32 v[26:27], v[26:27], v[2:3]
	v_pk_mul_f32 v[2:3], v[24:25], v[0:1]
	v_pk_mul_f32 v[6:7], v[56:57], v[6:7]
	v_pk_mul_f32 v[4:5], v[54:55], v[4:5]
	s_nop 0
	v_cvt_pk_bf16_f32 v0, v4, v5
	v_cvt_pk_bf16_f32 v1, v6, v7
	v_cvt_pk_bf16_f32 v2, v2, v3
	v_cvt_pk_bf16_f32 v3, v26, v27
	global_store_dwordx4 v[28:29], v[0:3], off offset:1024
	global_load_dwordx4 v[0:3], v[34:35], off offset:16
	global_load_dwordx4 v[4:7], v[34:35], off
	s_waitcnt vmcnt(0)
	v_pk_mul_f32 v[6:7], v[6:7], v[10:11]
	v_pk_mul_f32 v[4:5], v[4:5], v[8:9]
	v_pk_mul_f32 v[8:9], v[46:47], v[12:13] op_sel_hi:[0,1]
	v_pk_mul_f32 v[10:11], v[46:47], v[14:15] op_sel_hi:[0,1]
	v_pk_mul_f32 v[10:11], v[2:3], v[10:11]
	v_pk_mul_f32 v[2:3], v[0:1], v[8:9]
	v_cvt_pk_bf16_f32 v0, v4, v5
	v_cvt_pk_bf16_f32 v1, v6, v7
	v_pk_mul_f32 v[8:9], v[46:47], v[20:21] op_sel_hi:[0,1]
	v_cvt_pk_bf16_f32 v2, v2, v3
	v_cvt_pk_bf16_f32 v3, v10, v11
	global_store_dwordx4 v[28:29], v[0:3], off offset:2048
	global_load_dwordx4 v[0:3], v[36:37], off offset:16
	global_load_dwordx4 v[4:7], v[36:37], off
	v_pk_mul_f32 v[10:11], v[46:47], v[22:23] op_sel_hi:[0,1]
	s_waitcnt vmcnt(0)
	v_pk_mul_f32 v[6:7], v[6:7], v[10:11]
	v_pk_mul_f32 v[4:5], v[4:5], v[8:9]
	v_pk_mul_f32 v[8:9], v[46:47], v[16:17] op_sel_hi:[0,1]
	v_pk_mul_f32 v[10:11], v[46:47], v[18:19] op_sel_hi:[0,1]
	v_pk_mul_f32 v[10:11], v[2:3], v[10:11]
	v_pk_mul_f32 v[2:3], v[0:1], v[8:9]
	v_cvt_pk_bf16_f32 v0, v4, v5
	v_cvt_pk_bf16_f32 v1, v6, v7
	s_nop 0
	v_cvt_pk_bf16_f32 v2, v2, v3
	v_cvt_pk_bf16_f32 v3, v10, v11
	global_store_dwordx4 v[28:29], v[0:3], off offset:3072
	s_cbranch_scc0 .LBB0_110

; __device__ __forceinline__ unsigned addpair(unsigned x, unsigned y, float sg) { return cvt_pk_bf16(bf_lo(x) + sg * bf_lo(y), bf_hi(x) + sg * bf_hi(y)); }
; __global__ void __launch_bounds__(512, 2) mk_fwd(Args a) {
;     ...
;             for (int r = gw; r < LSEQ; r += NGW) {
;                 const bool v = r < LSEQ; const int kk = v ? pos_of(r) : 0; const bool up = kk > HF; const int kf = up ? LSEQ - kk : kk;
;                 const bf16_t* u = UW + (size_t)kf * 1024; const bf16_t* w = UW + (size_t)MH * 1024 + (size_t)kf * 1024;
; #pragma unroll
;                 for (int j = 0; j < 2; ++j) { const int c = (lane + 64 * j) * 8; u32x4 o = {0u, 0u, 0u, 0u};
;                     if (v) { const u32x4 x = *(const u32x4*)(u + c), y = *(const u32x4*)(w + c); const float sg = up ? 1.f : -1.f;
;                         o.x = addpair(x.x, y.x, sg); o.y = addpair(x.y, y.y, sg); o.z = addpair(x.z, y.z, sg); o.w = addpair(x.w, y.w, sg); }
;                     *(u32x4*)(CC + (size_t)r * 1024 + c) = o; }
.LBB0_121:
	s_cmpk_lt_i32 s1, 0x2000
	s_cselect_b32 s6, 16, 0xffffe000
	s_add_i32 s8, s6, s1
	s_sub_i32 s9, s0, s6
	s_cmpk_gt_i32 s8, 0x1008
	s_cselect_b64 s[6:7], -1, 0
	v_cndmask_b32_e64 v18, -1.0, 1.0, s[6:7]
	s_and_b64 s[6:7], s[6:7], exec
	s_cselect_b32 s6, s9, s8
	s_ashr_i32 s7, s6, 31
	s_lshl_b64 s[6:7], s[6:7], 11
	v_lshl_add_u64 v[14:15], v[0:1], 0, s[6:7]
	v_lshl_add_u64 v[16:17], v[2:3], 0, s[6:7]
	global_load_dwordx4 v[6:9], v[14:15], off
	global_load_dwordx4 v[10:13], v[16:17], off
	s_add_i32 s1, s1, s72
	s_sub_i32 s0, s0, s72
	s_cmpk_gt_i32 s1, 0x200f
	s_waitcnt vmcnt(0) lgkmcnt(0)
	v_lshlrev_b32_e32 v19, 16, v6
	v_lshlrev_b32_e32 v20, 16, v10
	v_and_b32_e32 v6, 0xffff0000, v6
	v_and_b32_e32 v10, 0xffff0000, v10
	v_lshlrev_b32_e32 v21, 16, v7
	v_lshlrev_b32_e32 v22, 16, v11
	v_and_b32_e32 v7, 0xffff0000, v7
	v_and_b32_e32 v11, 0xffff0000, v11
	v_lshlrev_b32_e32 v23, 16, v8
	v_lshlrev_b32_e32 v24, 16, v12
	v_and_b32_e32 v8, 0xffff0000, v8
	v_and_b32_e32 v12, 0xffff0000, v12
	v_lshlrev_b32_e32 v25, 16, v9
	v_lshlrev_b32_e32 v26, 16, v13
	v_and_b32_e32 v9, 0xffff0000, v9
	v_and_b32_e32 v13, 0xffff0000, v13
	v_fmac_f32_e32 v6, v18, v10
	v_fmac_f32_e32 v7, v18, v11
	v_fmac_f32_e32 v8, v18, v12
	v_fmac_f32_e32 v9, v18, v13
	v_fmac_f32_e32 v19, v18, v20
	v_fmac_f32_e32 v21, v18, v22
	v_fmac_f32_e32 v23, v18, v24
	v_fmac_f32_e32 v25, v18, v26
	v_cvt_pk_bf16_f32 v6, v19, v6
	v_cvt_pk_bf16_f32 v7, v21, v7
	v_cvt_pk_bf16_f32 v8, v23, v8
	v_cvt_pk_bf16_f32 v9, v25, v9
	global_store_dwordx4 v[4:5], v[6:9], off
	global_load_dwordx4 v[6:9], v[14:15], off offset:1024
	global_load_dwordx4 v[10:13], v[16:17], off offset:1024
	s_waitcnt vmcnt(0) lgkmcnt(0)
	v_lshlrev_b32_e32 v14, 16, v6
	v_lshlrev_b32_e32 v15, 16, v10
	v_and_b32_e32 v6, 0xffff0000, v6
	v_and_b32_e32 v10, 0xffff0000, v10
	v_lshlrev_b32_e32 v16, 16, v7
	v_lshlrev_b32_e32 v17, 16, v11
	v_and_b32_e32 v7, 0xffff0000, v7
	v_and_b32_e32 v11, 0xffff0000, v11
	v_lshlrev_b32_e32 v19, 16, v8
	v_lshlrev_b32_e32 v20, 16, v12
	v_and_b32_e32 v8, 0xffff0000, v8
	v_and_b32_e32 v12, 0xffff0000, v12
	v_lshlrev_b32_e32 v21, 16, v9
	v_lshlrev_b32_e32 v22, 16, v13
	v_and_b32_e32 v9, 0xffff0000, v9
	v_and_b32_e32 v13, 0xffff0000, v13
	v_fmac_f32_e32 v6, v18, v10
	v_fmac_f32_e32 v7, v18, v11
	v_fmac_f32_e32 v8, v18, v12
	v_fmac_f32_e32 v9, v18, v13
	v_fmac_f32_e32 v14, v18, v15
	v_fmac_f32_e32 v16, v18, v17
	v_fmac_f32_e32 v19, v18, v20
	v_fmac_f32_e32 v21, v18, v22
	v_cvt_pk_bf16_f32 v6, v14, v6
	v_cvt_pk_bf16_f32 v7, v16, v7
	v_cvt_pk_bf16_f32 v8, v19, v8
	v_cvt_pk_bf16_f32 v9, v21, v9
	global_store_dwordx4 v[4:5], v[6:9], off offset:1024
	v_lshl_add_u64 v[4:5], v[4:5], 0, s[80:81]
	s_cbranch_scc0 .LBB0_121

; __device__ __forceinline__ float shx(float v, int o, int lane) { return __int_as_float(__builtin_amdgcn_ds_bpermute((lane ^ o) << 2, __float_as_int(v))); }
; __global__ void __launch_bounds__(512, 2) mk_fwd(Args a) {
;     ...
;                 const float* gq = a.in[I_GQ] + (size_t)l * 192; const float* gk = a.in[I_GK] + (size_t)l * 192;
;                 float mq = fmaxf(fmaxf(fabsf(gq[lane]), fabsf(gq[64 + lane])), fabsf(gq[128 + lane])), mk = fmaxf(fmaxf(fabsf(gk[lane]), fabsf(gk[64 + lane])), fabsf(gk[128 + lane]));
; #pragma unroll
;                 for (int o = 1; o < 64; o <<= 1) { mq = fmaxf(mq, shx(mq, o, lane)); mk = fmaxf(mk, shx(mk, o, lane)); }
.LBB0_124:
	s_and_b64 vcc, exec, s[0:1]
	s_cbranch_vccz .LBB0_227
	v_ashrrev_i32_e32 v151, 31, v150
	v_lshlrev_b64 v[0:1], 2, v[150:151]
	s_waitcnt lgkmcnt(0)
	v_lshl_add_u64 v[2:3], s[44:45], 0, v[0:1]
	global_load_dword v4, v[2:3], off
	global_load_dword v5, v[2:3], off offset:256
	global_load_dword v2, v[2:3], off offset:512
	v_lshl_add_u64 v[0:1], s[14:15], 0, v[0:1]
	v_readlane_b32 s0, v252, 52
	v_and_b32_e32 v151, 31, v150
	v_readlane_b32 s1, v252, 53
	v_lshlrev_b32_e32 v205, 3, v150
	s_andn2_b64 vcc, exec, s[0:1]
	v_lshlrev_b32_e32 v154, 2, v151
	s_waitcnt vmcnt(0)
	v_max3_f32 v2, |v4|, |v5|, |v2|
	global_load_dword v3, v[0:1], off
	global_load_dword v4, v[0:1], off offset:256
	global_load_dword v0, v[0:1], off offset:512
	s_waitcnt vmcnt(0)
	v_max3_f32 v0, |v3|, |v4|, |v0|
	v_lshlrev_b32_e32 v3, 2, v150
	v_xor_b32_e32 v1, 4, v3
	ds_bpermute_b32 v4, v1, v2
	ds_bpermute_b32 v1, v1, v0
	s_waitcnt lgkmcnt(0)
	v_max_f32_e32 v4, v4, v4
	v_max_f32_e32 v1, v1, v1
	v_max_f32_e32 v2, v2, v4
	v_max_f32_e32 v0, v0, v1
	v_xor_b32_e32 v1, 8, v3
	ds_bpermute_b32 v4, v1, v2
	ds_bpermute_b32 v1, v1, v0
	s_waitcnt lgkmcnt(1)
	v_max_f32_e32 v4, v4, v4
	s_waitcnt lgkmcnt(0)
	v_max_f32_e32 v1, v1, v1
	v_max_f32_e32 v2, v2, v4
	v_max_f32_e32 v0, v0, v1
	v_xor_b32_e32 v1, 16, v3
	ds_bpermute_b32 v4, v1, v2
	ds_bpermute_b32 v1, v1, v0
	s_waitcnt lgkmcnt(1)
	v_max_f32_e32 v4, v4, v4
	s_waitcnt lgkmcnt(0)
	v_max_f32_e32 v1, v1, v1
	v_max_f32_e32 v2, v2, v4
	v_max_f32_e32 v0, v0, v1
	v_xor_b32_e32 v1, 32, v3
	ds_bpermute_b32 v4, v1, v2
	ds_bpermute_b32 v1, v1, v0
	s_waitcnt lgkmcnt(1)
	v_max_f32_e32 v4, v4, v4
	v_max_f32_e32 v2, v2, v4
	s_waitcnt lgkmcnt(0)
	v_max_f32_e32 v1, v1, v1
	v_xor_b32_e32 v4, 64, v3
	v_max_f32_e32 v1, v0, v1
	ds_bpermute_b32 v0, v4, v2
	s_waitcnt lgkmcnt(0)
	v_max_f32_e32 v0, v0, v0
	v_max_f32_e32 v0, v2, v0
	ds_bpermute_b32 v2, v4, v1
	s_waitcnt lgkmcnt(0)
	v_max_f32_e32 v2, v2, v2
	v_max_f32_e32 v1, v1, v2
	v_xor_b32_e32 v2, 0x80, v3
	ds_bpermute_b32 v3, v2, v0
	ds_bpermute_b32 v2, v2, v1
	s_cbranch_vccnz .LBB0_182
; __device__ __forceinline__ int v_rd_base(int lane) { return ((lane & 3) << 3) | (((lane >> 2) & 3) << 6) | (((lane >> 4) & 1) << 5) | (((lane >> 5) & 1) << 8); }
; __device__ __forceinline__ void attn_unit(const bf16_t* __restrict__ Qb, const bf16_t* __restrict__ Kh, const bf16_t* __restrict__ Vh, bf16_t* __restrict__ Ob,
;                                           LAS unsigned char* lds, float MB, int tid, int nrows, int t0, int t1, float* part, float* partl) {
;     ...
;     unsigned ko[3], vo[2];
; #pragma unroll
;     for (int i = 0; i < 3; ++i) { const int sl = tid + 512 * i, row = sl / 24, pc = sl - row * 24, ch = pc ^ ((row >> 1) & 7); ko[i] = (unsigned)(row * LDKK + ch * 8) * 2u; }
; #pragma unroll
;     for (int i = 0; i < 2; ++i) { const int sl = tid + 512 * i, sub = sl >> 5, kk = (sub >> 2) * 8 + ((sl >> 2) & 7), c = (sub & 3) * 32 + (sl & 3) * 8;
;         const int kx = (kk & ~0xC) | ((kk & 4) << 1) | ((kk & 8) >> 1); vo[i] = (unsigned)(kx * LDV + c) * 2u; }
;     const int vb0 = (int)(unsigned)(uintptr_t)V_lds + v_rd_base(lane);
;     const unsigned ldw = (unsigned)wid * 1024u;
; __global__ void __launch_bounds__(512, 2) mk_fwd(Args a) {
;     ...
;                 const float bound = mq * mk * 13.856406460551018f * 1.4426950408889634f;
;                 const float MBs = fmaxf(0.f, bound - 60.f);
;                 for (int rep = 0; rep < ATT_REPEAT; ++rep) {
;                 float* PM = (float*)(ws + O_PM);
;                 const int nr = (512 - bx + G - 1) / G, mp0 = (G >= 136 + 16 * NMP) ? bx - 136 : bx, mstep = (G >= 136 + 16 * NMP) ? G : G;
	s_waitcnt lgkmcnt(1)
	v_max_f32_e32 v3, v3, v3
	v_max_f32_e32 v0, v0, v0
	s_waitcnt lgkmcnt(0)
	v_max_f32_e32 v2, v2, v2
	v_max_f32_e32 v1, v1, v1
	v_max_f32_e32 v0, v0, v3
	v_max_f32_e32 v1, v1, v2
	v_mul_f32_e32 v0, v1, v0
	v_mul_f32_e32 v0, 0x415db3d7, v0
	v_fmamk_f32 v0, v0, 0x3fb8aa3b, v249
	s_mov_b32 s5, 0x2aaaaaab
	v_max_f32_e32 v206, 0, v0
	v_mul_hi_i32 v0, v152, s5
	v_lshrrev_b32_e32 v1, 31, v0
	v_ashrrev_i32_e32 v0, 2, v0
	v_add_u32_e32 v2, v0, v1
	s_mov_b32 s8, 0xfffffe8
	v_mad_u64_u32 v[0:1], s[0:1], v2, s8, v[152:153]
	v_lshrrev_b32_e32 v1, 1, v2
	s_movk_i32 s4, 0x1800
	v_bitop3_b32 v0, v0, v1, 7 bitop3:0x78
	v_mul_lo_u32 v1, v2, s4
	v_lshl_add_u32 v156, v0, 4, v1
	v_add_u32_e32 v0, 0x200, v152
	v_mul_hi_i32 v1, v0, s5
	v_lshrrev_b32_e32 v2, 31, v1
	v_ashrrev_i32_e32 v1, 2, v1
	v_add_u32_e32 v1, v1, v2
	v_mad_u64_u32 v[2:3], s[0:1], v1, s8, v[0:1]
	v_lshrrev_b32_e32 v3, 1, v1
	v_bitop3_b32 v2, v2, v3, 7 bitop3:0x78
	v_mul_lo_u32 v1, v1, s4
	v_lshl_add_u32 v158, v2, 4, v1
	v_add_u32_e32 v2, 0x400, v152
	v_mul_hi_i32 v1, v2, s5
	v_lshrrev_b32_e32 v3, 31, v1
	v_ashrrev_i32_e32 v1, 2, v1
	v_add_u32_e32 v1, v1, v3
	v_mad_u64_u32 v[2:3], s[0:1], v1, s8, v[2:3]
	v_lshrrev_b32_e32 v3, 1, v1
	v_bitop3_b32 v2, v2, v3, 7 bitop3:0x78
	v_mul_lo_u32 v1, v1, s4
	v_lshl_add_u32 v160, v2, 4, v1
	v_bfe_u32 v1, v152, 2, 2
	v_lshrrev_b32_e32 v3, 1, v152
	v_and_or_b32 v1, v3, 8, v1
	v_ashrrev_i32_e32 v3, 4, v152
	v_and_b32_e32 v2, 0x60, v152
	v_and_b32_e32 v6, 0x7fff0, v3
	v_lshrrev_b32_e32 v3, 1, v3
	v_and_or_b32 v2, v205, 24, v2
	v_and_b32_e32 v3, 4, v3
	v_lshlrev_b32_e32 v2, 1, v2
	v_or3_b32 v3, v6, v3, v1
	v_ashrrev_i32_e32 v0, 4, v0
	v_lshl_or_b32 v162, v3, 13, v2
	v_and_b32_e32 v3, 0x7fff0, v0
	v_lshrrev_b32_e32 v0, 1, v0
	v_bfe_u32 v5, v150, 5, 1
	v_and_b32_e32 v0, 4, v0
	s_movk_i32 s0, 0x180
	v_lshlrev_b32_e32 v207, 4, v5
	v_or3_b32 v0, v3, v0, v1
	v_lshlrev_b32_e32 v3, 3, v151
	v_mad_u32_u24 v208, v151, s0, 0
	s_movk_i32 s0, 0x70
	v_and_b32_e32 v6, 0x70, v3
	v_bitop3_b32 v209, v207, v3, s0 bitop3:0x78
	s_movk_i32 s0, 0x60
	v_bitop3_b32 v212, v207, v6, s0 bitop3:0x36
	s_movk_i32 s0, 0x80
	v_bitop3_b32 v213, v207, v6, s0 bitop3:0x36
	s_movk_i32 s0, 0xa0
	v_bitop3_b32 v214, v207, v6, s0 bitop3:0x36
	s_movk_i32 s0, 0xc0
	v_bitop3_b32 v215, v207, v6, s0 bitop3:0x36
	s_movk_i32 s0, 0xe0
	v_bitop3_b32 v216, v207, v6, s0 bitop3:0x36
	s_movk_i32 s0, 0x100
	v_lshl_or_b32 v164, v0, 13, v2
	v_lshlrev_b32_e32 v0, 1, v150
	v_lshlrev_b32_e32 v1, 4, v150
	v_and_b32_e32 v2, 0x118, v205
	v_bitop3_b32 v217, v207, v6, s0 bitop3:0x36
	s_movk_i32 s0, 0x120
	v_and_b32_e32 v4, 63, v150
	v_and_b32_e32 v1, 0xc0, v1
	v_bitop3_b32 v218, v207, v6, s0 bitop3:0x36
	s_movk_i32 s0, 0x140
	v_and_or_b32 v0, v0, 32, v2
	s_add_u32 s6, s64, 0x2c7c1000
	v_bitop3_b32 v219, v207, v6, s0 bitop3:0x36
	s_movk_i32 s0, 0x160
	v_add3_u32 v221, v1, 0, v0
	v_lshlrev_b32_e32 v0, 2, v4
	v_cmp_gt_u32_e64 s[38:39], 32, v4
	v_cmp_gt_u32_e32 vcc, 16, v151
	v_mov_b32_e32 v155, v145
	s_addc_u32 s7, s65, 0
	v_bitop3_b32 v220, v207, v6, s0 bitop3:0x36
	v_xor_b32_e32 v222, 0x80, v0
	v_lshlrev_b32_e32 v223, 2, v5
	s_and_b64 s[0:1], s[38:39], vcc
	v_lshl_add_u64 v[0:1], s[64:65], 0, v[154:155]
	s_mov_b64 s[8:9], 0x2c9c1000
	v_or_b32_e32 v239, 1, v223
	v_or_b32_e32 v250, 2, v223
	v_or_b32_e32 v203, 3, v223
	v_or_b32_e32 v248, 8, v223
	v_or_b32_e32 v228, 9, v223
	v_or_b32_e32 v229, 10, v223
	v_or_b32_e32 v230, 11, v223
	v_or_b32_e32 v231, 16, v223
	v_or_b32_e32 v232, 17, v223
	v_or_b32_e32 v233, 18, v223
	v_or_b32_e32 v234, 19, v223
	v_or_b32_e32 v235, 24, v223
	v_or_b32_e32 v236, 25, v223
	v_or_b32_e32 v237, 26, v223
	v_or_b32_e32 v238, 27, v223
	v_lshl_add_u64 v[198:199], v[0:1], 0, s[8:9]
	s_add_u32 s13, s64, 0x1fbc1000
	v_readlane_b32 s4, v252, 51
	v_readlane_b32 s8, v252, 47
	s_movk_i32 s5, 0x1800
	v_mov_b32_e32 v157, v145
	v_mov_b32_e32 v159, v145
	v_mov_b32_e32 v161, v145
	v_mov_b32_e32 v163, v145
	v_mov_b32_e32 v165, v145
	v_bitop3_b32 v210, v207, v6, 32 bitop3:0x36
	v_bitop3_b32 v211, v207, v6, 64 bitop3:0x36
	v_lshlrev_b32_e32 v166, 14, v5
	v_mov_b32_e32 v167, v145
	v_lshlrev_b32_e32 v168, 12, v239
	v_mov_b32_e32 v169, v145
	v_lshlrev_b32_e32 v170, 12, v250
	v_mov_b32_e32 v171, v145
	v_lshlrev_b32_e32 v172, 12, v203
	v_mov_b32_e32 v173, v145
	v_lshlrev_b32_e32 v174, 12, v248
	v_mov_b32_e32 v175, v145
	v_lshlrev_b32_e32 v176, 12, v228
	v_mov_b32_e32 v177, v145
	v_lshlrev_b32_e32 v178, 12, v229
	v_mov_b32_e32 v179, v145
	v_lshlrev_b32_e32 v180, 12, v230
	v_mov_b32_e32 v181, v145
	v_lshlrev_b32_e32 v182, 12, v231
	v_mov_b32_e32 v183, v145
	v_lshlrev_b32_e32 v184, 12, v232
	v_mov_b32_e32 v185, v145
	v_lshlrev_b32_e32 v186, 12, v233
	v_mov_b32_e32 v187, v145
	v_lshlrev_b32_e32 v188, 12, v234
	v_mov_b32_e32 v189, v145
	v_lshlrev_b32_e32 v190, 12, v235
	v_mov_b32_e32 v191, v145
	v_lshlrev_b32_e32 v192, 12, v236
	v_mov_b32_e32 v193, v145
	v_lshlrev_b32_e32 v194, 12, v237
	v_mov_b32_e32 v195, v145
	v_lshlrev_b32_e32 v196, 12, v238
	v_mov_b32_e32 v197, v145
	v_lshl_or_b32 v200, v5, 9, v151
	v_mov_b32_e32 v201, v145
	s_addc_u32 s18, s65, 0
	s_mov_b32 s24, 0
	s_mov_b32 s36, s4
	v_readlane_b32 s9, v252, 48
	v_and_b32_e32 v64, 15, v150
	v_bfe_u32 v65, v150, 4, 2
	v_lshrrev_b32_e32 v66, 1, v64
	v_xor_b32_e32 v67, v65, v66
	v_mul_u32_u24_e32 v68, 0x180, v64
	v_lshl_add_u32 v209, v67, 4, v68
	v_xor_b32_e32 v67, 4, v67
	v_lshl_add_u32 v210, v67, 4, v68
	v_lshrrev_b32_e32 v66, 1, v65
	v_and_b32_e32 v67, 1, v65
	v_lshlrev_b32_e32 v66, 11, v66
	v_lshl_or_b32 v66, v67, 7, v66
	v_lshrrev_b32_e32 v67, 2, v64
	v_lshl_or_b32 v66, v67, 5, v66
	v_and_b32_e32 v67, 3, v64
	v_lshl_or_b32 v221, v67, 3, v66
	v_lshl_or_b32 v200, v65, 9, v64
	v_lshrrev_b32_e32 v66, 7, v152
	v_bfe_u32 v67, v152, 1, 3
	v_lshl_or_b32 v66, v66, 3, v67
	v_bfe_u32 v67, v152, 4, 3
	v_and_b32_e32 v68, 1, v152
	v_lshl_or_b32 v67, v67, 1, v68
	v_lshlrev_b32_e32 v67, 4, v67
	v_lshl_or_b32 v162, v66, 13, v67
	v_add_u32_e32 v164, 0x40000, v162
	s_branch .LBB0_129

; #define PG8_STAGE(bufoff, gbase, voff) do { _Pragma("unroll") for (int _i = 0; _i < 2; ++_i) \
;         __builtin_amdgcn_global_load_lds((const unsigned*)((const char*)(gbase) + (voff)[_i]), (LAS unsigned*)(lds + (bufoff) + ldsw + _i * 8192), 16, 0, 0); } while (0)
; #define PG8_LDA(dst, b, h) do { _Pragma("unroll") for (int m = 0; m < 4; ++m) _Pragma("unroll") for (int k = 0; k < 2; ++k) dst[m][k] = *(const LAS bf16x8*)(lds + PG8_SA(b, h) + aoff + m * 2048 + k * 1024); } while (0)
; #define PG8_LDB(dst, b, h) do { _Pragma("unroll") for (int n = 0; n < 2; ++n) _Pragma("unroll") for (int k = 0; k < 2; ++k) dst[n][k] = *(const LAS bf16x8*)(lds + PG8_SB(b, h) + boff + n * 2048 + k * 1024); } while (0)
; #define PG8_WAIT_V(n) asm volatile("s_waitcnt vmcnt(" #n ")" ::: "memory")
; #define PG8_WAIT_L(n) asm volatile("s_waitcnt lgkmcnt(" #n ")" ::: "memory")
; __device__ __forceinline__ void gemm_phase(LAS unsigned char* lds, const Desc& g, int G, int cidx, int tid) {
;     ...
;         for (int t = 0; t < nt; t += 2) {
;             const bool last = (t == nt - 2);
;             const char* a1 = cA + (size_t)(t + 1) * kstep;
;             const char* a2 = last ? nA : cA + (size_t)(t + 2) * kstep; const char* b2 = last ? nB : cB + (size_t)(t + 2) * kstep;
;             const char* a3 = a2 + kstep; const char* b3 = b2 + kstep;
;             PG8_LDB(B0, 0, 0); PG8_LDB(B1, 0, 1); PG8_SCHED; PG8_LDA(At, 0, 0); PG8_STAGE(PG8_SA(1, 1), a1 + hstepA, voffA);
;             PG8_WAIT_V(8); PG8_WAIT_L(0); PG8_BAR; PG8_MMA(0, 0, At, B0); PG8_MMA(0, 1, At, B1); PG8_BAR; PG8_SCHED;
;             PG8_LDA(At, 0, 1); PG8_STAGE(PG8_SB(0, 0), b2, voffB); PG8_STAGE(PG8_SB(0, 1), b2 + hstepB, voffB); PG8_STAGE(PG8_SA(0, 0), a2, voffA);
;             PG8_WAIT_V(8); PG8_WAIT_L(0); PG8_BAR; PG8_MMA(1, 0, At, B0); PG8_MMA(1, 1, At, B1); PG8_BAR; PG8_SCHED;
;             PG8_LDB(B0, 1, 0); PG8_LDB(B1, 1, 1); PG8_SCHED; PG8_LDA(At, 1, 0); PG8_STAGE(PG8_SA(0, 1), a2 + hstepA, voffA);
;             PG8_WAIT_V(8); PG8_WAIT_L(0); PG8_BAR; PG8_MMA(0, 0, At, B0); PG8_MMA(0, 1, At, B1); PG8_BAR; PG8_SCHED;
;             PG8_LDA(At, 1, 1); PG8_STAGE(PG8_SB(1, 0), b3, voffB); PG8_STAGE(PG8_SB(1, 1), b3 + hstepB, voffB); PG8_STAGE(PG8_SA(1, 0), a3, voffA);
;             PG8_WAIT_V(8); PG8_WAIT_L(0); PG8_BAR; PG8_MMA(1, 0, At, B0); PG8_MMA(1, 1, At, B1); PG8_BAR; PG8_SCHED;
;         }
.LBB0_199:
	s_add_u32 s52, s50, 0x100
	s_addc_u32 s53, s51, 0
	s_add_i32 s42, 0, 0x10000
	s_cmp_eq_u32 s63, 62
	s_cselect_b32 s59, s1, s53
	s_cselect_b32 s58, s0, s52
	v_add_u32_e32 v142, s42, v139
	s_cselect_b32 s57, s49, s62
	s_cselect_b32 s56, s48, s61
	s_add_i32 s43, 0, 0x14000
	ds_read_b128 v[156:159], v142
	ds_read_b128 v[160:163], v142 offset:1024
	ds_read_b128 v[164:167], v142 offset:2048
	ds_read_b128 v[168:171], v142 offset:3072
	v_add_u32_e32 v142, s43, v139
	ds_read_b128 v[172:175], v142
	ds_read_b128 v[176:179], v142 offset:1024
	ds_read_b128 v[180:183], v142 offset:2048
	ds_read_b128 v[184:187], v142 offset:3072
	v_lshl_add_u64 v[142:143], s[50:51], 0, v[136:137]
	s_add_i32 m0, s7, 0xc000
	ds_read_b128 v[188:191], v141
	ds_read_b128 v[192:195], v141 offset:1024
	ds_read_b128 v[196:199], v141 offset:2048
	ds_read_b128 v[206:209], v141 offset:3072
	ds_read_b128 v[210:213], v141 offset:4096
	ds_read_b128 v[214:217], v141 offset:5120
	ds_read_b128 v[218:221], v141 offset:6144
	ds_read_b128 v[222:225], v141 offset:7168
	global_load_lds_dwordx4 v[142:143], off
	v_lshl_add_u64 v[142:143], s[50:51], 0, v[134:135]
	s_add_i32 m0, s7, 0xe000
	s_nop 0
	global_load_lds_dwordx4 v[142:143], off
	s_waitcnt vmcnt(8)
	s_barrier
	s_setprio 1
	s_waitcnt lgkmcnt(0)
	v_mfma_f32_16x16x32_bf16 v[124:127], v[156:159], v[188:191], v[124:127]
	v_mfma_f32_16x16x32_bf16 v[120:123], v[164:167], v[188:191], v[120:123]
	v_mfma_f32_16x16x32_bf16 v[108:111], v[156:159], v[196:199], v[108:111]
	v_mfma_f32_16x16x32_bf16 v[104:107], v[164:167], v[196:199], v[104:107]
	v_mfma_f32_16x16x32_bf16 v[92:95], v[156:159], v[210:213], v[92:95]
	v_mfma_f32_16x16x32_bf16 v[88:91], v[164:167], v[210:213], v[88:91]
	v_mfma_f32_16x16x32_bf16 v[76:79], v[156:159], v[218:221], v[76:79]
	v_mfma_f32_16x16x32_bf16 v[72:75], v[164:167], v[218:221], v[72:75]
	v_mfma_f32_16x16x32_bf16 v[124:127], v[160:163], v[192:195], v[124:127]
	v_mfma_f32_16x16x32_bf16 v[120:123], v[168:171], v[192:195], v[120:123]
	v_mfma_f32_16x16x32_bf16 v[108:111], v[160:163], v[206:209], v[108:111]
	v_mfma_f32_16x16x32_bf16 v[104:107], v[168:171], v[206:209], v[104:107]
	v_mfma_f32_16x16x32_bf16 v[92:95], v[160:163], v[214:217], v[92:95]
	v_mfma_f32_16x16x32_bf16 v[88:91], v[168:171], v[214:217], v[88:91]
	v_mfma_f32_16x16x32_bf16 v[76:79], v[160:163], v[222:225], v[76:79]
	v_mfma_f32_16x16x32_bf16 v[72:75], v[168:171], v[222:225], v[72:75]
	v_mfma_f32_16x16x32_bf16 v[116:119], v[172:175], v[188:191], v[116:119]
	v_mfma_f32_16x16x32_bf16 v[112:115], v[180:183], v[188:191], v[112:115]
	v_mfma_f32_16x16x32_bf16 v[100:103], v[172:175], v[196:199], v[100:103]
	v_mfma_f32_16x16x32_bf16 v[96:99], v[180:183], v[196:199], v[96:99]
	v_mfma_f32_16x16x32_bf16 v[84:87], v[172:175], v[210:213], v[84:87]
	v_mfma_f32_16x16x32_bf16 v[80:83], v[180:183], v[210:213], v[80:83]
	v_mfma_f32_16x16x32_bf16 v[68:71], v[172:175], v[218:221], v[68:71]
	v_mfma_f32_16x16x32_bf16 v[64:67], v[180:183], v[218:221], v[64:67]
	v_mfma_f32_16x16x32_bf16 v[116:119], v[176:179], v[192:195], v[116:119]
	v_mfma_f32_16x16x32_bf16 v[112:115], v[184:187], v[192:195], v[112:115]
	v_mfma_f32_16x16x32_bf16 v[100:103], v[176:179], v[206:209], v[100:103]
	v_mfma_f32_16x16x32_bf16 v[96:99], v[184:187], v[206:209], v[96:99]
	v_mfma_f32_16x16x32_bf16 v[84:87], v[176:179], v[214:217], v[84:87]
	v_mfma_f32_16x16x32_bf16 v[80:83], v[184:187], v[214:217], v[80:83]
	v_mfma_f32_16x16x32_bf16 v[68:71], v[176:179], v[222:225], v[68:71]
	v_mfma_f32_16x16x32_bf16 v[64:67], v[184:187], v[222:225], v[64:67]
	s_setprio 0
	s_barrier
	s_add_i32 s42, s42, s6
	v_lshl_add_u64 v[142:143], s[56:57], 0, v[144:145]
	s_mov_b32 m0, s42
	ds_read_b128 v[188:191], v141 offset:16384
	ds_read_b128 v[192:195], v141 offset:17408
	ds_read_b128 v[196:199], v141 offset:18432
	ds_read_b128 v[206:209], v141 offset:19456
	ds_read_b128 v[210:213], v141 offset:20480
	ds_read_b128 v[214:217], v141 offset:21504
	ds_read_b128 v[218:221], v141 offset:22528
	ds_read_b128 v[222:225], v141 offset:23552
	global_load_lds_dwordx4 v[142:143], off
	s_add_i32 m0, s42, 0x2000
	s_add_u32 s50, s56, 0x110000
	v_lshl_add_u64 v[146:147], s[56:57], 0, v[128:129]
	s_addc_u32 s51, s57, 0
	s_add_i32 s42, s43, s6
	global_load_lds_dwordx4 v[146:147], off
	v_lshl_add_u64 v[148:149], s[50:51], 0, v[144:145]
	s_mov_b32 m0, s42
	v_lshl_add_u64 v[200:201], s[58:59], 0, v[130:131]
	global_load_lds_dwordx4 v[148:149], off
	v_lshl_add_u64 v[148:149], s[50:51], 0, v[128:129]
	s_add_i32 m0, s42, 0x2000
	s_nop 0
	global_load_lds_dwordx4 v[148:149], off
	v_lshl_add_u64 v[148:149], s[58:59], 0, v[132:133]
	s_mov_b32 m0, s7
	s_nop 0
	global_load_lds_dwordx4 v[148:149], off
	s_mov_b32 m0, s13
	s_nop 0
	global_load_lds_dwordx4 v[200:201], off
	s_waitcnt vmcnt(8)
	s_barrier
; #define PG8_STAGE(bufoff, gbase, voff) do { _Pragma("unroll") for (int _i = 0; _i < 2; ++_i) \
;         __builtin_amdgcn_global_load_lds((const unsigned*)((const char*)(gbase) + (voff)[_i]), (LAS unsigned*)(lds + (bufoff) + ldsw + _i * 8192), 16, 0, 0); } while (0)
; #define PG8_LDA(dst, b, h) do { _Pragma("unroll") for (int m = 0; m < 4; ++m) _Pragma("unroll") for (int k = 0; k < 2; ++k) dst[m][k] = *(const LAS bf16x8*)(lds + PG8_SA(b, h) + aoff + m * 2048 + k * 1024); } while (0)
; #define PG8_LDB(dst, b, h) do { _Pragma("unroll") for (int n = 0; n < 2; ++n) _Pragma("unroll") for (int k = 0; k < 2; ++k) dst[n][k] = *(const LAS bf16x8*)(lds + PG8_SB(b, h) + boff + n * 2048 + k * 1024); } while (0)
; #define PG8_WAIT_V(n) asm volatile("s_waitcnt vmcnt(" #n ")" ::: "memory")
; #define PG8_WAIT_L(n) asm volatile("s_waitcnt lgkmcnt(" #n ")" ::: "memory")
; __device__ __forceinline__ void gemm_phase(LAS unsigned char* lds, const Desc& g, int G, int cidx, int tid) {
;     ...
;         for (int t = 0; t < nt; t += 2) {
;             const bool last = (t == nt - 2);
;             const char* a1 = cA + (size_t)(t + 1) * kstep;
;             const char* a2 = last ? nA : cA + (size_t)(t + 2) * kstep; const char* b2 = last ? nB : cB + (size_t)(t + 2) * kstep;
;             const char* a3 = a2 + kstep; const char* b3 = b2 + kstep;
;             PG8_LDB(B0, 0, 0); PG8_LDB(B1, 0, 1); PG8_SCHED; PG8_LDA(At, 0, 0); PG8_STAGE(PG8_SA(1, 1), a1 + hstepA, voffA);
;             PG8_WAIT_V(8); PG8_WAIT_L(0); PG8_BAR; PG8_MMA(0, 0, At, B0); PG8_MMA(0, 1, At, B1); PG8_BAR; PG8_SCHED;
;             PG8_LDA(At, 0, 1); PG8_STAGE(PG8_SB(0, 0), b2, voffB); PG8_STAGE(PG8_SB(0, 1), b2 + hstepB, voffB); PG8_STAGE(PG8_SA(0, 0), a2, voffA);
;             PG8_WAIT_V(8); PG8_WAIT_L(0); PG8_BAR; PG8_MMA(1, 0, At, B0); PG8_MMA(1, 1, At, B1); PG8_BAR; PG8_SCHED;
;             PG8_LDB(B0, 1, 0); PG8_LDB(B1, 1, 1); PG8_SCHED; PG8_LDA(At, 1, 0); PG8_STAGE(PG8_SA(0, 1), a2 + hstepA, voffA);
;             PG8_WAIT_V(8); PG8_WAIT_L(0); PG8_BAR; PG8_MMA(0, 0, At, B0); PG8_MMA(0, 1, At, B1); PG8_BAR; PG8_SCHED;
;             PG8_LDA(At, 1, 1); PG8_STAGE(PG8_SB(1, 0), b3, voffB); PG8_STAGE(PG8_SB(1, 1), b3 + hstepB, voffB); PG8_STAGE(PG8_SA(1, 0), a3, voffA);
;             PG8_WAIT_V(8); PG8_WAIT_L(0); PG8_BAR; PG8_MMA(1, 0, At, B0); PG8_MMA(1, 1, At, B1); PG8_BAR; PG8_SCHED;
;         }
	s_setprio 1
	s_waitcnt lgkmcnt(0)
	v_mfma_f32_16x16x32_bf16 v[60:63], v[156:159], v[188:191], v[60:63]
	v_mfma_f32_16x16x32_bf16 v[56:59], v[164:167], v[188:191], v[56:59]
	v_mfma_f32_16x16x32_bf16 v[44:47], v[156:159], v[196:199], v[44:47]
	v_mfma_f32_16x16x32_bf16 v[40:43], v[164:167], v[196:199], v[40:43]
	v_mfma_f32_16x16x32_bf16 v[28:31], v[156:159], v[210:213], v[28:31]
	v_mfma_f32_16x16x32_bf16 v[24:27], v[164:167], v[210:213], v[24:27]
	v_mfma_f32_16x16x32_bf16 v[12:15], v[156:159], v[218:221], v[12:15]
	v_mfma_f32_16x16x32_bf16 v[8:11], v[164:167], v[218:221], v[8:11]
	v_mfma_f32_16x16x32_bf16 v[60:63], v[160:163], v[192:195], v[60:63]
	v_mfma_f32_16x16x32_bf16 v[56:59], v[168:171], v[192:195], v[56:59]
	v_mfma_f32_16x16x32_bf16 v[44:47], v[160:163], v[206:209], v[44:47]
	v_mfma_f32_16x16x32_bf16 v[40:43], v[168:171], v[206:209], v[40:43]
	v_mfma_f32_16x16x32_bf16 v[28:31], v[160:163], v[214:217], v[28:31]
	v_mfma_f32_16x16x32_bf16 v[24:27], v[168:171], v[214:217], v[24:27]
	v_mfma_f32_16x16x32_bf16 v[12:15], v[160:163], v[222:225], v[12:15]
	v_mfma_f32_16x16x32_bf16 v[8:11], v[168:171], v[222:225], v[8:11]
	v_mfma_f32_16x16x32_bf16 v[52:55], v[172:175], v[188:191], v[52:55]
	v_mfma_f32_16x16x32_bf16 v[48:51], v[180:183], v[188:191], v[48:51]
	v_mfma_f32_16x16x32_bf16 v[36:39], v[172:175], v[196:199], v[36:39]
	v_mfma_f32_16x16x32_bf16 v[32:35], v[180:183], v[196:199], v[32:35]
	v_mfma_f32_16x16x32_bf16 v[20:23], v[172:175], v[210:213], v[20:23]
	v_mfma_f32_16x16x32_bf16 v[16:19], v[180:183], v[210:213], v[16:19]
	v_mfma_f32_16x16x32_bf16 v[0:3], v[172:175], v[218:221], v[0:3]
	v_mfma_f32_16x16x32_bf16 v[4:7], v[180:183], v[218:221], v[4:7]
	v_mfma_f32_16x16x32_bf16 v[52:55], v[176:179], v[192:195], v[52:55]
	v_mfma_f32_16x16x32_bf16 v[48:51], v[184:187], v[192:195], v[48:51]
	v_mfma_f32_16x16x32_bf16 v[36:39], v[176:179], v[206:209], v[36:39]
	v_mfma_f32_16x16x32_bf16 v[32:35], v[184:187], v[206:209], v[32:35]
	v_mfma_f32_16x16x32_bf16 v[20:23], v[176:179], v[214:217], v[20:23]
	v_mfma_f32_16x16x32_bf16 v[16:19], v[184:187], v[214:217], v[16:19]
	v_mfma_f32_16x16x32_bf16 v[0:3], v[176:179], v[222:225], v[0:3]
	v_mfma_f32_16x16x32_bf16 v[4:7], v[184:187], v[222:225], v[4:7]
	s_setprio 0
	s_barrier
	s_add_i32 s42, 0, 0x18000
	v_add_u32_e32 v155, s42, v139
	s_add_i32 s43, 0, 0x1c000
	ds_read_b128 v[156:159], v155
	ds_read_b128 v[160:163], v155 offset:1024
	ds_read_b128 v[164:167], v155 offset:2048
	ds_read_b128 v[168:171], v155 offset:3072
	v_add_u32_e32 v155, s43, v139
	ds_read_b128 v[172:175], v155
	ds_read_b128 v[176:179], v155 offset:1024
	ds_read_b128 v[180:183], v155 offset:2048
	ds_read_b128 v[184:187], v155 offset:3072
	s_add_u32 s50, s58, 0x110000
	s_addc_u32 s51, s59, 0
	s_mov_b32 m0, s18
	v_lshl_add_u64 v[226:227], s[50:51], 0, v[132:133]
	ds_read_b128 v[188:191], v141 offset:32768
	ds_read_b128 v[192:195], v141 offset:33792
	ds_read_b128 v[196:199], v141 offset:34816
	ds_read_b128 v[206:209], v141 offset:35840
	ds_read_b128 v[210:213], v141 offset:36864
	ds_read_b128 v[214:217], v141 offset:37888
	ds_read_b128 v[218:221], v141 offset:38912
	ds_read_b128 v[222:225], v141 offset:39936
	global_load_lds_dwordx4 v[226:227], off
	v_lshl_add_u64 v[226:227], s[50:51], 0, v[130:131]
	s_mov_b32 m0, s24
	s_nop 0
	global_load_lds_dwordx4 v[226:227], off
	s_waitcnt vmcnt(8)
	s_barrier
	s_setprio 1
	s_waitcnt lgkmcnt(0)
	v_mfma_f32_16x16x32_bf16 v[124:127], v[156:159], v[188:191], v[124:127]
	v_mfma_f32_16x16x32_bf16 v[120:123], v[164:167], v[188:191], v[120:123]
	v_mfma_f32_16x16x32_bf16 v[108:111], v[156:159], v[196:199], v[108:111]
	v_mfma_f32_16x16x32_bf16 v[104:107], v[164:167], v[196:199], v[104:107]
	v_mfma_f32_16x16x32_bf16 v[92:95], v[156:159], v[210:213], v[92:95]
	v_mfma_f32_16x16x32_bf16 v[88:91], v[164:167], v[210:213], v[88:91]
	v_mfma_f32_16x16x32_bf16 v[76:79], v[156:159], v[218:221], v[76:79]
	v_mfma_f32_16x16x32_bf16 v[72:75], v[164:167], v[218:221], v[72:75]
	v_mfma_f32_16x16x32_bf16 v[124:127], v[160:163], v[192:195], v[124:127]
	v_mfma_f32_16x16x32_bf16 v[120:123], v[168:171], v[192:195], v[120:123]
	v_mfma_f32_16x16x32_bf16 v[108:111], v[160:163], v[206:209], v[108:111]
	v_mfma_f32_16x16x32_bf16 v[104:107], v[168:171], v[206:209], v[104:107]
	v_mfma_f32_16x16x32_bf16 v[92:95], v[160:163], v[214:217], v[92:95]
	v_mfma_f32_16x16x32_bf16 v[88:91], v[168:171], v[214:217], v[88:91]
	v_mfma_f32_16x16x32_bf16 v[76:79], v[160:163], v[222:225], v[76:79]
	v_mfma_f32_16x16x32_bf16 v[72:75], v[168:171], v[222:225], v[72:75]
	v_mfma_f32_16x16x32_bf16 v[116:119], v[172:175], v[188:191], v[116:119]
	v_mfma_f32_16x16x32_bf16 v[112:115], v[180:183], v[188:191], v[112:115]
	v_mfma_f32_16x16x32_bf16 v[100:103], v[172:175], v[196:199], v[100:103]
	v_mfma_f32_16x16x32_bf16 v[96:99], v[180:183], v[196:199], v[96:99]
	v_mfma_f32_16x16x32_bf16 v[84:87], v[172:175], v[210:213], v[84:87]
	v_mfma_f32_16x16x32_bf16 v[80:83], v[180:183], v[210:213], v[80:83]
	v_mfma_f32_16x16x32_bf16 v[68:71], v[172:175], v[218:221], v[68:71]
	v_mfma_f32_16x16x32_bf16 v[64:67], v[180:183], v[218:221], v[64:67]
	v_mfma_f32_16x16x32_bf16 v[116:119], v[176:179], v[192:195], v[116:119]
	v_mfma_f32_16x16x32_bf16 v[112:115], v[184:187], v[192:195], v[112:115]
	v_mfma_f32_16x16x32_bf16 v[100:103], v[176:179], v[206:209], v[100:103]
	v_mfma_f32_16x16x32_bf16 v[96:99], v[184:187], v[206:209], v[96:99]
	v_mfma_f32_16x16x32_bf16 v[84:87], v[176:179], v[214:217], v[84:87]
	v_mfma_f32_16x16x32_bf16 v[80:83], v[184:187], v[214:217], v[80:83]
	v_mfma_f32_16x16x32_bf16 v[68:71], v[176:179], v[222:225], v[68:71]
	v_mfma_f32_16x16x32_bf16 v[64:67], v[184:187], v[222:225], v[64:67]
	s_setprio 0
	s_barrier
; #define PG8_STAGE(bufoff, gbase, voff) do { _Pragma("unroll") for (int _i = 0; _i < 2; ++_i) \
;         __builtin_amdgcn_global_load_lds((const unsigned*)((const char*)(gbase) + (voff)[_i]), (LAS unsigned*)(lds + (bufoff) + ldsw + _i * 8192), 16, 0, 0); } while (0)
; #define PG8_LDA(dst, b, h) do { _Pragma("unroll") for (int m = 0; m < 4; ++m) _Pragma("unroll") for (int k = 0; k < 2; ++k) dst[m][k] = *(const LAS bf16x8*)(lds + PG8_SA(b, h) + aoff + m * 2048 + k * 1024); } while (0)
; #define PG8_LDB(dst, b, h) do { _Pragma("unroll") for (int n = 0; n < 2; ++n) _Pragma("unroll") for (int k = 0; k < 2; ++k) dst[n][k] = *(const LAS bf16x8*)(lds + PG8_SB(b, h) + boff + n * 2048 + k * 1024); } while (0)
; #define PG8_WAIT_V(n) asm volatile("s_waitcnt vmcnt(" #n ")" ::: "memory")
; #define PG8_WAIT_L(n) asm volatile("s_waitcnt lgkmcnt(" #n ")" ::: "memory")
; __device__ __forceinline__ void gemm_phase(LAS unsigned char* lds, const Desc& g, int G, int cidx, int tid) {
;     ...
;         for (int t = 0; t < nt; t += 2) {
;             const bool last = (t == nt - 2);
;             const char* a1 = cA + (size_t)(t + 1) * kstep;
;             const char* a2 = last ? nA : cA + (size_t)(t + 2) * kstep; const char* b2 = last ? nB : cB + (size_t)(t + 2) * kstep;
;             const char* a3 = a2 + kstep; const char* b3 = b2 + kstep;
;             PG8_LDB(B0, 0, 0); PG8_LDB(B1, 0, 1); PG8_SCHED; PG8_LDA(At, 0, 0); PG8_STAGE(PG8_SA(1, 1), a1 + hstepA, voffA);
;             PG8_WAIT_V(8); PG8_WAIT_L(0); PG8_BAR; PG8_MMA(0, 0, At, B0); PG8_MMA(0, 1, At, B1); PG8_BAR; PG8_SCHED;
;             PG8_LDA(At, 0, 1); PG8_STAGE(PG8_SB(0, 0), b2, voffB); PG8_STAGE(PG8_SB(0, 1), b2 + hstepB, voffB); PG8_STAGE(PG8_SA(0, 0), a2, voffA);
;             PG8_WAIT_V(8); PG8_WAIT_L(0); PG8_BAR; PG8_MMA(1, 0, At, B0); PG8_MMA(1, 1, At, B1); PG8_BAR; PG8_SCHED;
;             PG8_LDB(B0, 1, 0); PG8_LDB(B1, 1, 1); PG8_SCHED; PG8_LDA(At, 1, 0); PG8_STAGE(PG8_SA(0, 1), a2 + hstepA, voffA);
;             PG8_WAIT_V(8); PG8_WAIT_L(0); PG8_BAR; PG8_MMA(0, 0, At, B0); PG8_MMA(0, 1, At, B1); PG8_BAR; PG8_SCHED;
;             PG8_LDA(At, 1, 1); PG8_STAGE(PG8_SB(1, 0), b3, voffB); PG8_STAGE(PG8_SB(1, 1), b3 + hstepB, voffB); PG8_STAGE(PG8_SA(1, 0), a3, voffA);
;             PG8_WAIT_V(8); PG8_WAIT_L(0); PG8_BAR; PG8_MMA(1, 0, At, B0); PG8_MMA(1, 1, At, B1); PG8_BAR; PG8_SCHED;
;         }
	s_add_i32 s42, s42, s6
	v_lshl_add_u64 v[142:143], v[142:143], 0, s[22:23]
	s_mov_b32 m0, s42
	ds_read_b128 v[188:191], v141 offset:49152
	ds_read_b128 v[192:195], v141 offset:50176
	ds_read_b128 v[196:199], v141 offset:51200
	ds_read_b128 v[206:209], v141 offset:52224
	ds_read_b128 v[210:213], v141 offset:53248
	ds_read_b128 v[214:217], v141 offset:54272
	ds_read_b128 v[218:221], v141 offset:55296
	ds_read_b128 v[222:225], v141 offset:56320
	global_load_lds_dwordx4 v[142:143], off
	s_add_i32 m0, s42, 0x2000
	s_add_u32 s50, s56, 0x110080
	v_lshl_add_u64 v[142:143], v[146:147], 0, s[22:23]
	s_addc_u32 s51, s57, 0
	s_add_i32 s42, s43, s6
	global_load_lds_dwordx4 v[142:143], off
	v_lshl_add_u64 v[142:143], s[50:51], 0, v[144:145]
	s_mov_b32 m0, s42
	s_nop 0
	global_load_lds_dwordx4 v[142:143], off
	v_lshl_add_u64 v[142:143], s[50:51], 0, v[128:129]
	s_add_i32 m0, s42, 0x2000
	s_nop 0
	global_load_lds_dwordx4 v[142:143], off
	v_lshl_add_u64 v[142:143], v[148:149], 0, s[22:23]
	s_mov_b32 m0, s26
	s_nop 0
	global_load_lds_dwordx4 v[142:143], off
	v_lshl_add_u64 v[142:143], v[200:201], 0, s[22:23]
	s_mov_b32 m0, s28
	s_nop 0
	global_load_lds_dwordx4 v[142:143], off
	s_waitcnt vmcnt(8)
	s_barrier
	s_setprio 1
	s_waitcnt lgkmcnt(0)
	v_mfma_f32_16x16x32_bf16 v[60:63], v[156:159], v[188:191], v[60:63]
	v_mfma_f32_16x16x32_bf16 v[56:59], v[164:167], v[188:191], v[56:59]
	v_mfma_f32_16x16x32_bf16 v[44:47], v[156:159], v[196:199], v[44:47]
	v_mfma_f32_16x16x32_bf16 v[40:43], v[164:167], v[196:199], v[40:43]
	v_mfma_f32_16x16x32_bf16 v[28:31], v[156:159], v[210:213], v[28:31]
	v_mfma_f32_16x16x32_bf16 v[24:27], v[164:167], v[210:213], v[24:27]
	v_mfma_f32_16x16x32_bf16 v[12:15], v[156:159], v[218:221], v[12:15]
	v_mfma_f32_16x16x32_bf16 v[8:11], v[164:167], v[218:221], v[8:11]
	v_mfma_f32_16x16x32_bf16 v[60:63], v[160:163], v[192:195], v[60:63]
	v_mfma_f32_16x16x32_bf16 v[56:59], v[168:171], v[192:195], v[56:59]
	v_mfma_f32_16x16x32_bf16 v[44:47], v[160:163], v[206:209], v[44:47]
	v_mfma_f32_16x16x32_bf16 v[40:43], v[168:171], v[206:209], v[40:43]
	v_mfma_f32_16x16x32_bf16 v[28:31], v[160:163], v[214:217], v[28:31]
	v_mfma_f32_16x16x32_bf16 v[24:27], v[168:171], v[214:217], v[24:27]
	v_mfma_f32_16x16x32_bf16 v[12:15], v[160:163], v[222:225], v[12:15]
	v_mfma_f32_16x16x32_bf16 v[8:11], v[168:171], v[222:225], v[8:11]
	v_mfma_f32_16x16x32_bf16 v[52:55], v[172:175], v[188:191], v[52:55]
	v_mfma_f32_16x16x32_bf16 v[48:51], v[180:183], v[188:191], v[48:51]
	v_mfma_f32_16x16x32_bf16 v[36:39], v[172:175], v[196:199], v[36:39]
	v_mfma_f32_16x16x32_bf16 v[32:35], v[180:183], v[196:199], v[32:35]
	v_mfma_f32_16x16x32_bf16 v[20:23], v[172:175], v[210:213], v[20:23]
	v_mfma_f32_16x16x32_bf16 v[16:19], v[180:183], v[210:213], v[16:19]
	v_mfma_f32_16x16x32_bf16 v[0:3], v[172:175], v[218:221], v[0:3]
	v_mfma_f32_16x16x32_bf16 v[4:7], v[180:183], v[218:221], v[4:7]
	v_mfma_f32_16x16x32_bf16 v[52:55], v[176:179], v[192:195], v[52:55]
	v_mfma_f32_16x16x32_bf16 v[48:51], v[184:187], v[192:195], v[48:51]
	v_mfma_f32_16x16x32_bf16 v[36:39], v[176:179], v[206:209], v[36:39]
	v_mfma_f32_16x16x32_bf16 v[32:35], v[184:187], v[206:209], v[32:35]
	v_mfma_f32_16x16x32_bf16 v[20:23], v[176:179], v[214:217], v[20:23]
	v_mfma_f32_16x16x32_bf16 v[16:19], v[184:187], v[214:217], v[16:19]
	v_mfma_f32_16x16x32_bf16 v[0:3], v[176:179], v[222:225], v[0:3]
	v_mfma_f32_16x16x32_bf16 v[4:7], v[184:187], v[222:225], v[4:7]
	s_setprio 0
	s_barrier
	s_add_i32 s63, s63, 2
	s_add_u32 s61, s61, 0x100
	s_addc_u32 s62, s62, 0
	s_cmp_gt_u32 s63, 63
	s_mov_b64 s[50:51], s[52:53]
	s_cbranch_scc0 .LBB0_199
	s_and_b64 vcc, exec, s[36:37]
	s_cbranch_vccz .LBB0_202
	s_barrier

; __device__ __forceinline__ float bf_lo(unsigned w) { return __uint_as_float(w << 16); }
; __device__ __forceinline__ float bf_hi(unsigned w) { return __uint_as_float(w & 0xffff0000u); }
; __global__ void __launch_bounds__(512, 2) mk_fwd(Args a) {
;     ...
;             for (int r = gw; r < LSEQ; r += NGW) {
;                 const int pos = pos_of(r);
;                 const f32x4 cs0 = *(const f32x4*)(ROPE + pos * 64 + 8 * qq), cs1 = *(const f32x4*)(ROPE + pos * 64 + 8 * qq + 4);
;                 const f32x4 sn0 = *(const f32x4*)(ROPE + pos * 64 + 32 + 8 * qq), sn1 = *(const f32x4*)(ROPE + pos * 64 + 32 + 8 * qq + 4);
;                 bf16_t* qp = Q + (size_t)r * NQ + hh * 192 + 8 * qq;
;                 const bf16_t* kvp = KV + (size_t)r * NKV + hh * 256 + 8 * qq;
;                 bf16_t* kp = KP + (size_t)r * NQ + hh * 192 + 8 * qq;
;                 u32x4 xq[6], xk[6];
; #pragma unroll
;                 for (int m = 0; m < 6; ++m) xq[m] = *(const u32x4*)(qp + 32 * m);
; #pragma unroll
;                 for (int m = 0; m < 4; ++m) xk[m] = *(const u32x4*)(kvp + 32 * m);
;                 xk[4] = *(const u32x4*)(KR + (size_t)r * NKR + 8 * qq); xk[5] = *(const u32x4*)(KR + (size_t)r * NKR + 32 + 8 * qq);
; #pragma unroll
;                 for (int which = 0; which < 2; ++which) {
;                     f32x4 v[6][2]; float ss = 0.f;
; #pragma unroll
;                     for (int m = 0; m < 6; ++m) { const u32x4 w = which ? xk[m] : xq[m];
;                         v[m][0] = (f32x4){bf_lo(w.x), bf_hi(w.x), bf_lo(w.y), bf_hi(w.y)}; v[m][1] = (f32x4){bf_lo(w.z), bf_hi(w.z), bf_lo(w.w), bf_hi(w.w)};
;                         const f32x4 sq = v[m][0] * v[m][0] + v[m][1] * v[m][1]; ss += (sq[0] + sq[1]) + (sq[2] + sq[3]); }
.LBB0_233:
	s_cmpk_lt_i32 s2, 0x2000
	s_cselect_b32 s3, 16, 0xffffe000
	s_add_i32 s3, s3, s2
	s_lshl_b32 s6, s3, 6
	v_lshl_add_u64 v[138:139], v[136:137], 0, v[144:145]
	s_mov_b32 s3, 0xfc01000
	s_ashr_i32 s7, s6, 31
	v_add_co_u32_e32 v140, vcc, s3, v138
	v_lshl_add_u64 v[100:101], s[6:7], 2, v[132:133]
	s_nop 0
	v_addc_co_u32_e32 v141, vcc, 0, v139, vcc
	global_load_dwordx4 v[104:107], v[100:101], off
	global_load_dwordx4 v[96:99], v[100:101], off offset:16
	global_load_dwordx4 v[108:111], v[100:101], off offset:128
	global_load_dwordx4 v[100:103], v[100:101], off offset:144
	global_load_dwordx4 v[154:157], v[140:141], off
	global_load_dwordx4 v[158:161], v[140:141], off offset:64
	global_load_dwordx4 v[164:167], v[140:141], off offset:128
	global_load_dwordx4 v[168:171], v[140:141], off offset:192
	global_load_dwordx4 v[172:175], v[140:141], off offset:256
	global_load_dwordx4 v[176:179], v[140:141], off offset:320
	v_lshl_add_u64 v[112:113], v[134:135], 0, v[144:145]
	s_mov_b32 s3, 0x1b9c1000
	v_add_co_u32_e32 v112, vcc, s3, v112
	v_lshl_add_u64 v[116:117], s[0:1], 0, v[144:145]
	s_nop 0
	v_addc_co_u32_e32 v113, vcc, 0, v113, vcc
	global_load_dwordx4 v[180:183], v[112:113], off
	global_load_dwordx4 v[128:131], v[112:113], off offset:64
	global_load_dwordx4 v[124:127], v[112:113], off offset:128
	global_load_dwordx4 v[112:115], v[112:113], off offset:192
	s_mov_b32 s3, 0x1b5a1000
	v_add_co_u32_e32 v116, vcc, s3, v116
	s_mov_b32 s3, 0x1fbc1000
	s_nop 0
	v_addc_co_u32_e32 v117, vcc, 0, v117, vcc
	global_load_dwordx4 v[120:123], v[116:117], off
	global_load_dwordx4 v[116:119], v[116:117], off offset:64
	s_add_i32 s2, s2, s72
	s_add_u32 s0, s0, s38
	s_addc_u32 s1, s1, s39
	v_lshl_add_u64 v[134:135], v[134:135], 0, s[36:37]
	v_lshl_add_u64 v[136:137], v[136:137], 0, s[8:9]
	s_cmpk_gt_i32 s2, 0x200f
	s_waitcnt vmcnt(0) lgkmcnt(0)
	v_lshlrev_b32_e32 v142, 16, v154
	v_and_b32_e32 v143, 0xffff0000, v154
	v_lshlrev_b32_e32 v146, 16, v155
	v_and_b32_e32 v147, 0xffff0000, v155
	v_lshlrev_b32_e32 v148, 16, v156
	v_and_b32_e32 v149, 0xffff0000, v156
	v_lshlrev_b32_e32 v154, 16, v157
	v_and_b32_e32 v155, 0xffff0000, v157
	v_lshlrev_b32_e32 v188, 16, v160
	v_and_b32_e32 v189, 0xffff0000, v160
	v_lshlrev_b32_e32 v160, 16, v161
	v_and_b32_e32 v161, 0xffff0000, v161
	v_lshlrev_b32_e32 v196, 16, v166
	v_and_b32_e32 v197, 0xffff0000, v166
	v_lshlrev_b32_e32 v166, 16, v167
	v_and_b32_e32 v167, 0xffff0000, v167
	v_pk_mul_f32 v[156:157], v[148:149], v[148:149]
	v_pk_mul_f32 v[184:185], v[154:155], v[154:155]
	v_lshlrev_b32_e32 v186, 16, v158
	v_and_b32_e32 v187, 0xffff0000, v158
	v_lshlrev_b32_e32 v158, 16, v159
	v_and_b32_e32 v159, 0xffff0000, v159
	v_pk_mul_f32 v[190:191], v[188:189], v[188:189]
	v_pk_mul_f32 v[192:193], v[160:161], v[160:161]
	v_lshlrev_b32_e32 v194, 16, v164
	v_and_b32_e32 v195, 0xffff0000, v164
	v_lshlrev_b32_e32 v164, 16, v165
	v_and_b32_e32 v165, 0xffff0000, v165
	v_pk_mul_f32 v[198:199], v[196:197], v[196:197]
	v_pk_mul_f32 v[200:201], v[166:167], v[166:167]
	v_pk_fma_f32 v[184:185], v[146:147], v[146:147], v[184:185]
	v_pk_fma_f32 v[156:157], v[142:143], v[142:143], v[156:157]
	v_pk_fma_f32 v[192:193], v[158:159], v[158:159], v[192:193]
	v_pk_fma_f32 v[190:191], v[186:187], v[186:187], v[190:191]
	v_pk_fma_f32 v[200:201], v[164:165], v[164:165], v[200:201]
	v_pk_fma_f32 v[198:199], v[194:195], v[194:195], v[198:199]
	v_add_f32_e32 v156, v156, v157
	v_add_f32_e32 v184, v184, v185
	v_add_f32_e32 v190, v190, v191
	v_add_f32_e32 v192, v192, v193
	v_mov_b32_e32 v157, v198
	v_mov_b32_e32 v185, v199
	v_mov_b32_e32 v191, v200
	v_mov_b32_e32 v193, v201
	v_pk_add_f32 v[156:157], v[156:157], v[184:185]
	v_pk_add_f32 v[184:185], v[190:191], v[192:193]
	v_lshlrev_b32_e32 v190, 16, v170
	v_and_b32_e32 v191, 0xffff0000, v170
	v_lshlrev_b32_e32 v170, 16, v171
	v_and_b32_e32 v171, 0xffff0000, v171
	v_pk_add_f32 v[156:157], v[156:157], v[184:185]
	v_lshlrev_b32_e32 v184, 16, v168
	v_and_b32_e32 v185, 0xffff0000, v168
	v_lshlrev_b32_e32 v168, 16, v169
	v_and_b32_e32 v169, 0xffff0000, v169
	v_pk_mul_f32 v[192:193], v[190:191], v[190:191]
	v_pk_mul_f32 v[198:199], v[170:171], v[170:171]
	v_pk_fma_f32 v[192:193], v[184:185], v[184:185], v[192:193]
	v_pk_fma_f32 v[198:199], v[168:169], v[168:169], v[198:199]
	v_lshlrev_b32_e32 v212, 16, v178
	v_pk_mov_b32 v[200:201], v[192:193], v[198:199] op_sel:[1,0]
	v_mov_b32_e32 v193, v199
	v_pk_add_f32 v[192:193], v[200:201], v[192:193]
	v_lshlrev_b32_e32 v200, 16, v174
	v_and_b32_e32 v201, 0xffff0000, v174
	v_lshlrev_b32_e32 v174, 16, v175
	v_and_b32_e32 v175, 0xffff0000, v175
	v_and_b32_e32 v213, 0xffff0000, v178
	v_lshlrev_b32_e32 v178, 16, v179
	v_and_b32_e32 v179, 0xffff0000, v179
	v_lshlrev_b32_e32 v198, 16, v172
	v_and_b32_e32 v199, 0xffff0000, v172
	v_lshlrev_b32_e32 v172, 16, v173
	v_and_b32_e32 v173, 0xffff0000, v173
	v_pk_mul_f32 v[206:207], v[200:201], v[200:201]
	v_pk_mul_f32 v[208:209], v[174:175], v[174:175]
	v_lshlrev_b32_e32 v210, 16, v176
	v_and_b32_e32 v211, 0xffff0000, v176
	v_lshlrev_b32_e32 v176, 16, v177
	v_and_b32_e32 v177, 0xffff0000, v177
	v_pk_mul_f32 v[214:215], v[212:213], v[212:213]
	v_pk_mul_f32 v[216:217], v[178:179], v[178:179]
	v_pk_add_f32 v[156:157], v[156:157], v[156:157] op_sel:[0,1] op_sel_hi:[1,0]
	v_pk_add_f32 v[192:193], v[192:193], v[192:193] op_sel:[0,1] op_sel_hi:[1,0]
	v_pk_fma_f32 v[208:209], v[172:173], v[172:173], v[208:209]
	v_pk_fma_f32 v[206:207], v[198:199], v[198:199], v[206:207]
	v_pk_fma_f32 v[216:217], v[176:177], v[176:177], v[216:217]
	v_pk_fma_f32 v[214:215], v[210:211], v[210:211], v[214:215]
	v_add_f32_e32 v206, v206, v207
	v_add_f32_e32 v208, v208, v209
	v_mov_b32_e32 v157, v214
	v_mov_b32_e32 v193, v215
	v_mov_b32_e32 v207, v216
	v_mov_b32_e32 v209, v217
	v_pk_add_f32 v[156:157], v[156:157], v[192:193]
	v_pk_add_f32 v[192:193], v[206:207], v[208:209]
	s_nop 0
	v_pk_add_f32 v[156:157], v[156:157], v[192:193]
	s_nop 0
	v_add_f32_e32 v156, v156, v157
	ds_bpermute_b32 v157, v151, v156
	s_waitcnt lgkmcnt(0)
; __device__ __forceinline__ float shx(float v, int o, int lane) { return __int_as_float(__builtin_amdgcn_ds_bpermute((lane ^ o) << 2, __float_as_int(v))); }
; __device__ __forceinline__ u32x4 pack8(f32x4 v0, f32x4 v1) { u32x4 w; w.x = cvt_pk_bf16(v0[0], v0[1]); w.y = cvt_pk_bf16(v0[2], v0[3]); w.z = cvt_pk_bf16(v1[0], v1[1]); w.w = cvt_pk_bf16(v1[2], v1[3]); return w; }
; __global__ void __launch_bounds__(512, 2) mk_fwd(Args a) {
;     ...
;                     ss += shx(ss, 1, lane); ss += shx(ss, 2, lane);
;                     const float rs = __builtin_amdgcn_rsqf(ss * (1.f / 192.f) + EPS) * (which ? 1.f : C2);
; #pragma unroll
;                     for (int m = 0; m < 6; ++m) { v[m][0] = v[m][0] * rs * (which ? gkv[m][0] : gqv[m][0]); v[m][1] = v[m][1] * rs * (which ? gkv[m][1] : gqv[m][1]); }
;                     const f32x4 a0 = v[4][0], a1 = v[4][1], b0 = v[5][0], b1 = v[5][1];
;                     v[4][0] = a0 * cs0 - b0 * sn0; v[4][1] = a1 * cs1 - b1 * sn1; v[5][0] = b0 * cs0 + a0 * sn0; v[5][1] = b1 * cs1 + a1 * sn1;
;                     bf16_t* op = which ? kp : qp;
; #pragma unroll
;                     for (int m = 0; m < 6; ++m) *(u32x4*)(op + 32 * m) = pg8::pack8(v[m][0], v[m][1]);
	v_add_f32_e32 v156, v156, v157
	ds_bpermute_b32 v157, v162, v156
	s_waitcnt lgkmcnt(0)
	v_add_f32_e32 v156, v156, v157
	v_fmamk_f32 v156, v156, 0x3baaaaab, v202
	v_rsq_f32_e32 v156, v156
	s_nop 0
	v_mul_f32_e32 v156, 0x3dd53b94, v156
	v_pk_mul_f32 v[154:155], v[156:157], v[154:155] op_sel_hi:[0,1]
	v_pk_mul_f32 v[192:193], v[154:155], v[2:3]
	v_pk_mul_f32 v[154:155], v[156:157], v[186:187] op_sel_hi:[0,1]
	v_pk_mul_f32 v[186:187], v[154:155], v[20:21]
	v_pk_mul_f32 v[154:155], v[156:157], v[188:189] op_sel_hi:[0,1]
	v_pk_mul_f32 v[188:189], v[154:155], v[16:17]
	v_pk_mul_f32 v[154:155], v[156:157], v[194:195] op_sel_hi:[0,1]
	v_pk_mul_f32 v[194:195], v[154:155], v[36:37]
	v_pk_mul_f32 v[154:155], v[156:157], v[196:197] op_sel_hi:[0,1]
	v_pk_mul_f32 v[196:197], v[154:155], v[32:33]
	v_pk_mul_f32 v[154:155], v[156:157], v[184:185] op_sel_hi:[0,1]
	v_pk_mul_f32 v[184:185], v[154:155], v[52:53]
	v_pk_mul_f32 v[154:155], v[156:157], v[190:191] op_sel_hi:[0,1]
	v_pk_mul_f32 v[176:177], v[156:157], v[176:177] op_sel_hi:[0,1]
	v_pk_mul_f32 v[142:143], v[156:157], v[142:143] op_sel_hi:[0,1]
	v_pk_mul_f32 v[146:147], v[156:157], v[146:147] op_sel_hi:[0,1]
	v_pk_mul_f32 v[148:149], v[156:157], v[148:149] op_sel_hi:[0,1]
	v_pk_mul_f32 v[158:159], v[156:157], v[158:159] op_sel_hi:[0,1]
	v_pk_mul_f32 v[160:161], v[156:157], v[160:161] op_sel_hi:[0,1]
	v_pk_mul_f32 v[164:165], v[156:157], v[164:165] op_sel_hi:[0,1]
	v_pk_mul_f32 v[166:167], v[156:157], v[166:167] op_sel_hi:[0,1]
	v_pk_mul_f32 v[168:169], v[156:157], v[168:169] op_sel_hi:[0,1]
	v_pk_mul_f32 v[170:171], v[156:157], v[170:171] op_sel_hi:[0,1]
	v_pk_mul_f32 v[190:191], v[154:155], v[48:49]
	v_pk_mul_f32 v[154:155], v[156:157], v[172:173] op_sel_hi:[0,1]
	v_pk_mul_f32 v[172:173], v[156:157], v[198:199] op_sel_hi:[0,1]
	v_pk_mul_f32 v[174:175], v[156:157], v[174:175] op_sel_hi:[0,1]
	v_pk_mul_f32 v[198:199], v[156:157], v[200:201] op_sel_hi:[0,1]
	v_pk_mul_f32 v[200:201], v[156:157], v[210:211] op_sel_hi:[0,1]
	v_pk_mul_f32 v[176:177], v[176:177], v[86:87]
	v_pk_mul_f32 v[206:207], v[156:157], v[212:213] op_sel_hi:[0,1]
	v_pk_mul_f32 v[156:157], v[156:157], v[178:179] op_sel_hi:[0,1]
	v_pk_mul_f32 v[154:155], v[154:155], v[70:71]
	v_pk_mul_f32 v[156:157], v[156:157], v[82:83]
	v_pk_mul_f32 v[178:179], v[206:207], v[80:81]
	v_pk_mul_f32 v[208:209], v[110:111], v[176:177]
	v_pk_mul_f32 v[176:177], v[106:107], v[176:177]
	v_pk_mul_f32 v[198:199], v[198:199], v[64:65]
	v_pk_mul_f32 v[174:175], v[174:175], v[66:67]
	v_pk_fma_f32 v[208:209], v[106:107], v[154:155], v[208:209] neg_lo:[0,0,1] neg_hi:[0,0,1]
	v_pk_mul_f32 v[212:213], v[102:103], v[156:157]
	v_pk_fma_f32 v[176:177], v[110:111], v[154:155], v[176:177]
	v_pk_mul_f32 v[154:155], v[96:97], v[178:179]
	v_pk_mul_f32 v[156:157], v[98:99], v[156:157]
	v_pk_mul_f32 v[146:147], v[146:147], v[6:7]
	v_pk_mul_f32 v[142:143], v[142:143], v[4:5]
	v_pk_mul_f32 v[148:149], v[148:149], v[0:1]
	v_pk_mul_f32 v[210:211], v[100:101], v[178:179]
	v_pk_fma_f32 v[212:213], v[98:99], v[174:175], v[212:213] neg_lo:[0,0,1] neg_hi:[0,0,1]
	v_pk_fma_f32 v[174:175], v[102:103], v[174:175], v[156:157]
	v_pk_fma_f32 v[178:179], v[100:101], v[198:199], v[154:155]
	v_cvt_pk_bf16_f32 v154, v142, v143
	v_cvt_pk_bf16_f32 v155, v146, v147
	v_cvt_pk_bf16_f32 v156, v148, v149
	v_cvt_pk_bf16_f32 v157, v192, v193
	v_pk_mul_f32 v[158:159], v[158:159], v[22:23]
	v_pk_mul_f32 v[160:161], v[160:161], v[18:19]
	global_store_dwordx4 v[140:141], v[154:157], off
	v_pk_mul_f32 v[164:165], v[164:165], v[38:39]
	v_pk_mul_f32 v[166:167], v[166:167], v[34:35]
	v_cvt_pk_bf16_f32 v154, v186, v187
	v_cvt_pk_bf16_f32 v155, v158, v159
	v_cvt_pk_bf16_f32 v156, v188, v189
	v_cvt_pk_bf16_f32 v157, v160, v161
	v_pk_mul_f32 v[200:201], v[200:201], v[84:85]
	global_store_dwordx4 v[140:141], v[154:157], off offset:64
	v_pk_mul_f32 v[168:169], v[168:169], v[54:55]
	v_pk_mul_f32 v[170:171], v[170:171], v[50:51]
	v_cvt_pk_bf16_f32 v154, v194, v195
	v_cvt_pk_bf16_f32 v155, v164, v165
	v_cvt_pk_bf16_f32 v156, v196, v197
	v_cvt_pk_bf16_f32 v157, v166, v167
	v_pk_mul_f32 v[172:173], v[172:173], v[68:69]
	v_pk_mul_f32 v[206:207], v[108:109], v[200:201]
	global_store_dwordx4 v[140:141], v[154:157], off offset:128
	v_pk_fma_f32 v[206:207], v[104:105], v[172:173], v[206:207] neg_lo:[0,0,1] neg_hi:[0,0,1]
	v_pk_fma_f32 v[210:211], v[96:97], v[198:199], v[210:211] neg_lo:[0,0,1] neg_hi:[0,0,1]
	v_cvt_pk_bf16_f32 v154, v184, v185
	v_cvt_pk_bf16_f32 v155, v168, v169
	v_cvt_pk_bf16_f32 v156, v190, v191
	v_cvt_pk_bf16_f32 v157, v170, v171
	v_pk_mul_f32 v[200:201], v[104:105], v[200:201]
	global_store_dwordx4 v[140:141], v[154:157], off offset:192
	v_pk_fma_f32 v[172:173], v[108:109], v[172:173], v[200:201]
	v_lshlrev_b32_e32 v146, 16, v182
	v_cvt_pk_bf16_f32 v154, v206, v207
	v_cvt_pk_bf16_f32 v155, v208, v209
	v_cvt_pk_bf16_f32 v156, v210, v211
	v_cvt_pk_bf16_f32 v157, v212, v213
	global_store_dwordx4 v[140:141], v[154:157], off offset:256
	v_and_b32_e32 v147, 0xffff0000, v182
	v_lshlrev_b32_e32 v148, 16, v183
	v_cvt_pk_bf16_f32 v154, v172, v173
	v_cvt_pk_bf16_f32 v155, v176, v177
	v_cvt_pk_bf16_f32 v156, v178, v179
	v_cvt_pk_bf16_f32 v157, v174, v175
	v_and_b32_e32 v149, 0xffff0000, v183
	v_lshlrev_b32_e32 v160, 16, v130
	v_and_b32_e32 v161, 0xffff0000, v130
	v_lshlrev_b32_e32 v130, 16, v131
	v_and_b32_e32 v131, 0xffff0000, v131
	v_lshlrev_b32_e32 v170, 16, v126
	v_and_b32_e32 v171, 0xffff0000, v126
	v_lshlrev_b32_e32 v126, 16, v127
	v_and_b32_e32 v127, 0xffff0000, v127
	global_store_dwordx4 v[140:141], v[154:157], off offset:320
	v_lshlrev_b32_e32 v140, 16, v180
	v_and_b32_e32 v141, 0xffff0000, v180
; __device__ __forceinline__ float bf_lo(unsigned w) { return __uint_as_float(w << 16); }
; __device__ __forceinline__ float bf_hi(unsigned w) { return __uint_as_float(w & 0xffff0000u); }
; __device__ __forceinline__ float shx(float v, int o, int lane) { return __int_as_float(__builtin_amdgcn_ds_bpermute((lane ^ o) << 2, __float_as_int(v))); }
; __global__ void __launch_bounds__(512, 2) mk_fwd(Args a) {
;     ...
;                 for (int which = 0; which < 2; ++which) {
;                     f32x4 v[6][2]; float ss = 0.f;
; #pragma unroll
;                     for (int m = 0; m < 6; ++m) { const u32x4 w = which ? xk[m] : xq[m];
;                         v[m][0] = (f32x4){bf_lo(w.x), bf_hi(w.x), bf_lo(w.y), bf_hi(w.y)}; v[m][1] = (f32x4){bf_lo(w.z), bf_hi(w.z), bf_lo(w.w), bf_hi(w.w)};
;                         const f32x4 sq = v[m][0] * v[m][0] + v[m][1] * v[m][1]; ss += (sq[0] + sq[1]) + (sq[2] + sq[3]); }
;                     ss += shx(ss, 1, lane); ss += shx(ss, 2, lane);
	v_lshlrev_b32_e32 v142, 16, v181
	v_and_b32_e32 v143, 0xffff0000, v181
	v_pk_mul_f32 v[154:155], v[146:147], v[146:147]
	v_pk_mul_f32 v[156:157], v[148:149], v[148:149]
	v_lshlrev_b32_e32 v158, 16, v128
	v_and_b32_e32 v159, 0xffff0000, v128
	v_lshlrev_b32_e32 v128, 16, v129
	v_and_b32_e32 v129, 0xffff0000, v129
	v_pk_mul_f32 v[164:165], v[160:161], v[160:161]
	v_pk_mul_f32 v[166:167], v[130:131], v[130:131]
	v_lshlrev_b32_e32 v168, 16, v124
	v_and_b32_e32 v169, 0xffff0000, v124
	v_lshlrev_b32_e32 v124, 16, v125
	v_and_b32_e32 v125, 0xffff0000, v125
	v_pk_mul_f32 v[172:173], v[170:171], v[170:171]
	v_pk_mul_f32 v[174:175], v[126:127], v[126:127]
	v_pk_fma_f32 v[156:157], v[142:143], v[142:143], v[156:157]
	v_pk_fma_f32 v[154:155], v[140:141], v[140:141], v[154:155]
	v_pk_fma_f32 v[166:167], v[128:129], v[128:129], v[166:167]
	v_pk_fma_f32 v[164:165], v[158:159], v[158:159], v[164:165]
	v_pk_fma_f32 v[174:175], v[124:125], v[124:125], v[174:175]
	v_pk_fma_f32 v[172:173], v[168:169], v[168:169], v[172:173]
	v_add_f32_e32 v154, v154, v155
	v_add_f32_e32 v156, v156, v157
	v_add_f32_e32 v164, v164, v165
	v_add_f32_e32 v166, v166, v167
	v_mov_b32_e32 v155, v172
	v_mov_b32_e32 v157, v173
	v_mov_b32_e32 v165, v174
	v_mov_b32_e32 v167, v175
	v_pk_add_f32 v[154:155], v[154:155], v[156:157]
	v_pk_add_f32 v[156:157], v[164:165], v[166:167]
	v_lshlrev_b32_e32 v166, 16, v114
	v_and_b32_e32 v167, 0xffff0000, v114
	v_lshlrev_b32_e32 v172, 16, v115
	v_and_b32_e32 v173, 0xffff0000, v115
	v_pk_add_f32 v[154:155], v[154:155], v[156:157]
	v_lshlrev_b32_e32 v156, 16, v112
	v_and_b32_e32 v157, 0xffff0000, v112
	v_lshlrev_b32_e32 v164, 16, v113
	v_and_b32_e32 v165, 0xffff0000, v113
	v_pk_mul_f32 v[112:113], v[166:167], v[166:167]
	v_pk_mul_f32 v[114:115], v[172:173], v[172:173]
	v_pk_fma_f32 v[112:113], v[156:157], v[156:157], v[112:113]
	v_pk_fma_f32 v[114:115], v[164:165], v[164:165], v[114:115]
	v_lshlrev_b32_e32 v178, 16, v122
	v_pk_mov_b32 v[174:175], v[112:113], v[114:115] op_sel:[1,0]
	v_mov_b32_e32 v113, v115
	v_and_b32_e32 v179, 0xffff0000, v122
	v_lshlrev_b32_e32 v180, 16, v123
	v_and_b32_e32 v181, 0xffff0000, v123
	v_lshlrev_b32_e32 v186, 16, v118
	v_and_b32_e32 v187, 0xffff0000, v118
	v_lshlrev_b32_e32 v188, 16, v119
	v_and_b32_e32 v189, 0xffff0000, v119
	v_pk_add_f32 v[112:113], v[174:175], v[112:113]
	v_lshlrev_b32_e32 v174, 16, v120
	v_and_b32_e32 v175, 0xffff0000, v120
	v_lshlrev_b32_e32 v176, 16, v121
	v_and_b32_e32 v177, 0xffff0000, v121
	v_pk_mul_f32 v[114:115], v[178:179], v[178:179]
	v_pk_mul_f32 v[120:121], v[180:181], v[180:181]
	v_lshlrev_b32_e32 v182, 16, v116
	v_and_b32_e32 v183, 0xffff0000, v116
	v_lshlrev_b32_e32 v184, 16, v117
	v_and_b32_e32 v185, 0xffff0000, v117
	v_pk_mul_f32 v[116:117], v[186:187], v[186:187]
	v_pk_mul_f32 v[118:119], v[188:189], v[188:189]
	v_pk_add_f32 v[154:155], v[154:155], v[154:155] op_sel:[0,1] op_sel_hi:[1,0]
	v_pk_add_f32 v[112:113], v[112:113], v[112:113] op_sel:[0,1] op_sel_hi:[1,0]
	v_pk_fma_f32 v[120:121], v[176:177], v[176:177], v[120:121]
	v_pk_fma_f32 v[114:115], v[174:175], v[174:175], v[114:115]
	v_pk_fma_f32 v[118:119], v[184:185], v[184:185], v[118:119]
	v_pk_fma_f32 v[116:117], v[182:183], v[182:183], v[116:117]
	v_add_f32_e32 v114, v114, v115
	v_add_f32_e32 v120, v120, v121
	v_mov_b32_e32 v155, v116
	v_mov_b32_e32 v113, v117
	v_mov_b32_e32 v115, v118
	v_mov_b32_e32 v121, v119
	v_pk_add_f32 v[112:113], v[154:155], v[112:113]
	v_pk_add_f32 v[114:115], v[114:115], v[120:121]
	s_nop 0
	v_pk_add_f32 v[112:113], v[112:113], v[114:115]
	s_nop 0
	v_add_f32_e32 v112, v112, v113
	ds_bpermute_b32 v113, v151, v112
	s_waitcnt lgkmcnt(0)
	v_add_f32_e32 v112, v112, v113
	ds_bpermute_b32 v113, v162, v112
	s_waitcnt lgkmcnt(0)
; __device__ __forceinline__ float shx(float v, int o, int lane) { return __int_as_float(__builtin_amdgcn_ds_bpermute((lane ^ o) << 2, __float_as_int(v))); }
; __device__ __forceinline__ u32x4 pack8(f32x4 v0, f32x4 v1) { u32x4 w; w.x = cvt_pk_bf16(v0[0], v0[1]); w.y = cvt_pk_bf16(v0[2], v0[3]); w.z = cvt_pk_bf16(v1[0], v1[1]); w.w = cvt_pk_bf16(v1[2], v1[3]); return w; }
; __global__ void __launch_bounds__(512, 2) mk_fwd(Args a) {
;     ...
;                     ss += shx(ss, 1, lane); ss += shx(ss, 2, lane);
;                     const float rs = __builtin_amdgcn_rsqf(ss * (1.f / 192.f) + EPS) * (which ? 1.f : C2);
; #pragma unroll
;                     for (int m = 0; m < 6; ++m) { v[m][0] = v[m][0] * rs * (which ? gkv[m][0] : gqv[m][0]); v[m][1] = v[m][1] * rs * (which ? gkv[m][1] : gqv[m][1]); }
;                     const f32x4 a0 = v[4][0], a1 = v[4][1], b0 = v[5][0], b1 = v[5][1];
;                     v[4][0] = a0 * cs0 - b0 * sn0; v[4][1] = a1 * cs1 - b1 * sn1; v[5][0] = b0 * cs0 + a0 * sn0; v[5][1] = b1 * cs1 + a1 * sn1;
;                     bf16_t* op = which ? kp : qp;
; #pragma unroll
;                     for (int m = 0; m < 6; ++m) *(u32x4*)(op + 32 * m) = pg8::pack8(v[m][0], v[m][1]);
	v_add_f32_e32 v112, v112, v113
	v_fmamk_f32 v112, v112, 0x3baaaaab, v202
	v_rsq_f32_e32 v154, v112
	s_nop 0
	v_pk_mul_f32 v[114:115], v[154:155], v[142:143] op_sel_hi:[0,1]
	v_pk_mul_f32 v[112:113], v[154:155], v[140:141] op_sel_hi:[0,1]
	v_pk_mul_f32 v[190:191], v[114:115], v[14:15]
	v_pk_mul_f32 v[114:115], v[154:155], v[148:149] op_sel_hi:[0,1]
	v_pk_mul_f32 v[116:117], v[154:155], v[130:131] op_sel_hi:[0,1]
	v_pk_mul_f32 v[130:131], v[154:155], v[156:157] op_sel_hi:[0,1]
	v_pk_mul_f32 v[156:157], v[154:155], v[176:177] op_sel_hi:[0,1]
	v_pk_mul_f32 v[192:193], v[112:113], v[12:13]
	v_pk_mul_f32 v[112:113], v[154:155], v[146:147] op_sel_hi:[0,1]
	v_pk_mul_f32 v[146:147], v[114:115], v[10:11]
	v_pk_mul_f32 v[114:115], v[154:155], v[158:159] op_sel_hi:[0,1]
	v_pk_mul_f32 v[118:119], v[154:155], v[160:161] op_sel_hi:[0,1]
	v_pk_mul_f32 v[142:143], v[154:155], v[166:167] op_sel_hi:[0,1]
	v_pk_mul_f32 v[158:159], v[154:155], v[174:175] op_sel_hi:[0,1]
	v_pk_mul_f32 v[166:167], v[156:157], v[78:79]
	v_pk_mul_f32 v[156:157], v[154:155], v[180:181] op_sel_hi:[0,1]
	v_pk_mul_f32 v[148:149], v[112:113], v[8:9]
	v_pk_mul_f32 v[112:113], v[154:155], v[128:129] op_sel_hi:[0,1]
	v_pk_mul_f32 v[120:121], v[118:119], v[24:25]
	v_pk_mul_f32 v[118:119], v[154:155], v[124:125] op_sel_hi:[0,1]
	v_pk_mul_f32 v[128:129], v[154:155], v[170:171] op_sel_hi:[0,1]
	v_pk_mul_f32 v[124:125], v[154:155], v[126:127] op_sel_hi:[0,1]
	v_pk_mul_f32 v[126:127], v[154:155], v[164:165] op_sel_hi:[0,1]
	v_pk_mul_f32 v[164:165], v[158:159], v[76:77]
	v_pk_mul_f32 v[158:159], v[154:155], v[178:179] op_sel_hi:[0,1]
	v_pk_mul_f32 v[170:171], v[156:157], v[74:75]
	v_pk_mul_f32 v[156:157], v[154:155], v[182:183] op_sel_hi:[0,1]
	v_pk_mul_f32 v[122:123], v[154:155], v[168:169] op_sel_hi:[0,1]
	v_pk_mul_f32 v[140:141], v[154:155], v[172:173] op_sel_hi:[0,1]
	v_pk_mul_f32 v[168:169], v[158:159], v[72:73]
	v_pk_mul_f32 v[158:159], v[154:155], v[184:185] op_sel_hi:[0,1]
	v_pk_mul_f32 v[174:175], v[156:157], v[92:93]
	v_pk_mul_f32 v[156:157], v[154:155], v[186:187] op_sel_hi:[0,1]
	v_pk_mul_f32 v[154:155], v[154:155], v[188:189] op_sel_hi:[0,1]
	v_pk_mul_f32 v[172:173], v[158:159], v[94:95]
	v_pk_mul_f32 v[176:177], v[154:155], v[90:91]
	v_pk_mul_f32 v[178:179], v[156:157], v[88:89]
	v_pk_mul_f32 v[156:157], v[108:109], v[174:175]
	v_pk_mul_f32 v[154:155], v[110:111], v[172:173]
	v_pk_mul_f32 v[160:161], v[100:101], v[178:179]
	v_pk_mul_f32 v[158:159], v[102:103], v[176:177]
	v_pk_mul_f32 v[174:175], v[104:105], v[174:175]
	v_pk_fma_f32 v[154:155], v[106:107], v[166:167], v[154:155] neg_lo:[0,0,1] neg_hi:[0,0,1]
	v_pk_fma_f32 v[156:157], v[104:105], v[164:165], v[156:157] neg_lo:[0,0,1] neg_hi:[0,0,1]
	v_pk_fma_f32 v[158:159], v[98:99], v[170:171], v[158:159] neg_lo:[0,0,1] neg_hi:[0,0,1]
	v_pk_fma_f32 v[160:161], v[96:97], v[168:169], v[160:161] neg_lo:[0,0,1] neg_hi:[0,0,1]
	v_pk_mul_f32 v[104:105], v[106:107], v[172:173]
	v_pk_fma_f32 v[106:107], v[108:109], v[164:165], v[174:175]
	v_pk_mul_f32 v[96:97], v[96:97], v[178:179]
	v_pk_mul_f32 v[98:99], v[98:99], v[176:177]
	v_add_co_u32_e32 v108, vcc, s3, v138
	v_pk_fma_f32 v[102:103], v[102:103], v[170:171], v[98:99]
	v_pk_fma_f32 v[100:101], v[100:101], v[168:169], v[96:97]
	v_cvt_pk_bf16_f32 v96, v192, v193
	v_cvt_pk_bf16_f32 v97, v190, v191
	v_cvt_pk_bf16_f32 v98, v148, v149
	v_cvt_pk_bf16_f32 v99, v146, v147
	v_addc_co_u32_e32 v109, vcc, 0, v139, vcc
	v_pk_mul_f32 v[112:113], v[112:113], v[30:31]
	v_pk_mul_f32 v[114:115], v[114:115], v[28:29]
	v_pk_mul_f32 v[116:117], v[116:117], v[26:27]
	global_store_dwordx4 v[108:109], v[96:99], off
	v_pk_mul_f32 v[118:119], v[118:119], v[46:47]
	v_pk_mul_f32 v[122:123], v[122:123], v[44:45]
	v_cvt_pk_bf16_f32 v96, v114, v115
	v_cvt_pk_bf16_f32 v97, v112, v113
	v_cvt_pk_bf16_f32 v98, v120, v121
	v_cvt_pk_bf16_f32 v99, v116, v117
	v_pk_mul_f32 v[124:125], v[124:125], v[42:43]
	v_pk_mul_f32 v[128:129], v[128:129], v[40:41]
	global_store_dwordx4 v[108:109], v[96:99], off offset:64
	v_pk_mul_f32 v[126:127], v[126:127], v[62:63]
	v_pk_mul_f32 v[130:131], v[130:131], v[60:61]
	v_cvt_pk_bf16_f32 v96, v122, v123
	v_cvt_pk_bf16_f32 v97, v118, v119
	v_cvt_pk_bf16_f32 v98, v128, v129
	v_cvt_pk_bf16_f32 v99, v124, v125
	v_pk_mul_f32 v[140:141], v[140:141], v[58:59]
	v_pk_mul_f32 v[142:143], v[142:143], v[56:57]
	global_store_dwordx4 v[108:109], v[96:99], off offset:128
	v_pk_fma_f32 v[104:105], v[110:111], v[166:167], v[104:105]
	s_nop 0
	v_cvt_pk_bf16_f32 v96, v130, v131
	v_cvt_pk_bf16_f32 v97, v126, v127
	v_cvt_pk_bf16_f32 v98, v142, v143
	v_cvt_pk_bf16_f32 v99, v140, v141
	global_store_dwordx4 v[108:109], v[96:99], off offset:192
	s_nop 1
	v_cvt_pk_bf16_f32 v96, v156, v157
	v_cvt_pk_bf16_f32 v97, v154, v155
	v_cvt_pk_bf16_f32 v98, v160, v161
	v_cvt_pk_bf16_f32 v99, v158, v159
	global_store_dwordx4 v[108:109], v[96:99], off offset:256
	s_nop 1
	v_cvt_pk_bf16_f32 v96, v106, v107
	v_cvt_pk_bf16_f32 v97, v104, v105
	v_cvt_pk_bf16_f32 v98, v100, v101
	v_cvt_pk_bf16_f32 v99, v102, v103
	global_store_dwordx4 v[108:109], v[96:99], off offset:320
	s_cbranch_scc0 .LBB0_233

; __device__ __forceinline__ unsigned cvt_pk_bf16(float lo, float hi) { unsigned r; asm volatile("v_cvt_pk_bf16_f32 %0, %1, %2" : "=v"(r) : "v"(lo), "v"(hi)); return r; }
; __device__ __forceinline__ float bf_lo(unsigned w) { return __uint_as_float(w << 16); }
; __global__ void __launch_bounds__(512, 2) mk_fwd(Args a) {
;     ...
;             for (int r = gw; r < LSEQ; r += NGW) {
;                 const bf16_t* pr = PA + (size_t)r * NPA;
;                 { u32x2 w[3]; float s = 0.f;
; #pragma unroll
;                   for (int j = 0; j < 3; ++j) { w[j] = *(const u32x2*)(pr + 1024 + (lane + 64 * j) * 4); const float a0 = bf_lo(w[j].x), a1 = bf_hi(w[j].x), a2 = bf_lo(w[j].y), a3 = bf_hi(w[j].y); s += (a0 * a0 + a1 * a1) + (a2 * a2 + a3 * a3); }
;                   const float rs = __builtin_amdgcn_rsqf(wave_sum(s, lane) * (1.f / QL) + EPS);
; #pragma unroll
;                   for (int j = 0; j < 3; ++j) { const f32x4 g = *(const f32x4*)(gqa + (lane + 64 * j) * 4); u32x2 o;
;                       o.x = cvt_pk_bf16(bf_lo(w[j].x) * rs * g.x, bf_hi(w[j].x) * rs * g.y); o.y = cvt_pk_bf16(bf_lo(w[j].y) * rs * g.z, bf_hi(w[j].y) * rs * g.w);
;                       *(u32x2*)(CQN + (size_t)r * QL + (lane + 64 * j) * 4) = o; } }
;                 { u32x2 w[2]; float s = 0.f;
; #pragma unroll
;                   for (int j = 0; j < 2; ++j) { w[j] = *(const u32x2*)(pr + 1792 + (lane + 64 * j) * 4); const float a0 = bf_lo(w[j].x), a1 = bf_hi(w[j].x), a2 = bf_lo(w[j].y), a3 = bf_hi(w[j].y); s += (a0 * a0 + a1 * a1) + (a2 * a2 + a3 * a3); }
;                   const float rs = __builtin_amdgcn_rsqf(wave_sum(s, lane) * (1.f / KVL) + EPS);
; #pragma unroll
;                   for (int j = 0; j < 2; ++j) { const f32x4 g = *(const f32x4*)(gkva + (lane + 64 * j) * 4); u32x2 o;
;                       o.x = cvt_pk_bf16(bf_lo(w[j].x) * rs * g.x, bf_hi(w[j].x) * rs * g.y); o.y = cvt_pk_bf16(bf_lo(w[j].y) * rs * g.z, bf_hi(w[j].y) * rs * g.w);
;                       *(u32x2*)(CKVN + (size_t)r * KVL + (lane + 64 * j) * 4) = o; } }
;                 { const int rl = row_left(r), rr = row_right(r);
;                   const bf16_t* pl = PA + (size_t)(rl < 0 ? r : rl) * NPA; const bf16_t* pq = PA + (size_t)(rr < 0 ? r : rr) * NPA;
;                   const float ml = rl < 0 ? 0.f : 1.f, mr = rr < 0 ? 0.f : 1.f;
.LBB0_239:
	v_lshl_add_u64 v[38:39], s[64:65], 0, v[26:27]
	v_add_co_u32_e32 v62, vcc, 0xfc01000, v38
	global_load_dwordx4 v[0:3], v[4:5], off
	s_nop 0
	v_addc_co_u32_e32 v63, vcc, 0, v39, vcc
	global_load_dwordx2 v[68:69], v[62:63], off offset:2048
	global_load_dwordx2 v[70:71], v[62:63], off offset:2560
	global_load_dwordx2 v[72:73], v[62:63], off offset:3072
	v_lshl_add_u64 v[40:41], s[64:65], 0, v[18:19]
	v_add_co_u32_e64 v64, s[0:1], s13, v40
	v_lshl_add_u64 v[42:43], s[64:65], 0, v[20:21]
	s_nop 0
	v_addc_co_u32_e64 v65, s[0:1], 0, v41, s[0:1]
	s_mov_b32 s0, 0xe761000
	s_nop 0
	v_add_co_u32_e64 v66, s[0:1], s0, v42
	v_lshl_add_u64 v[44:45], s[64:65], 0, v[32:33]
	s_nop 0
	v_addc_co_u32_e64 v67, s[0:1], 0, v43, s[0:1]
	v_add_co_u32_e64 v78, s[0:1], s18, v44
	v_lshl_add_u64 v[46:47], s[64:65], 0, v[24:25]
	s_nop 0
	v_addc_co_u32_e64 v79, s[0:1], 0, v45, s[0:1]
	v_add_co_u32_e64 v82, s[0:1], s24, v44
	v_lshl_add_u64 v[36:37], s[64:65], 0, v[28:29]
	s_nop 0
	v_addc_co_u32_e64 v83, s[0:1], 0, v45, s[0:1]
	s_mov_b32 s0, 0x22d41000
	s_nop 0
	v_add_co_u32_e64 v40, s[0:1], s0, v46
	s_waitcnt vmcnt(0)
	v_lshl_add_u64 v[50:51], s[64:65], 0, v[30:31]
	v_addc_co_u32_e64 v41, s[0:1], 0, v47, s[0:1]
	v_add_co_u32_e64 v42, s[0:1], s18, v50
	v_sub_co_u32_e64 v48, s[2:3], s6, 1
	s_nop 0
	v_addc_co_u32_e64 v43, s[0:1], 0, v51, s[0:1]
	s_cmpk_lg_i32 s6, 0x2000
	v_readfirstlane_b32 s7, v48
	v_add_co_u32_e64 v44, s[0:1], s24, v50
	s_cselect_b32 s7, s7, -1
	s_nop 0
	v_addc_co_u32_e64 v45, s[0:1], 0, v51, s[0:1]
	s_and_b64 s[0:1], s[2:3], exec
	s_cselect_b32 s2, 0x200f, s7
	s_add_i32 s0, s6, 1
	s_cmpk_lg_i32 s6, 0x200f
	s_cselect_b32 s0, s0, 0
	s_cmpk_lg_i32 s6, 0x1fff
	s_cselect_b32 s3, s0, -1
	s_cmp_lt_i32 s2, 0
	s_cselect_b64 s[0:1], -1, 0
	v_cndmask_b32_e64 v38, 1.0, 0, s[0:1]
	s_and_b64 s[0:1], s[0:1], exec
	s_cselect_b32 s0, s6, s2
	s_mul_hi_i32 s1, s0, 0x2a00
	s_mulk_i32 s0, 0x2a00
	s_add_u32 s2, s84, s0
	s_addc_u32 s7, s85, s1
	s_cmp_lt_i32 s3, 0
	s_cselect_b64 s[0:1], -1, 0
	v_cndmask_b32_e64 v46, 1.0, 0, s[0:1]
	s_and_b64 s[0:1], s[0:1], exec
	s_cselect_b32 s0, s6, s3
	s_mul_hi_i32 s1, s0, 0x2a00
	s_mulk_i32 s0, 0x2a00
	s_add_u32 s8, s84, s0
	s_addc_u32 s9, s85, s1
	s_add_u32 s0, s2, 0x1a00
	s_addc_u32 s1, s7, 0
	s_add_u32 s2, s2, 0x2200
	s_addc_u32 s3, s7, 0
	v_lshl_add_u64 v[74:75], s[0:1], 0, v[22:23]
	v_lshl_add_u64 v[48:49], s[0:1], 0, v[34:35]
	s_add_u32 s0, s8, 0x1a00
	s_addc_u32 s1, s9, 0
	v_lshl_add_u64 v[76:77], s[2:3], 0, v[22:23]
	v_lshl_add_u64 v[50:51], s[2:3], 0, v[34:35]
	s_add_u32 s2, s8, 0x2200
	s_waitcnt lgkmcnt(0)
	v_lshlrev_b32_e32 v39, 16, v68
	v_and_b32_e32 v47, 0xffff0000, v68
	v_lshlrev_b32_e32 v68, 16, v69
	v_and_b32_e32 v69, 0xffff0000, v69
	v_lshlrev_b32_e32 v86, 16, v70
	v_and_b32_e32 v70, 0xffff0000, v70
	v_lshlrev_b32_e32 v87, 16, v71
	v_and_b32_e32 v71, 0xffff0000, v71
	v_lshlrev_b32_e32 v88, 16, v72
	v_and_b32_e32 v72, 0xffff0000, v72
	v_lshlrev_b32_e32 v89, 16, v73
	v_and_b32_e32 v73, 0xffff0000, v73
	v_mul_f32_e32 v90, v47, v47
	v_mul_f32_e32 v91, v69, v69
	v_mul_f32_e32 v92, v70, v70
	v_mul_f32_e32 v93, v71, v71
	v_mul_f32_e32 v94, v72, v72
	v_mul_f32_e32 v95, v73, v73
	v_fmac_f32_e32 v90, v39, v39
	v_fmac_f32_e32 v91, v68, v68
	v_fmac_f32_e32 v92, v86, v86
	v_fmac_f32_e32 v93, v87, v87
	v_fmac_f32_e32 v94, v88, v88
	v_fmac_f32_e32 v95, v89, v89
	v_add_f32_e32 v90, v90, v91
	v_add_f32_e32 v91, v92, v93
	v_add_f32_e32 v92, v94, v95
	v_add_f32_e32 v90, v90, v91
	v_add_f32_e32 v90, v90, v92
	ds_bpermute_b32 v91, v56, v90
	s_addc_u32 s3, s9, 0
	v_lshl_add_u64 v[80:81], s[0:1], 0, v[22:23]
	v_lshl_add_u64 v[84:85], s[2:3], 0, v[22:23]
	v_lshl_add_u64 v[52:53], s[0:1], 0, v[34:35]
	s_waitcnt lgkmcnt(0)
	v_add_f32_e32 v90, v90, v91
	ds_bpermute_b32 v91, v57, v90
	v_lshl_add_u64 v[54:55], s[2:3], 0, v[34:35]
	s_add_i32 s6, s6, s72
	v_lshl_add_u64 v[18:19], v[18:19], 0, s[28:29]
	v_lshl_add_u64 v[20:21], v[20:21], 0, s[4:5]
	s_waitcnt lgkmcnt(0)
	v_add_f32_e32 v90, v90, v91
	ds_bpermute_b32 v91, v58, v90
	v_lshl_add_u64 v[24:25], v[24:25], 0, s[80:81]
	v_lshl_add_u64 v[26:27], v[26:27], 0, s[34:35]
	v_lshl_add_u64 v[28:29], v[28:29], 0, s[34:35]
	v_lshl_add_u64 v[30:31], v[30:31], 0, s[34:35]
	s_waitcnt lgkmcnt(0)
	v_add_f32_e32 v90, v90, v91
	ds_bpermute_b32 v91, v59, v90
	v_lshl_add_u64 v[32:33], v[32:33], 0, s[34:35]
	s_cmpk_gt_i32 s6, 0x200f
	s_waitcnt lgkmcnt(0)
	v_add_f32_e32 v90, v90, v91
	ds_bpermute_b32 v91, v60, v90
	s_waitcnt lgkmcnt(0)
	v_add_f32_e32 v90, v90, v91
	ds_bpermute_b32 v91, v61, v90
	s_waitcnt lgkmcnt(0)
	v_add_f32_e32 v90, v90, v91
	v_fmamk_f32 v90, v90, 0x3aaaaaab, v202
	v_rsq_f32_e32 v90, v90
	s_nop 0
	v_mul_f32_e32 v39, v90, v39
	v_mul_f32_e32 v47, v90, v47
	v_mul_f32_e32 v68, v90, v68
	v_mul_f32_e32 v69, v90, v69
	v_mul_f32_e32 v0, v0, v39
	v_mul_f32_e32 v1, v1, v47
	v_mul_f32_e32 v2, v2, v68
	v_mul_f32_e32 v3, v3, v69
	v_cvt_pk_bf16_f32 v0, v0, v1
	v_cvt_pk_bf16_f32 v1, v2, v3
	global_store_dwordx2 v[64:65], v[0:1], off
	global_load_dwordx4 v[0:3], v[4:5], off offset:1024
	v_mul_f32_e32 v86, v90, v86
	v_mul_f32_e32 v70, v90, v70
	v_mul_f32_e32 v87, v90, v87
	v_mul_f32_e32 v71, v90, v71
	v_mul_f32_e32 v88, v90, v88
	v_mul_f32_e32 v72, v90, v72
	v_mul_f32_e32 v89, v90, v89
	v_mul_f32_e32 v73, v90, v73
	s_waitcnt vmcnt(0)
	v_mul_f32_e32 v0, v0, v86
	v_mul_f32_e32 v1, v1, v70
	v_mul_f32_e32 v2, v2, v87
	v_mul_f32_e32 v3, v3, v71
	v_cvt_pk_bf16_f32 v0, v0, v1
	v_cvt_pk_bf16_f32 v1, v2, v3
	global_store_dwordx2 v[64:65], v[0:1], off offset:512
	global_load_dwordx4 v[0:3], v[4:5], off offset:2048
	s_waitcnt vmcnt(0)
; __device__ __forceinline__ unsigned cvt_pk_bf16(float lo, float hi) { unsigned r; asm volatile("v_cvt_pk_bf16_f32 %0, %1, %2" : "=v"(r) : "v"(lo), "v"(hi)); return r; }
; __device__ __forceinline__ float bf_lo(unsigned w) { return __uint_as_float(w << 16); }
; __device__ __forceinline__ float bf_hi(unsigned w) { return __uint_as_float(w & 0xffff0000u); }
; __global__ void __launch_bounds__(512, 2) mk_fwd(Args a) {
;     ...
;                 { u32x2 w[2]; float s = 0.f;
; #pragma unroll
;                   for (int j = 0; j < 2; ++j) { w[j] = *(const u32x2*)(pr + 1792 + (lane + 64 * j) * 4); const float a0 = bf_lo(w[j].x), a1 = bf_hi(w[j].x), a2 = bf_lo(w[j].y), a3 = bf_hi(w[j].y); s += (a0 * a0 + a1 * a1) + (a2 * a2 + a3 * a3); }
;                   const float rs = __builtin_amdgcn_rsqf(wave_sum(s, lane) * (1.f / KVL) + EPS);
; #pragma unroll
;                   for (int j = 0; j < 2; ++j) { const f32x4 g = *(const f32x4*)(gkva + (lane + 64 * j) * 4); u32x2 o;
;                       o.x = cvt_pk_bf16(bf_lo(w[j].x) * rs * g.x, bf_hi(w[j].x) * rs * g.y); o.y = cvt_pk_bf16(bf_lo(w[j].y) * rs * g.z, bf_hi(w[j].y) * rs * g.w);
;                       *(u32x2*)(CKVN + (size_t)r * KVL + (lane + 64 * j) * 4) = o; } }
;                 { const int rl = row_left(r), rr = row_right(r);
;                   const bf16_t* pl = PA + (size_t)(rl < 0 ? r : rl) * NPA; const bf16_t* pq = PA + (size_t)(rr < 0 ? r : rr) * NPA;
;                   const float ml = rl < 0 ? 0.f : 1.f, mr = rr < 0 ? 0.f : 1.f;
; #pragma unroll
;                   for (int j = 0; j < 2; ++j) { const int c = (lane + 64 * j) * 8;
;                       const u32x4 b = *(const u32x4*)(pr + 2304 + c);
;                       const u32x4 c0 = *(const u32x4*)(pl + 3328 + c), h0 = *(const u32x4*)(pl + 4352 + c);
;                       const u32x4 c1 = *(const u32x4*)(pr + 3328 + c), h1 = *(const u32x4*)(pr + 4352 + c);
;                       const u32x4 c2 = *(const u32x4*)(pq + 3328 + c), h2 = *(const u32x4*)(pq + 4352 + c);
;                       const f32x4 w0 = *(const f32x4*)(cw + c) * ml, w0b = *(const f32x4*)(cw + c + 4) * ml, w1 = *(const f32x4*)(cw + 1024 + c), w1b = *(const f32x4*)(cw + 1024 + c + 4);
;                       const f32x4 w2 = *(const f32x4*)(cw + 2048 + c) * mr, w2b = *(const f32x4*)(cw + 2048 + c + 4) * mr;
	v_mul_f32_e32 v0, v0, v88
	v_mul_f32_e32 v1, v1, v72
	v_mul_f32_e32 v2, v2, v89
	v_mul_f32_e32 v3, v3, v73
	v_cvt_pk_bf16_f32 v0, v0, v1
	v_cvt_pk_bf16_f32 v1, v2, v3
	global_store_dwordx2 v[64:65], v[0:1], off offset:1024
	global_load_dwordx2 v[62:63], v[62:63], off offset:3584
	global_load_dwordx2 v[36:37], v[36:37], off
	global_load_dwordx4 v[0:3], v[6:7], off
	s_waitcnt vmcnt(0) lgkmcnt(0)
	v_lshlrev_b32_e32 v39, 16, v62
	v_and_b32_e32 v47, 0xffff0000, v62
	v_lshlrev_b32_e32 v62, 16, v63
	v_and_b32_e32 v63, 0xffff0000, v63
	v_lshlrev_b32_e32 v64, 16, v36
	v_and_b32_e32 v36, 0xffff0000, v36
	v_lshlrev_b32_e32 v65, 16, v37
	v_and_b32_e32 v37, 0xffff0000, v37
	v_mul_f32_e32 v68, v47, v47
	v_mul_f32_e32 v69, v63, v63
	v_mul_f32_e32 v70, v36, v36
	v_mul_f32_e32 v71, v37, v37
	v_fmac_f32_e32 v68, v39, v39
	v_fmac_f32_e32 v69, v62, v62
	v_fmac_f32_e32 v70, v64, v64
	v_fmac_f32_e32 v71, v65, v65
	v_add_f32_e32 v68, v68, v69
	v_add_f32_e32 v69, v70, v71
	v_add_f32_e32 v68, v68, v69
	ds_bpermute_b32 v69, v56, v68
	s_waitcnt lgkmcnt(0)
	v_add_f32_e32 v68, v68, v69
	ds_bpermute_b32 v69, v57, v68
	s_waitcnt lgkmcnt(0)
	v_add_f32_e32 v68, v68, v69
	ds_bpermute_b32 v69, v58, v68
	s_waitcnt lgkmcnt(0)
	v_add_f32_e32 v68, v68, v69
	ds_bpermute_b32 v69, v59, v68
	s_waitcnt lgkmcnt(0)
	v_add_f32_e32 v68, v68, v69
	ds_bpermute_b32 v69, v60, v68
	s_waitcnt lgkmcnt(0)
	v_add_f32_e32 v68, v68, v69
	ds_bpermute_b32 v69, v61, v68
	s_waitcnt lgkmcnt(0)
	v_add_f32_e32 v68, v68, v69
	v_fmamk_f32 v68, v68, 0x3b000000, v202
	v_rsq_f32_e32 v68, v68
	s_nop 0
	v_mul_f32_e32 v39, v68, v39
	v_mul_f32_e32 v47, v68, v47
	v_mul_f32_e32 v62, v68, v62
	v_mul_f32_e32 v63, v68, v63
	v_mul_f32_e32 v0, v0, v39
	v_mul_f32_e32 v1, v1, v47
	v_mul_f32_e32 v2, v2, v62
	v_mul_f32_e32 v3, v3, v63
	v_cvt_pk_bf16_f32 v0, v0, v1
	v_cvt_pk_bf16_f32 v1, v2, v3
	global_store_dwordx2 v[66:67], v[0:1], off
	global_load_dwordx4 v[0:3], v[6:7], off offset:1024
	v_mul_f32_e32 v64, v68, v64
	v_mul_f32_e32 v36, v68, v36
	v_mul_f32_e32 v65, v68, v65
	v_mul_f32_e32 v37, v68, v37
	s_waitcnt vmcnt(0)
	v_mul_f32_e32 v0, v0, v64
	v_mul_f32_e32 v1, v1, v36
	v_mul_f32_e32 v2, v2, v65
	v_mul_f32_e32 v3, v3, v37
	v_cvt_pk_bf16_f32 v0, v0, v1
	v_cvt_pk_bf16_f32 v1, v2, v3
	global_store_dwordx2 v[66:67], v[0:1], off offset:512
	global_load_dwordx4 v[0:3], v[78:79], off offset:2560
	global_load_dwordx4 v[62:65], v[80:81], off
	global_load_dwordx4 v[66:69], v[74:75], off
	global_load_dwordx4 v[70:73], v[84:85], off
	global_load_dwordx4 v[74:77], v[76:77], off
	global_load_dwordx4 v[78:81], v[78:79], off offset:512
	global_load_dwordx4 v[82:85], v[82:83], off offset:512
	global_load_dwordx4 v[86:89], v[8:9], off
	global_load_dwordx4 v[90:93], v[8:9], off offset:16
	global_load_dwordx4 v[94:97], v[12:13], off
	global_load_dwordx4 v[98:101], v[12:13], off offset:16
	global_load_dwordx4 v[102:105], v[10:11], off
	global_load_dwordx4 v[106:109], v[10:11], off offset:16
	s_waitcnt vmcnt(0) lgkmcnt(0)
	v_lshlrev_b32_e32 v39, 16, v0
	v_and_b32_e32 v47, 0xffff0000, v0
	v_lshlrev_b32_e32 v37, 16, v62
	v_lshlrev_b32_e32 v36, 16, v66
	v_lshlrev_b32_e32 v111, 16, v70
	v_and_b32_e32 v113, 0xffff0000, v62
	v_and_b32_e32 v112, 0xffff0000, v66
	v_and_b32_e32 v115, 0xffff0000, v70
	v_lshlrev_b32_e32 v124, 16, v1
	v_lshlrev_b32_e32 v117, 16, v63
	v_lshlrev_b32_e32 v116, 16, v67
	v_and_b32_e32 v125, 0xffff0000, v1
	v_and_b32_e32 v1, 0xffff0000, v63
	v_and_b32_e32 v0, 0xffff0000, v67
	v_lshlrev_b32_e32 v63, 16, v64
	v_and_b32_e32 v67, 0xffff0000, v64
	v_lshlrev_b32_e32 v126, 16, v2
	v_lshlrev_b32_e32 v62, 16, v68
	v_and_b32_e32 v66, 0xffff0000, v68
	v_lshlrev_b32_e32 v120, 16, v69
	v_and_b32_e32 v64, 0xffff0000, v69
	v_lshlrev_b32_e32 v69, 16, v72
	v_and_b32_e32 v127, 0xffff0000, v2
	v_lshlrev_b32_e32 v128, 16, v3
	v_and_b32_e32 v129, 0xffff0000, v3
	v_and_b32_e32 v3, 0xffff0000, v72
	v_lshlrev_b32_e32 v110, 16, v74
	v_and_b32_e32 v114, 0xffff0000, v74
	v_lshlrev_b32_e32 v118, 16, v75
	v_and_b32_e32 v70, 0xffff0000, v75
	v_lshlrev_b32_e32 v68, 16, v76
	v_and_b32_e32 v2, 0xffff0000, v76
	v_lshlrev_b32_e32 v122, 16, v77
	v_and_b32_e32 v72, 0xffff0000, v77
	v_lshlrev_b32_e32 v130, 16, v78
	v_and_b32_e32 v131, 0xffff0000, v78
	v_lshlrev_b32_e32 v132, 16, v79
	v_and_b32_e32 v133, 0xffff0000, v79
	v_lshlrev_b32_e32 v134, 16, v80
	v_and_b32_e32 v135, 0xffff0000, v80
	v_lshlrev_b32_e32 v136, 16, v81
	v_and_b32_e32 v137, 0xffff0000, v81
	v_lshlrev_b32_e32 v138, 16, v82
	v_and_b32_e32 v139, 0xffff0000, v82
	v_lshlrev_b32_e32 v140, 16, v83
	v_and_b32_e32 v141, 0xffff0000, v83
	v_lshlrev_b32_e32 v142, 16, v84
	v_and_b32_e32 v143, 0xffff0000, v84
	v_lshlrev_b32_e32 v144, 16, v85
	v_and_b32_e32 v146, 0xffff0000, v85
	v_pk_mul_f32 v[74:75], v[38:39], v[88:89] op_sel_hi:[0,1]
	v_pk_mul_f32 v[76:77], v[38:39], v[86:87] op_sel_hi:[0,1]
	v_pk_mul_f32 v[78:79], v[38:39], v[92:93] op_sel_hi:[0,1]
	v_pk_mul_f32 v[80:81], v[38:39], v[90:91] op_sel_hi:[0,1]
	v_pk_mul_f32 v[82:83], v[46:47], v[96:97] op_sel_hi:[0,1]
	v_pk_mul_f32 v[84:85], v[46:47], v[94:95] op_sel_hi:[0,1]
	v_pk_mul_f32 v[86:87], v[46:47], v[100:101] op_sel_hi:[0,1]
	v_pk_mul_f32 v[88:89], v[46:47], v[98:99] op_sel_hi:[0,1]
	v_lshlrev_b32_e32 v121, 16, v65
	v_mov_b32_e32 v90, v76
	v_mov_b32_e32 v91, v84
	v_mov_b32_e32 v84, v77
	v_mov_b32_e32 v76, v74
	v_mov_b32_e32 v77, v82
	v_mov_b32_e32 v82, v75
	v_mov_b32_e32 v74, v80
	v_mov_b32_e32 v75, v88
	v_mov_b32_e32 v88, v81
	v_mov_b32_e32 v80, v78
	v_mov_b32_e32 v81, v86
	v_and_b32_e32 v65, 0xffff0000, v65
	v_lshlrev_b32_e32 v123, 16, v73
	v_mov_b32_e32 v86, v79
	v_pk_mul_f32 v[62:63], v[74:75], v[62:63]
	v_pk_mul_f32 v[66:67], v[88:89], v[66:67]
; __global__ void __launch_bounds__(512, 2) mk_fwd(Args a) {
;     ...
;                   for (int j = 0; j < 2; ++j) { const int c = (lane + 64 * j) * 8;
;                       const u32x4 b = *(const u32x4*)(pr + 2304 + c);
;                       const u32x4 c0 = *(const u32x4*)(pl + 3328 + c), h0 = *(const u32x4*)(pl + 4352 + c);
;                       const u32x4 c1 = *(const u32x4*)(pr + 3328 + c), h1 = *(const u32x4*)(pr + 4352 + c);
;                       const u32x4 c2 = *(const u32x4*)(pq + 3328 + c), h2 = *(const u32x4*)(pq + 4352 + c);
;                       const f32x4 w0 = *(const f32x4*)(cw + c) * ml, w0b = *(const f32x4*)(cw + c + 4) * ml, w1 = *(const f32x4*)(cw + 1024 + c), w1b = *(const f32x4*)(cw + 1024 + c + 4);
;                       const f32x4 w2 = *(const f32x4*)(cw + 2048 + c) * mr, w2b = *(const f32x4*)(cw + 2048 + c + 4) * mr;
;                       u32x4 o;
;                       o.x = convpair(b.x, c0.x, h0.x, c1.x, h1.x, c2.x, h2.x, w0.x, w0.y, w1.x, w1.y, w2.x, w2.y);
;                       o.y = convpair(b.y, c0.y, h0.y, c1.y, h1.y, c2.y, h2.y, w0.z, w0.w, w1.z, w1.w, w2.z, w2.w);
;                       o.z = convpair(b.z, c0.z, h0.z, c1.z, h1.z, c2.z, h2.z, w0b.x, w0b.y, w1b.x, w1b.y, w2b.x, w2b.y);
;                       o.w = convpair(b.w, c0.w, h0.w, c1.w, h1.w, c2.w, h2.w, w0b.z, w0b.w, w1b.z, w1b.w, w2b.z, w2b.w);
;                       *(u32x4*)(CC + (size_t)r * 1024 + c) = o; } }
	v_pk_mul_f32 v[74:75], v[80:81], v[120:121]
	v_lshlrev_b32_e32 v119, 16, v71
	v_and_b32_e32 v71, 0xffff0000, v71
	v_and_b32_e32 v73, 0xffff0000, v73
	v_mul_f32_e32 v95, v107, v127
	v_mul_f32_e32 v96, v108, v128
	v_pk_mul_f32 v[36:37], v[90:91], v[36:37]
	v_pk_mul_f32 v[78:79], v[84:85], v[112:113]
	v_pk_mul_f32 v[76:77], v[76:77], v[116:117]
	v_pk_mul_f32 v[0:1], v[82:83], v[0:1]
	v_pk_mul_f32 v[64:65], v[86:87], v[64:65]
	v_pk_mul_f32 v[2:3], v[66:67], v[2:3]
	v_pk_mul_f32 v[66:67], v[74:75], v[122:123]
	v_mul_f32_e32 v39, v102, v39
	v_mul_f32_e32 v47, v103, v47
	v_mul_f32_e32 v92, v104, v124
	v_mul_f32_e32 v93, v105, v125
	v_mul_f32_e32 v94, v106, v126
	v_mul_f32_e32 v97, v109, v129
	v_pk_mul_f32 v[36:37], v[36:37], v[110:111]
	v_pk_mul_f32 v[78:79], v[78:79], v[114:115]
	v_pk_mul_f32 v[76:77], v[76:77], v[118:119]
	v_pk_mul_f32 v[0:1], v[0:1], v[70:71]
	v_pk_mul_f32 v[62:63], v[62:63], v[68:69]
	v_pk_mul_f32 v[64:65], v[64:65], v[72:73]
	v_fma_f32 v2, v95, v143, v2
	v_fma_f32 v66, v96, v144, v66
	v_fma_f32 v36, v39, v138, v36
	v_fma_f32 v39, v47, v139, v78
	v_fma_f32 v47, v92, v140, v76
	v_fma_f32 v0, v93, v141, v0
	v_fma_f32 v62, v94, v142, v62
	v_fma_f32 v64, v97, v146, v64
	v_add_f32_e32 v2, v2, v3
	v_add_f32_e32 v3, v66, v67
	v_add_f32_e32 v36, v36, v37
	v_add_f32_e32 v37, v39, v79
	v_add_f32_e32 v39, v47, v77
	v_add_f32_e32 v0, v0, v1
	v_add_f32_e32 v1, v62, v63
	v_add_f32_e32 v47, v64, v65
	v_mul_f32_e32 v2, v2, v135
	v_mul_f32_e32 v3, v3, v136
	v_mul_f32_e32 v36, v36, v130
	v_mul_f32_e32 v37, v37, v131
	v_mul_f32_e32 v39, v39, v132
	v_mul_f32_e32 v62, v0, v133
	v_mul_f32_e32 v63, v1, v134
	v_mul_f32_e32 v47, v47, v137
	v_cvt_pk_bf16_f32 v0, v36, v37
	v_cvt_pk_bf16_f32 v1, v39, v62
	v_cvt_pk_bf16_f32 v2, v63, v2
	v_cvt_pk_bf16_f32 v3, v3, v47
	global_store_dwordx4 v[40:41], v[0:3], off
	global_load_dwordx4 v[0:3], v[8:9], off offset:2048
	global_load_dwordx4 v[62:65], v[8:9], off offset:2064
	global_load_dwordx4 v[66:69], v[16:17], off
	global_load_dwordx4 v[70:73], v[16:17], off offset:16
	global_load_dwordx4 v[74:77], v[52:53], off
	global_load_dwordx4 v[78:81], v[48:49], off
	global_load_dwordx4 v[52:55], v[54:55], off
	global_load_dwordx4 v[48:51], v[50:51], off
	global_load_dwordx4 v[82:85], v[42:43], off offset:2560
	global_load_dwordx4 v[86:89], v[42:43], off offset:512
	global_load_dwordx4 v[42:45], v[44:45], off offset:512
	global_load_dwordx4 v[90:93], v[14:15], off
	global_load_dwordx4 v[94:97], v[14:15], off offset:16
	s_waitcnt vmcnt(0)
	v_pk_mul_f32 v[2:3], v[38:39], v[2:3] op_sel_hi:[0,1]
	v_pk_mul_f32 v[0:1], v[38:39], v[0:1] op_sel_hi:[0,1]
	v_pk_mul_f32 v[36:37], v[38:39], v[64:65] op_sel_hi:[0,1]
	v_pk_mul_f32 v[38:39], v[38:39], v[62:63] op_sel_hi:[0,1]
	v_pk_mul_f32 v[62:63], v[46:47], v[68:69] op_sel_hi:[0,1]
	v_pk_mul_f32 v[64:65], v[46:47], v[66:67] op_sel_hi:[0,1]
	v_pk_mul_f32 v[66:67], v[46:47], v[72:73] op_sel_hi:[0,1]
	v_pk_mul_f32 v[46:47], v[46:47], v[70:71] op_sel_hi:[0,1]
	s_waitcnt lgkmcnt(0)
	v_lshlrev_b32_e32 v69, 16, v74
	v_and_b32_e32 v73, 0xffff0000, v74
	v_lshlrev_b32_e32 v101, 16, v75
	v_lshlrev_b32_e32 v100, 16, v79
	v_and_b32_e32 v75, 0xffff0000, v75
	v_lshlrev_b32_e32 v103, 16, v76
	v_and_b32_e32 v105, 0xffff0000, v76
	v_and_b32_e32 v74, 0xffff0000, v79
	v_lshlrev_b32_e32 v102, 16, v80
	v_and_b32_e32 v104, 0xffff0000, v80
	v_lshlrev_b32_e32 v116, 16, v42
	v_and_b32_e32 v117, 0xffff0000, v42
	v_lshlrev_b32_e32 v118, 16, v43
	v_and_b32_e32 v119, 0xffff0000, v43
	v_mov_b32_e32 v42, v0
	v_mov_b32_e32 v43, v64
	v_mov_b32_e32 v64, v1
	v_mov_b32_e32 v0, v2
	v_mov_b32_e32 v1, v62
	v_mov_b32_e32 v62, v3
	v_mov_b32_e32 v2, v38
	v_mov_b32_e32 v3, v46
	v_mov_b32_e32 v46, v39
	v_lshlrev_b32_e32 v68, 16, v78
	v_lshlrev_b32_e32 v71, 16, v52
	v_and_b32_e32 v72, 0xffff0000, v78
	v_and_b32_e32 v99, 0xffff0000, v52
	v_lshlrev_b32_e32 v107, 16, v77
	v_and_b32_e32 v77, 0xffff0000, v77
	v_lshlrev_b32_e32 v109, 16, v53
	v_lshlrev_b32_e32 v106, 16, v81
	v_and_b32_e32 v76, 0xffff0000, v81
	v_and_b32_e32 v53, 0xffff0000, v53
	v_lshlrev_b32_e32 v79, 16, v54
	v_and_b32_e32 v81, 0xffff0000, v54
	v_lshlrev_b32_e32 v70, 16, v48
	v_and_b32_e32 v98, 0xffff0000, v48
	v_lshlrev_b32_e32 v108, 16, v49
	v_and_b32_e32 v52, 0xffff0000, v49
	v_lshlrev_b32_e32 v78, 16, v50
	v_and_b32_e32 v80, 0xffff0000, v50
	v_lshlrev_b32_e32 v110, 16, v51
	v_and_b32_e32 v54, 0xffff0000, v51
	v_lshlrev_b32_e32 v48, 16, v82
	v_and_b32_e32 v49, 0xffff0000, v82
	v_lshlrev_b32_e32 v50, 16, v83
	v_and_b32_e32 v51, 0xffff0000, v83
	v_lshlrev_b32_e32 v82, 16, v84
	v_and_b32_e32 v83, 0xffff0000, v84
	v_lshlrev_b32_e32 v120, 16, v44
	v_and_b32_e32 v121, 0xffff0000, v44
	v_lshlrev_b32_e32 v122, 16, v45
	v_and_b32_e32 v123, 0xffff0000, v45
	v_mov_b32_e32 v38, v36
	v_mov_b32_e32 v39, v66
	v_mov_b32_e32 v66, v37
	v_pk_mul_f32 v[0:1], v[0:1], v[100:101]
	v_pk_mul_f32 v[44:45], v[62:63], v[74:75]
	v_pk_mul_f32 v[2:3], v[2:3], v[102:103]
	v_pk_mul_f32 v[46:47], v[46:47], v[104:105]
	v_lshlrev_b32_e32 v111, 16, v55
	v_and_b32_e32 v55, 0xffff0000, v55
	v_lshlrev_b32_e32 v84, 16, v85
	v_and_b32_e32 v85, 0xffff0000, v85
	v_mul_f32_e32 v90, v90, v48
	v_mul_f32_e32 v91, v91, v49
	v_mul_f32_e32 v50, v92, v50
	v_mul_f32_e32 v51, v93, v51
	v_mul_f32_e32 v82, v94, v82
	v_mul_f32_e32 v83, v95, v83
	v_pk_mul_f32 v[36:37], v[42:43], v[68:69]
	v_pk_mul_f32 v[42:43], v[64:65], v[72:73]
	v_pk_mul_f32 v[38:39], v[38:39], v[106:107]
	v_pk_mul_f32 v[48:49], v[66:67], v[76:77]
	v_pk_mul_f32 v[0:1], v[0:1], v[108:109]
	v_pk_mul_f32 v[44:45], v[44:45], v[52:53]
	v_pk_mul_f32 v[2:3], v[2:3], v[78:79]
	v_pk_mul_f32 v[46:47], v[46:47], v[80:81]
	v_mul_f32_e32 v84, v96, v84
	v_mul_f32_e32 v85, v97, v85
	v_pk_mul_f32 v[36:37], v[36:37], v[70:71]
	v_pk_mul_f32 v[42:43], v[42:43], v[98:99]
	v_pk_mul_f32 v[38:39], v[38:39], v[110:111]
	v_pk_mul_f32 v[48:49], v[48:49], v[54:55]
	v_fma_f32 v0, v50, v118, v0
	v_fma_f32 v44, v51, v119, v44
	v_fma_f32 v2, v82, v120, v2
	v_fma_f32 v46, v83, v121, v46
	v_lshlrev_b32_e32 v113, 16, v87
	v_and_b32_e32 v87, 0xffff0000, v87
	v_lshlrev_b32_e32 v114, 16, v88
	v_and_b32_e32 v88, 0xffff0000, v88
	v_fma_f32 v36, v90, v116, v36
	v_fma_f32 v42, v91, v117, v42
	v_fma_f32 v38, v84, v122, v38
	v_fma_f32 v48, v85, v123, v48
	v_add_f32_e32 v0, v0, v1
	v_add_f32_e32 v1, v44, v45
	v_add_f32_e32 v2, v2, v3
	v_add_f32_e32 v3, v46, v47
	v_lshlrev_b32_e32 v112, 16, v86
	v_and_b32_e32 v86, 0xffff0000, v86
	v_lshlrev_b32_e32 v115, 16, v89
	v_and_b32_e32 v89, 0xffff0000, v89
	v_add_f32_e32 v36, v36, v37
	v_add_f32_e32 v37, v42, v43
	v_add_f32_e32 v38, v38, v39
	v_add_f32_e32 v39, v48, v49
	v_mul_f32_e32 v1, v1, v87
	v_mul_f32_e32 v2, v2, v114
	v_mul_f32_e32 v3, v3, v88
	v_mul_f32_e32 v36, v36, v112
	v_mul_f32_e32 v37, v37, v86
	v_mul_f32_e32 v42, v0, v113
	v_mul_f32_e32 v38, v38, v115
	v_mul_f32_e32 v39, v39, v89
	v_cvt_pk_bf16_f32 v0, v36, v37
	v_cvt_pk_bf16_f32 v1, v42, v1
	v_cvt_pk_bf16_f32 v2, v2, v3
	v_cvt_pk_bf16_f32 v3, v38, v39
	global_store_dwordx4 v[40:41], v[0:3], off offset:1024
	s_cbranch_scc0 .LBB0_239

; #define PG8_STAGE(bufoff, gbase, voff) do { _Pragma("unroll") for (int _i = 0; _i < 2; ++_i) \
;         __builtin_amdgcn_global_load_lds((const unsigned*)((const char*)(gbase) + (voff)[_i]), (LAS unsigned*)(lds + (bufoff) + ldsw + _i * 8192), 16, 0, 0); } while (0)
; #define PG8_LDA(dst, b, h) do { _Pragma("unroll") for (int m = 0; m < 4; ++m) _Pragma("unroll") for (int k = 0; k < 2; ++k) dst[m][k] = *(const LAS bf16x8*)(lds + PG8_SA(b, h) + aoff + m * 2048 + k * 1024); } while (0)
; #define PG8_LDB(dst, b, h) do { _Pragma("unroll") for (int n = 0; n < 2; ++n) _Pragma("unroll") for (int k = 0; k < 2; ++k) dst[n][k] = *(const LAS bf16x8*)(lds + PG8_SB(b, h) + boff + n * 2048 + k * 1024); } while (0)
; #define PG8_MMA(ai, bj, At, Bt) do { __builtin_amdgcn_s_setprio(1); _Pragma("unroll") for (int m = 0; m < 4; ++m) _Pragma("unroll") for (int n = 0; n < 2; ++n) _Pragma("unroll") for (int k = 0; k < 2; ++k) \
;         acc[ai][bj][m][n] = __builtin_amdgcn_mfma_f32_16x16x32_bf16(Bt[n][k], At[m][k], acc[ai][bj][m][n], 0, 0, 0); __builtin_amdgcn_s_setprio(0); } while (0)
; #define PG8_WAIT_V(n) asm volatile("s_waitcnt vmcnt(" #n ")" ::: "memory")
; #define PG8_WAIT_L(n) asm volatile("s_waitcnt lgkmcnt(" #n ")" ::: "memory")
; #define PG8_BAR __builtin_amdgcn_s_barrier()
; #define PG8_SCHED __builtin_amdgcn_sched_barrier(0)
; __device__ __forceinline__ void gemm_phase(LAS unsigned char* lds, const Desc& g, int G, int cidx, int tid) {
;     ...
;             PG8_LDB(B0, 0, 0); PG8_LDB(B1, 0, 1); PG8_SCHED; PG8_LDA(At, 0, 0); PG8_STAGE(PG8_SA(1, 1), a1 + hstepA, voffA);
;             PG8_WAIT_V(8); PG8_WAIT_L(0); PG8_BAR; PG8_MMA(0, 0, At, B0); PG8_MMA(0, 1, At, B1); PG8_BAR; PG8_SCHED;
;             PG8_LDA(At, 0, 1); PG8_STAGE(PG8_SB(0, 0), b2, voffB); PG8_STAGE(PG8_SB(0, 1), b2 + hstepB, voffB); PG8_STAGE(PG8_SA(0, 0), a2, voffA);
;             PG8_WAIT_V(8); PG8_WAIT_L(0); PG8_BAR; PG8_MMA(1, 0, At, B0); PG8_MMA(1, 1, At, B1); PG8_BAR; PG8_SCHED;
.LBB0_310:
	s_add_i32 s72, s40, 2
	s_add_u32 s4, s0, 0x80
	s_addc_u32 s5, s1, 0
	s_add_i32 s73, 0, 0x10000
	s_cmp_eq_u32 s60, s40
	s_cselect_b32 s41, s69, s5
	s_cselect_b32 s40, s68, s4
	v_add_u32_e32 v144, s73, v170
	s_cselect_b32 s43, s71, s75
	s_cselect_b32 s42, s70, s67
	s_add_i32 s4, 0, 0x14000
	ds_read_b128 v[128:131], v144
	ds_read_b128 v[132:135], v144 offset:1024
	ds_read_b128 v[146:149], v144 offset:2048
	ds_read_b128 v[158:161], v144 offset:3072
	v_add_u32_e32 v144, s4, v170
	ds_read_b128 v[162:165], v144
	ds_read_b128 v[166:169], v144 offset:1024
	ds_read_b128 v[174:177], v144 offset:2048
	ds_read_b128 v[178:181], v144 offset:3072
	v_lshl_add_u64 v[218:219], s[0:1], 0, v[156:157]
	s_add_i32 m0, s89, 0xc000
	ds_read_b128 v[182:185], v172
	ds_read_b128 v[186:189], v172 offset:1024
	ds_read_b128 v[190:193], v172 offset:2048
	ds_read_b128 v[194:197], v172 offset:3072
	ds_read_b128 v[198:201], v172 offset:4096
	ds_read_b128 v[206:209], v172 offset:5120
	ds_read_b128 v[210:213], v172 offset:6144
	ds_read_b128 v[214:217], v172 offset:7168
	global_load_lds_dwordx4 v[218:219], off
	v_lshl_add_u64 v[218:219], s[0:1], 0, v[154:155]
	s_add_i32 m0, s89, 0xe000
	s_nop 0
	global_load_lds_dwordx4 v[218:219], off
	s_waitcnt vmcnt(8)
	s_barrier
	s_setprio 1
	s_waitcnt lgkmcnt(0)
	v_mfma_f32_16x16x32_bf16 v[124:127], v[128:131], v[182:185], v[124:127]
	v_mfma_f32_16x16x32_bf16 v[120:123], v[146:149], v[182:185], v[120:123]
	v_mfma_f32_16x16x32_bf16 v[108:111], v[128:131], v[190:193], v[108:111]
	v_mfma_f32_16x16x32_bf16 v[104:107], v[146:149], v[190:193], v[104:107]
	v_mfma_f32_16x16x32_bf16 v[92:95], v[128:131], v[198:201], v[92:95]
	v_mfma_f32_16x16x32_bf16 v[88:91], v[146:149], v[198:201], v[88:91]
	v_mfma_f32_16x16x32_bf16 v[76:79], v[128:131], v[210:213], v[76:79]
	v_mfma_f32_16x16x32_bf16 v[72:75], v[146:149], v[210:213], v[72:75]
	v_mfma_f32_16x16x32_bf16 v[124:127], v[132:135], v[186:189], v[124:127]
	v_mfma_f32_16x16x32_bf16 v[120:123], v[158:161], v[186:189], v[120:123]
	v_mfma_f32_16x16x32_bf16 v[108:111], v[132:135], v[194:197], v[108:111]
	v_mfma_f32_16x16x32_bf16 v[104:107], v[158:161], v[194:197], v[104:107]
	v_mfma_f32_16x16x32_bf16 v[92:95], v[132:135], v[206:209], v[92:95]
	v_mfma_f32_16x16x32_bf16 v[88:91], v[158:161], v[206:209], v[88:91]
	v_mfma_f32_16x16x32_bf16 v[76:79], v[132:135], v[214:217], v[76:79]
	v_mfma_f32_16x16x32_bf16 v[72:75], v[158:161], v[214:217], v[72:75]
	v_mfma_f32_16x16x32_bf16 v[116:119], v[162:165], v[182:185], v[116:119]
	v_mfma_f32_16x16x32_bf16 v[112:115], v[174:177], v[182:185], v[112:115]
	v_mfma_f32_16x16x32_bf16 v[100:103], v[162:165], v[190:193], v[100:103]
	v_mfma_f32_16x16x32_bf16 v[96:99], v[174:177], v[190:193], v[96:99]
	v_mfma_f32_16x16x32_bf16 v[84:87], v[162:165], v[198:201], v[84:87]
	v_mfma_f32_16x16x32_bf16 v[80:83], v[174:177], v[198:201], v[80:83]
	v_mfma_f32_16x16x32_bf16 v[68:71], v[162:165], v[210:213], v[68:71]
	v_mfma_f32_16x16x32_bf16 v[64:67], v[174:177], v[210:213], v[64:67]
	v_mfma_f32_16x16x32_bf16 v[116:119], v[166:169], v[186:189], v[116:119]
	v_mfma_f32_16x16x32_bf16 v[112:115], v[178:181], v[186:189], v[112:115]
	v_mfma_f32_16x16x32_bf16 v[100:103], v[166:169], v[194:197], v[100:103]
	v_mfma_f32_16x16x32_bf16 v[96:99], v[178:181], v[194:197], v[96:99]
	v_mfma_f32_16x16x32_bf16 v[84:87], v[166:169], v[206:209], v[84:87]
	v_mfma_f32_16x16x32_bf16 v[80:83], v[178:181], v[206:209], v[80:83]
	v_mfma_f32_16x16x32_bf16 v[68:71], v[166:169], v[214:217], v[68:71]
	v_mfma_f32_16x16x32_bf16 v[64:67], v[178:181], v[214:217], v[64:67]
	s_setprio 0
	s_barrier
	s_add_i32 s5, s73, s88
	v_lshl_add_u64 v[218:219], s[42:43], 0, v[138:139]
	s_mov_b32 m0, s5
	ds_read_b128 v[182:185], v172 offset:16384
	ds_read_b128 v[186:189], v172 offset:17408
	ds_read_b128 v[190:193], v172 offset:18432
	ds_read_b128 v[194:197], v172 offset:19456
	ds_read_b128 v[198:201], v172 offset:20480
	ds_read_b128 v[206:209], v172 offset:21504
	ds_read_b128 v[210:213], v172 offset:22528
	ds_read_b128 v[214:217], v172 offset:23552
	global_load_lds_dwordx4 v[218:219], off
	s_add_i32 m0, s5, 0x2000
	v_lshl_add_u64 v[220:221], s[42:43], 0, v[142:143]
	s_add_u32 s42, s42, s99
	s_addc_u32 s43, s43, 0
	s_add_i32 s4, s4, s88
	global_load_lds_dwordx4 v[220:221], off
	v_lshl_add_u64 v[222:223], s[42:43], 0, v[138:139]
	s_mov_b32 m0, s4
	v_lshl_add_u64 v[224:225], s[42:43], 0, v[142:143]
	global_load_lds_dwordx4 v[222:223], off
	s_add_i32 m0, s4, 0x2000
	v_lshl_add_u64 v[226:227], s[40:41], 0, v[136:137]
	global_load_lds_dwordx4 v[224:225], off
	s_mov_b32 m0, s89
	v_lshl_add_u64 v[228:229], s[40:41], 0, v[140:141]
	global_load_lds_dwordx4 v[226:227], off
	s_mov_b32 m0, s90
	s_nop 0
	global_load_lds_dwordx4 v[228:229], off
	s_waitcnt vmcnt(8)
	s_barrier
; #define PG8_STAGE(bufoff, gbase, voff) do { _Pragma("unroll") for (int _i = 0; _i < 2; ++_i) \
;         __builtin_amdgcn_global_load_lds((const unsigned*)((const char*)(gbase) + (voff)[_i]), (LAS unsigned*)(lds + (bufoff) + ldsw + _i * 8192), 16, 0, 0); } while (0)
; #define PG8_LDA(dst, b, h) do { _Pragma("unroll") for (int m = 0; m < 4; ++m) _Pragma("unroll") for (int k = 0; k < 2; ++k) dst[m][k] = *(const LAS bf16x8*)(lds + PG8_SA(b, h) + aoff + m * 2048 + k * 1024); } while (0)
; #define PG8_LDB(dst, b, h) do { _Pragma("unroll") for (int n = 0; n < 2; ++n) _Pragma("unroll") for (int k = 0; k < 2; ++k) dst[n][k] = *(const LAS bf16x8*)(lds + PG8_SB(b, h) + boff + n * 2048 + k * 1024); } while (0)
; #define PG8_MMA(ai, bj, At, Bt) do { __builtin_amdgcn_s_setprio(1); _Pragma("unroll") for (int m = 0; m < 4; ++m) _Pragma("unroll") for (int n = 0; n < 2; ++n) _Pragma("unroll") for (int k = 0; k < 2; ++k) \
;         acc[ai][bj][m][n] = __builtin_amdgcn_mfma_f32_16x16x32_bf16(Bt[n][k], At[m][k], acc[ai][bj][m][n], 0, 0, 0); __builtin_amdgcn_s_setprio(0); } while (0)
; #define PG8_WAIT_V(n) asm volatile("s_waitcnt vmcnt(" #n ")" ::: "memory")
; #define PG8_WAIT_L(n) asm volatile("s_waitcnt lgkmcnt(" #n ")" ::: "memory")
; #define PG8_BAR __builtin_amdgcn_s_barrier()
; #define PG8_SCHED __builtin_amdgcn_sched_barrier(0)
; __device__ __forceinline__ void gemm_phase(LAS unsigned char* lds, const Desc& g, int G, int cidx, int tid) {
;     ...
;             PG8_WAIT_V(8); PG8_WAIT_L(0); PG8_BAR; PG8_MMA(1, 0, At, B0); PG8_MMA(1, 1, At, B1); PG8_BAR; PG8_SCHED;
;             PG8_LDB(B0, 1, 0); PG8_LDB(B1, 1, 1); PG8_SCHED; PG8_LDA(At, 1, 0); PG8_STAGE(PG8_SA(0, 1), a2 + hstepA, voffA);
;             PG8_WAIT_V(8); PG8_WAIT_L(0); PG8_BAR; PG8_MMA(0, 0, At, B0); PG8_MMA(0, 1, At, B1); PG8_BAR; PG8_SCHED;
	s_setprio 1
	s_waitcnt lgkmcnt(0)
	v_mfma_f32_16x16x32_bf16 v[60:63], v[128:131], v[182:185], v[60:63]
	v_mfma_f32_16x16x32_bf16 v[56:59], v[146:149], v[182:185], v[56:59]
	v_mfma_f32_16x16x32_bf16 v[44:47], v[128:131], v[190:193], v[44:47]
	v_mfma_f32_16x16x32_bf16 v[40:43], v[146:149], v[190:193], v[40:43]
	v_mfma_f32_16x16x32_bf16 v[28:31], v[128:131], v[198:201], v[28:31]
	v_mfma_f32_16x16x32_bf16 v[24:27], v[146:149], v[198:201], v[24:27]
	v_mfma_f32_16x16x32_bf16 v[12:15], v[128:131], v[210:213], v[12:15]
	v_mfma_f32_16x16x32_bf16 v[8:11], v[146:149], v[210:213], v[8:11]
	v_mfma_f32_16x16x32_bf16 v[60:63], v[132:135], v[186:189], v[60:63]
	v_mfma_f32_16x16x32_bf16 v[56:59], v[158:161], v[186:189], v[56:59]
	v_mfma_f32_16x16x32_bf16 v[44:47], v[132:135], v[194:197], v[44:47]
	v_mfma_f32_16x16x32_bf16 v[40:43], v[158:161], v[194:197], v[40:43]
	v_mfma_f32_16x16x32_bf16 v[28:31], v[132:135], v[206:209], v[28:31]
	v_mfma_f32_16x16x32_bf16 v[24:27], v[158:161], v[206:209], v[24:27]
	v_mfma_f32_16x16x32_bf16 v[12:15], v[132:135], v[214:217], v[12:15]
	v_mfma_f32_16x16x32_bf16 v[8:11], v[158:161], v[214:217], v[8:11]
	v_mfma_f32_16x16x32_bf16 v[52:55], v[162:165], v[182:185], v[52:55]
	v_mfma_f32_16x16x32_bf16 v[48:51], v[174:177], v[182:185], v[48:51]
	v_mfma_f32_16x16x32_bf16 v[36:39], v[162:165], v[190:193], v[36:39]
	v_mfma_f32_16x16x32_bf16 v[32:35], v[174:177], v[190:193], v[32:35]
	v_mfma_f32_16x16x32_bf16 v[20:23], v[162:165], v[198:201], v[20:23]
	v_mfma_f32_16x16x32_bf16 v[16:19], v[174:177], v[198:201], v[16:19]
	v_mfma_f32_16x16x32_bf16 v[0:3], v[162:165], v[210:213], v[0:3]
	v_mfma_f32_16x16x32_bf16 v[4:7], v[174:177], v[210:213], v[4:7]
	v_mfma_f32_16x16x32_bf16 v[52:55], v[166:169], v[186:189], v[52:55]
	v_mfma_f32_16x16x32_bf16 v[48:51], v[178:181], v[186:189], v[48:51]
	v_mfma_f32_16x16x32_bf16 v[36:39], v[166:169], v[194:197], v[36:39]
	v_mfma_f32_16x16x32_bf16 v[32:35], v[178:181], v[194:197], v[32:35]
	v_mfma_f32_16x16x32_bf16 v[20:23], v[166:169], v[206:209], v[20:23]
	v_mfma_f32_16x16x32_bf16 v[16:19], v[178:181], v[206:209], v[16:19]
	v_mfma_f32_16x16x32_bf16 v[0:3], v[166:169], v[214:217], v[0:3]
	v_mfma_f32_16x16x32_bf16 v[4:7], v[178:181], v[214:217], v[4:7]
	s_setprio 0
	s_barrier
	s_add_i32 s4, 0, 0x18000
	v_add_u32_e32 v144, s4, v170
	s_add_i32 s5, 0, 0x1c000
	ds_read_b128 v[128:131], v144
	ds_read_b128 v[132:135], v144 offset:1024
	ds_read_b128 v[146:149], v144 offset:2048
	ds_read_b128 v[158:161], v144 offset:3072
	v_add_u32_e32 v144, s5, v170
	ds_read_b128 v[162:165], v144
	ds_read_b128 v[166:169], v144 offset:1024
	ds_read_b128 v[174:177], v144 offset:2048
	ds_read_b128 v[178:181], v144 offset:3072
	s_add_u32 s40, s40, s2
	s_addc_u32 s41, s41, 0
	s_mov_b32 m0, s91
	v_lshl_add_u64 v[230:231], s[40:41], 0, v[136:137]
	ds_read_b128 v[182:185], v172 offset:32768
	ds_read_b128 v[186:189], v172 offset:33792
	ds_read_b128 v[190:193], v172 offset:34816
	ds_read_b128 v[194:197], v172 offset:35840
	ds_read_b128 v[198:201], v172 offset:36864
	ds_read_b128 v[206:209], v172 offset:37888
	ds_read_b128 v[210:213], v172 offset:38912
	ds_read_b128 v[214:217], v172 offset:39936
	global_load_lds_dwordx4 v[230:231], off
	v_lshl_add_u64 v[230:231], s[40:41], 0, v[140:141]
	s_mov_b32 m0, s92
	s_nop 0
	global_load_lds_dwordx4 v[230:231], off
	s_waitcnt vmcnt(8)
	s_barrier
	s_setprio 1
	s_waitcnt lgkmcnt(0)
	v_mfma_f32_16x16x32_bf16 v[124:127], v[128:131], v[182:185], v[124:127]
	v_mfma_f32_16x16x32_bf16 v[120:123], v[146:149], v[182:185], v[120:123]
	v_mfma_f32_16x16x32_bf16 v[108:111], v[128:131], v[190:193], v[108:111]
	v_mfma_f32_16x16x32_bf16 v[104:107], v[146:149], v[190:193], v[104:107]
	v_mfma_f32_16x16x32_bf16 v[92:95], v[128:131], v[198:201], v[92:95]
	v_mfma_f32_16x16x32_bf16 v[88:91], v[146:149], v[198:201], v[88:91]
	v_mfma_f32_16x16x32_bf16 v[76:79], v[128:131], v[210:213], v[76:79]
	v_mfma_f32_16x16x32_bf16 v[72:75], v[146:149], v[210:213], v[72:75]
	v_mfma_f32_16x16x32_bf16 v[124:127], v[132:135], v[186:189], v[124:127]
	v_mfma_f32_16x16x32_bf16 v[120:123], v[158:161], v[186:189], v[120:123]
	v_mfma_f32_16x16x32_bf16 v[108:111], v[132:135], v[194:197], v[108:111]
	v_mfma_f32_16x16x32_bf16 v[104:107], v[158:161], v[194:197], v[104:107]
	v_mfma_f32_16x16x32_bf16 v[92:95], v[132:135], v[206:209], v[92:95]
	v_mfma_f32_16x16x32_bf16 v[88:91], v[158:161], v[206:209], v[88:91]
	v_mfma_f32_16x16x32_bf16 v[76:79], v[132:135], v[214:217], v[76:79]
	v_mfma_f32_16x16x32_bf16 v[72:75], v[158:161], v[214:217], v[72:75]
	v_mfma_f32_16x16x32_bf16 v[116:119], v[162:165], v[182:185], v[116:119]
	v_mfma_f32_16x16x32_bf16 v[112:115], v[174:177], v[182:185], v[112:115]
	v_mfma_f32_16x16x32_bf16 v[100:103], v[162:165], v[190:193], v[100:103]
	v_mfma_f32_16x16x32_bf16 v[96:99], v[174:177], v[190:193], v[96:99]
	v_mfma_f32_16x16x32_bf16 v[84:87], v[162:165], v[198:201], v[84:87]
	v_mfma_f32_16x16x32_bf16 v[80:83], v[174:177], v[198:201], v[80:83]
	v_mfma_f32_16x16x32_bf16 v[68:71], v[162:165], v[210:213], v[68:71]
	v_mfma_f32_16x16x32_bf16 v[64:67], v[174:177], v[210:213], v[64:67]
	v_mfma_f32_16x16x32_bf16 v[116:119], v[166:169], v[186:189], v[116:119]
	v_mfma_f32_16x16x32_bf16 v[112:115], v[178:181], v[186:189], v[112:115]
	v_mfma_f32_16x16x32_bf16 v[100:103], v[166:169], v[194:197], v[100:103]
	v_mfma_f32_16x16x32_bf16 v[96:99], v[178:181], v[194:197], v[96:99]
	v_mfma_f32_16x16x32_bf16 v[84:87], v[166:169], v[206:209], v[84:87]
	v_mfma_f32_16x16x32_bf16 v[80:83], v[178:181], v[206:209], v[80:83]
	v_mfma_f32_16x16x32_bf16 v[68:71], v[166:169], v[214:217], v[68:71]
	v_mfma_f32_16x16x32_bf16 v[64:67], v[178:181], v[214:217], v[64:67]
	s_setprio 0
	s_barrier
; #define PG8_STAGE(bufoff, gbase, voff) do { _Pragma("unroll") for (int _i = 0; _i < 2; ++_i) \
;         __builtin_amdgcn_global_load_lds((const unsigned*)((const char*)(gbase) + (voff)[_i]), (LAS unsigned*)(lds + (bufoff) + ldsw + _i * 8192), 16, 0, 0); } while (0)
; #define PG8_LDA(dst, b, h) do { _Pragma("unroll") for (int m = 0; m < 4; ++m) _Pragma("unroll") for (int k = 0; k < 2; ++k) dst[m][k] = *(const LAS bf16x8*)(lds + PG8_SA(b, h) + aoff + m * 2048 + k * 1024); } while (0)
; #define PG8_MMA(ai, bj, At, Bt) do { __builtin_amdgcn_s_setprio(1); _Pragma("unroll") for (int m = 0; m < 4; ++m) _Pragma("unroll") for (int n = 0; n < 2; ++n) _Pragma("unroll") for (int k = 0; k < 2; ++k) \
;         acc[ai][bj][m][n] = __builtin_amdgcn_mfma_f32_16x16x32_bf16(Bt[n][k], At[m][k], acc[ai][bj][m][n], 0, 0, 0); __builtin_amdgcn_s_setprio(0); } while (0)
; #define PG8_WAIT_V(n) asm volatile("s_waitcnt vmcnt(" #n ")" ::: "memory")
; #define PG8_WAIT_L(n) asm volatile("s_waitcnt lgkmcnt(" #n ")" ::: "memory")
; #define PG8_BAR __builtin_amdgcn_s_barrier()
; #define PG8_SCHED __builtin_amdgcn_sched_barrier(0)
; __device__ __forceinline__ void gemm_phase(LAS unsigned char* lds, const Desc& g, int G, int cidx, int tid) {
;     ...
;             PG8_LDA(At, 1, 1); PG8_STAGE(PG8_SB(1, 0), b3, voffB); PG8_STAGE(PG8_SB(1, 1), b3 + hstepB, voffB); PG8_STAGE(PG8_SA(1, 0), a3, voffA);
;             PG8_WAIT_V(8); PG8_WAIT_L(0); PG8_BAR; PG8_MMA(1, 0, At, B0); PG8_MMA(1, 1, At, B1); PG8_BAR; PG8_SCHED;
;         }
;         if (wr == 0) PG8_BAR;
	s_add_i32 s4, s4, s88
	v_lshl_add_u64 v[218:219], v[218:219], 0, s[22:23]
	s_mov_b32 m0, s4
	ds_read_b128 v[182:185], v172 offset:49152
	ds_read_b128 v[186:189], v172 offset:50176
	ds_read_b128 v[190:193], v172 offset:51200
	ds_read_b128 v[194:197], v172 offset:52224
	ds_read_b128 v[198:201], v172 offset:53248
	ds_read_b128 v[206:209], v172 offset:54272
	ds_read_b128 v[210:213], v172 offset:55296
	ds_read_b128 v[214:217], v172 offset:56320
	global_load_lds_dwordx4 v[218:219], off
	v_lshl_add_u64 v[218:219], v[220:221], 0, s[22:23]
	s_add_i32 m0, s4, 0x2000
	s_add_i32 s4, s5, s88
	global_load_lds_dwordx4 v[218:219], off
	v_lshl_add_u64 v[218:219], v[222:223], 0, s[22:23]
	s_mov_b32 m0, s4
	s_nop 0
	global_load_lds_dwordx4 v[218:219], off
	v_lshl_add_u64 v[218:219], v[224:225], 0, s[22:23]
	s_add_i32 m0, s4, 0x2000
	s_nop 0
	global_load_lds_dwordx4 v[218:219], off
	v_lshl_add_u64 v[218:219], v[226:227], 0, s[22:23]
	s_mov_b32 m0, s54
	s_nop 0
	global_load_lds_dwordx4 v[218:219], off
	v_lshl_add_u64 v[218:219], v[228:229], 0, s[22:23]
	s_mov_b32 m0, s55
	s_nop 0
	global_load_lds_dwordx4 v[218:219], off
	s_waitcnt vmcnt(8)
	s_barrier
	s_setprio 1
	s_waitcnt lgkmcnt(0)
	v_mfma_f32_16x16x32_bf16 v[60:63], v[128:131], v[182:185], v[60:63]
	v_mfma_f32_16x16x32_bf16 v[56:59], v[146:149], v[182:185], v[56:59]
	v_mfma_f32_16x16x32_bf16 v[44:47], v[128:131], v[190:193], v[44:47]
	v_mfma_f32_16x16x32_bf16 v[40:43], v[146:149], v[190:193], v[40:43]
	v_mfma_f32_16x16x32_bf16 v[28:31], v[128:131], v[198:201], v[28:31]
	v_mfma_f32_16x16x32_bf16 v[24:27], v[146:149], v[198:201], v[24:27]
	v_mfma_f32_16x16x32_bf16 v[12:15], v[128:131], v[210:213], v[12:15]
	v_mfma_f32_16x16x32_bf16 v[8:11], v[146:149], v[210:213], v[8:11]
	v_mfma_f32_16x16x32_bf16 v[60:63], v[132:135], v[186:189], v[60:63]
	v_mfma_f32_16x16x32_bf16 v[56:59], v[158:161], v[186:189], v[56:59]
	v_mfma_f32_16x16x32_bf16 v[44:47], v[132:135], v[194:197], v[44:47]
	v_mfma_f32_16x16x32_bf16 v[40:43], v[158:161], v[194:197], v[40:43]
	v_mfma_f32_16x16x32_bf16 v[28:31], v[132:135], v[206:209], v[28:31]
	v_mfma_f32_16x16x32_bf16 v[24:27], v[158:161], v[206:209], v[24:27]
	v_mfma_f32_16x16x32_bf16 v[12:15], v[132:135], v[214:217], v[12:15]
	v_mfma_f32_16x16x32_bf16 v[8:11], v[158:161], v[214:217], v[8:11]
	v_mfma_f32_16x16x32_bf16 v[52:55], v[162:165], v[182:185], v[52:55]
	v_mfma_f32_16x16x32_bf16 v[48:51], v[174:177], v[182:185], v[48:51]
	v_mfma_f32_16x16x32_bf16 v[36:39], v[162:165], v[190:193], v[36:39]
	v_mfma_f32_16x16x32_bf16 v[32:35], v[174:177], v[190:193], v[32:35]
	v_mfma_f32_16x16x32_bf16 v[20:23], v[162:165], v[198:201], v[20:23]
	v_mfma_f32_16x16x32_bf16 v[16:19], v[174:177], v[198:201], v[16:19]
	v_mfma_f32_16x16x32_bf16 v[0:3], v[162:165], v[210:213], v[0:3]
	v_mfma_f32_16x16x32_bf16 v[4:7], v[174:177], v[210:213], v[4:7]
	v_mfma_f32_16x16x32_bf16 v[52:55], v[166:169], v[186:189], v[52:55]
	v_mfma_f32_16x16x32_bf16 v[48:51], v[178:181], v[186:189], v[48:51]
	v_mfma_f32_16x16x32_bf16 v[36:39], v[166:169], v[194:197], v[36:39]
	v_mfma_f32_16x16x32_bf16 v[32:35], v[178:181], v[194:197], v[32:35]
	v_mfma_f32_16x16x32_bf16 v[20:23], v[166:169], v[206:209], v[20:23]
	v_mfma_f32_16x16x32_bf16 v[16:19], v[178:181], v[206:209], v[16:19]
	v_mfma_f32_16x16x32_bf16 v[0:3], v[166:169], v[214:217], v[0:3]
	v_mfma_f32_16x16x32_bf16 v[4:7], v[178:181], v[214:217], v[4:7]
	s_setprio 0
	s_barrier
	s_add_u32 s67, s67, 0x100
	s_addc_u32 s75, s75, 0
	s_add_u32 s0, s0, 0x100
	s_addc_u32 s1, s1, 0
	s_cmp_ge_u32 s72, s6
	s_mov_b32 s40, s72
	s_cbranch_scc0 .LBB0_310
	s_and_b64 vcc, exec, s[8:9]
	s_cbranch_vccz .LBB0_313
	s_barrier

; __device__ __forceinline__ void epi8(const Desc& d, int pb, int row, int col, f32x4 v0, f32x4 v1) {
;     ...
;     } else {
;         float* hp = (float*)d.o0 + (size_t)row * DM + col;
;         const float* rp = (row < LREAL ? (const float*)d.o2 + (size_t)row * DM : (const float*)d.gate + (size_t)(row - LREAL) * DM) + col;
;         v0 += *(const f32x4*)rp; v1 += *(const f32x4*)(rp + 4);
;         if (d.epi == EPI_RESID) { *(f32x4*)hp = v0; *(f32x4*)(hp + 4) = v1; }
;         else if (row < LREAL) { float* op = (float*)d.o1 + (size_t)row * DM + col; *(f32x4*)op = v0; *(f32x4*)(op + 4) = v1; }
.LBB0_317:
	s_cmp_lt_i32 s26, 2
	s_cbranch_scc1 .LBB0_332
	s_cmp_gt_i32 s26, 4
	s_cbranch_scc0 .LBB0_326
	v_lshl_add_u64 v[128:129], v[162:163], 2, s[86:87]
	v_lshl_add_u64 v[130:131], s[82:83], 0, v[164:165]
	v_ashrrev_i32_e32 v167, 31, v144
	v_mov_b32_e32 v166, v144
	v_cndmask_b32_e64 v129, v131, v129, s[0:1]
	v_cndmask_b32_e64 v128, v130, v128, s[0:1]
	v_lshl_add_u64 v[132:133], v[166:167], 2, v[128:129]
	global_load_dwordx4 v[128:131], v[132:133], off
	global_load_dwordx4 v[132:135], v[132:133], off offset:16
	s_and_b64 vcc, exec, s[64:65]
	s_waitcnt vmcnt(0) lgkmcnt(0)
	v_pk_add_f32 v[130:131], v[126:127], v[130:131]
	v_pk_add_f32 v[128:129], v[124:125], v[128:129]
	v_pk_add_f32 v[134:135], v[122:123], v[134:135]
	v_pk_add_f32 v[132:133], v[120:121], v[132:133]
	s_cbranch_vccz .LBB0_323
	s_and_saveexec_b64 s[74:75], s[0:1]
	s_cbranch_execz .LBB0_322
	v_lshl_add_u64 v[146:147], v[162:163], 2, s[84:85]
	v_lshl_add_u64 v[146:147], v[166:167], 2, v[146:147]
	global_store_dwordx4 v[146:147], v[128:131], off
	global_store_dwordx4 v[146:147], v[132:135], off offset:16

; __device__ __forceinline__ void epi8(const Desc& d, int pb, int row, int col, f32x4 v0, f32x4 v1) {
;     ...
;     } else {
;         float* hp = (float*)d.o0 + (size_t)row * DM + col;
;         const float* rp = (row < LREAL ? (const float*)d.o2 + (size_t)row * DM : (const float*)d.gate + (size_t)(row - LREAL) * DM) + col;
;         v0 += *(const f32x4*)rp; v1 += *(const f32x4*)(rp + 4);
;         if (d.epi == EPI_RESID) { *(f32x4*)hp = v0; *(f32x4*)(hp + 4) = v1; }
;         else if (row < LREAL) { float* op = (float*)d.o1 + (size_t)row * DM + col; *(f32x4*)op = v0; *(f32x4*)(op + 4) = v1; }
.LBB0_344:
	s_cmp_lt_i32 s26, 2
	s_cbranch_scc1 .LBB0_359
	s_cmp_gt_i32 s26, 4
	s_cbranch_scc0 .LBB0_353
	v_lshl_add_u64 v[120:121], v[162:163], 2, s[86:87]
	v_lshl_add_u64 v[122:123], s[82:83], 0, v[164:165]
	v_cndmask_b32_e64 v121, v123, v121, s[0:1]
	v_cndmask_b32_e64 v120, v122, v120, s[0:1]
	v_ashrrev_i32_e32 v133, 31, v144
	v_mov_b32_e32 v132, v144
	v_lshl_add_u64 v[124:125], v[132:133], 2, v[120:121]
	global_load_dwordx4 v[120:123], v[124:125], off offset:512
	global_load_dwordx4 v[124:127], v[124:125], off offset:528
	s_andn2_b64 vcc, exec, s[64:65]
	s_waitcnt vmcnt(0) lgkmcnt(0)
	v_pk_add_f32 v[122:123], v[118:119], v[122:123]
	v_pk_add_f32 v[120:121], v[116:117], v[120:121]
	v_pk_add_f32 v[126:127], v[114:115], v[126:127]
	v_pk_add_f32 v[124:125], v[112:113], v[124:125]
	s_cbranch_vccnz .LBB0_350
	s_and_saveexec_b64 s[74:75], s[0:1]
	s_cbranch_execz .LBB0_349
	v_lshl_add_u64 v[134:135], v[162:163], 2, s[84:85]
	v_lshl_add_u64 v[134:135], v[132:133], 2, v[134:135]
	global_store_dwordx4 v[134:135], v[120:123], off offset:512
	global_store_dwordx4 v[134:135], v[124:127], off offset:528

; __device__ __forceinline__ void epi8(const Desc& d, int pb, int row, int col, f32x4 v0, f32x4 v1) {
;     ...
;     } else {
;         float* hp = (float*)d.o0 + (size_t)row * DM + col;
;         const float* rp = (row < LREAL ? (const float*)d.o2 + (size_t)row * DM : (const float*)d.gate + (size_t)(row - LREAL) * DM) + col;
;         v0 += *(const f32x4*)rp; v1 += *(const f32x4*)(rp + 4);
;         if (d.epi == EPI_RESID) { *(f32x4*)hp = v0; *(f32x4*)(hp + 4) = v1; }
;         else if (row < LREAL) { float* op = (float*)d.o1 + (size_t)row * DM + col; *(f32x4*)op = v0; *(f32x4*)(op + 4) = v1; }
.LBB0_375:
	s_cmp_lt_i32 s26, 2
	s_cbranch_scc1 .LBB0_390
	s_cmp_gt_i32 s26, 4
	s_cbranch_scc0 .LBB0_384
	v_lshl_add_u64 v[112:113], v[124:125], 2, s[86:87]
	v_lshl_add_u64 v[114:115], s[82:83], 0, v[126:127]
	v_ashrrev_i32_e32 v129, 31, v144
	v_mov_b32_e32 v128, v144
	v_cndmask_b32_e64 v113, v115, v113, s[0:1]
	v_cndmask_b32_e64 v112, v114, v112, s[0:1]
	v_lshl_add_u64 v[116:117], v[128:129], 2, v[112:113]
	global_load_dwordx4 v[112:115], v[116:117], off
	global_load_dwordx4 v[116:119], v[116:117], off offset:16
	s_andn2_b64 vcc, exec, s[64:65]
	s_waitcnt vmcnt(0) lgkmcnt(0)
	v_pk_add_f32 v[114:115], v[110:111], v[114:115]
	v_pk_add_f32 v[112:113], v[108:109], v[112:113]
	v_pk_add_f32 v[118:119], v[106:107], v[118:119]
	v_pk_add_f32 v[116:117], v[104:105], v[116:117]
	s_cbranch_vccnz .LBB0_381
	s_and_saveexec_b64 s[74:75], s[0:1]
	s_cbranch_execz .LBB0_380
	v_lshl_add_u64 v[130:131], v[124:125], 2, s[84:85]
	v_lshl_add_u64 v[130:131], v[128:129], 2, v[130:131]
	global_store_dwordx4 v[130:131], v[112:115], off
	global_store_dwordx4 v[130:131], v[116:119], off offset:16

; __device__ __forceinline__ void epi8(const Desc& d, int pb, int row, int col, f32x4 v0, f32x4 v1) {
;     ...
;     } else {
;         float* hp = (float*)d.o0 + (size_t)row * DM + col;
;         const float* rp = (row < LREAL ? (const float*)d.o2 + (size_t)row * DM : (const float*)d.gate + (size_t)(row - LREAL) * DM) + col;
;         v0 += *(const f32x4*)rp; v1 += *(const f32x4*)(rp + 4);
;         if (d.epi == EPI_RESID) { *(f32x4*)hp = v0; *(f32x4*)(hp + 4) = v1; }
;         else if (row < LREAL) { float* op = (float*)d.o1 + (size_t)row * DM + col; *(f32x4*)op = v0; *(f32x4*)(op + 4) = v1; }
.LBB0_402:
	s_cmp_lt_i32 s26, 2
	s_cbranch_scc1 .LBB0_417
	s_cmp_gt_i32 s26, 4
	s_cbranch_scc0 .LBB0_411
	v_lshl_add_u64 v[104:105], v[124:125], 2, s[86:87]
	v_lshl_add_u64 v[106:107], s[82:83], 0, v[126:127]
	v_cndmask_b32_e64 v105, v107, v105, s[0:1]
	v_cndmask_b32_e64 v104, v106, v104, s[0:1]
	v_ashrrev_i32_e32 v117, 31, v144
	v_mov_b32_e32 v116, v144
	v_lshl_add_u64 v[108:109], v[116:117], 2, v[104:105]
	global_load_dwordx4 v[104:107], v[108:109], off offset:512
	global_load_dwordx4 v[108:111], v[108:109], off offset:528
	s_andn2_b64 vcc, exec, s[64:65]
	s_waitcnt vmcnt(0) lgkmcnt(0)
	v_pk_add_f32 v[106:107], v[102:103], v[106:107]
	v_pk_add_f32 v[104:105], v[100:101], v[104:105]
	v_pk_add_f32 v[110:111], v[98:99], v[110:111]
	v_pk_add_f32 v[108:109], v[96:97], v[108:109]
	s_cbranch_vccnz .LBB0_408
	s_and_saveexec_b64 s[74:75], s[0:1]
	s_cbranch_execz .LBB0_407
	v_lshl_add_u64 v[118:119], v[124:125], 2, s[84:85]
	v_lshl_add_u64 v[118:119], v[116:117], 2, v[118:119]
	global_store_dwordx4 v[118:119], v[104:107], off offset:512
	global_store_dwordx4 v[118:119], v[108:111], off offset:528

; __device__ __forceinline__ void epi8(const Desc& d, int pb, int row, int col, f32x4 v0, f32x4 v1) {
;     ...
;     } else {
;         float* hp = (float*)d.o0 + (size_t)row * DM + col;
;         const float* rp = (row < LREAL ? (const float*)d.o2 + (size_t)row * DM : (const float*)d.gate + (size_t)(row - LREAL) * DM) + col;
;         v0 += *(const f32x4*)rp; v1 += *(const f32x4*)(rp + 4);
;         if (d.epi == EPI_RESID) { *(f32x4*)hp = v0; *(f32x4*)(hp + 4) = v1; }
;         else if (row < LREAL) { float* op = (float*)d.o1 + (size_t)row * DM + col; *(f32x4*)op = v0; *(f32x4*)(op + 4) = v1; }
.LBB0_433:
	s_cmp_lt_i32 s26, 2
	s_cbranch_scc1 .LBB0_448
	s_cmp_gt_i32 s26, 4
	s_cbranch_scc0 .LBB0_442
	v_lshl_add_u64 v[96:97], v[108:109], 2, s[86:87]
	v_lshl_add_u64 v[98:99], s[82:83], 0, v[110:111]
	v_ashrrev_i32_e32 v113, 31, v144
	v_mov_b32_e32 v112, v144
	v_cndmask_b32_e64 v97, v99, v97, s[0:1]
	v_cndmask_b32_e64 v96, v98, v96, s[0:1]
	v_lshl_add_u64 v[100:101], v[112:113], 2, v[96:97]
	global_load_dwordx4 v[96:99], v[100:101], off
	global_load_dwordx4 v[100:103], v[100:101], off offset:16
	s_andn2_b64 vcc, exec, s[64:65]
	s_waitcnt vmcnt(0) lgkmcnt(0)
	v_pk_add_f32 v[98:99], v[94:95], v[98:99]
	v_pk_add_f32 v[96:97], v[92:93], v[96:97]
	v_pk_add_f32 v[102:103], v[90:91], v[102:103]
	v_pk_add_f32 v[100:101], v[88:89], v[100:101]
	s_cbranch_vccnz .LBB0_439
	s_and_saveexec_b64 s[74:75], s[0:1]
	s_cbranch_execz .LBB0_438
	v_lshl_add_u64 v[114:115], v[108:109], 2, s[84:85]
	v_lshl_add_u64 v[114:115], v[112:113], 2, v[114:115]
	global_store_dwordx4 v[114:115], v[96:99], off
	global_store_dwordx4 v[114:115], v[100:103], off offset:16

; __device__ __forceinline__ void epi8(const Desc& d, int pb, int row, int col, f32x4 v0, f32x4 v1) {
;     ...
;     } else {
;         float* hp = (float*)d.o0 + (size_t)row * DM + col;
;         const float* rp = (row < LREAL ? (const float*)d.o2 + (size_t)row * DM : (const float*)d.gate + (size_t)(row - LREAL) * DM) + col;
;         v0 += *(const f32x4*)rp; v1 += *(const f32x4*)(rp + 4);
;         if (d.epi == EPI_RESID) { *(f32x4*)hp = v0; *(f32x4*)(hp + 4) = v1; }
;         else if (row < LREAL) { float* op = (float*)d.o1 + (size_t)row * DM + col; *(f32x4*)op = v0; *(f32x4*)(op + 4) = v1; }
.LBB0_460:
	s_cmp_lt_i32 s26, 2
	s_cbranch_scc1 .LBB0_475
	s_cmp_gt_i32 s26, 4
	s_cbranch_scc0 .LBB0_469
	v_lshl_add_u64 v[88:89], v[108:109], 2, s[86:87]
	v_lshl_add_u64 v[90:91], s[82:83], 0, v[110:111]
	v_cndmask_b32_e64 v89, v91, v89, s[0:1]
	v_cndmask_b32_e64 v88, v90, v88, s[0:1]
	v_ashrrev_i32_e32 v101, 31, v144
	v_mov_b32_e32 v100, v144
	v_lshl_add_u64 v[92:93], v[100:101], 2, v[88:89]
	global_load_dwordx4 v[88:91], v[92:93], off offset:512
	global_load_dwordx4 v[92:95], v[92:93], off offset:528
	s_andn2_b64 vcc, exec, s[64:65]
	s_waitcnt vmcnt(0) lgkmcnt(0)
	v_pk_add_f32 v[90:91], v[86:87], v[90:91]
	v_pk_add_f32 v[88:89], v[84:85], v[88:89]
	v_pk_add_f32 v[94:95], v[82:83], v[94:95]
	v_pk_add_f32 v[92:93], v[80:81], v[92:93]
	s_cbranch_vccnz .LBB0_466
	s_and_saveexec_b64 s[74:75], s[0:1]
	s_cbranch_execz .LBB0_465
	v_lshl_add_u64 v[102:103], v[108:109], 2, s[84:85]
	v_lshl_add_u64 v[102:103], v[100:101], 2, v[102:103]
	global_store_dwordx4 v[102:103], v[88:91], off offset:512
	global_store_dwordx4 v[102:103], v[92:95], off offset:528

; __device__ __forceinline__ void epi8(const Desc& d, int pb, int row, int col, f32x4 v0, f32x4 v1) {
;     ...
;     } else {
;         float* hp = (float*)d.o0 + (size_t)row * DM + col;
;         const float* rp = (row < LREAL ? (const float*)d.o2 + (size_t)row * DM : (const float*)d.gate + (size_t)(row - LREAL) * DM) + col;
;         v0 += *(const f32x4*)rp; v1 += *(const f32x4*)(rp + 4);
;         if (d.epi == EPI_RESID) { *(f32x4*)hp = v0; *(f32x4*)(hp + 4) = v1; }
;         else if (row < LREAL) { float* op = (float*)d.o1 + (size_t)row * DM + col; *(f32x4*)op = v0; *(f32x4*)(op + 4) = v1; }
.LBB0_491:
	s_cmp_lt_i32 s26, 2
	s_cbranch_scc1 .LBB0_506
	s_cmp_gt_i32 s26, 4
	s_cbranch_scc0 .LBB0_500
	v_lshl_add_u64 v[80:81], v[92:93], 2, s[86:87]
	v_lshl_add_u64 v[82:83], s[82:83], 0, v[94:95]
	v_ashrrev_i32_e32 v97, 31, v144
	v_mov_b32_e32 v96, v144
	v_cndmask_b32_e64 v81, v83, v81, s[0:1]
	v_cndmask_b32_e64 v80, v82, v80, s[0:1]
	v_lshl_add_u64 v[84:85], v[96:97], 2, v[80:81]
	global_load_dwordx4 v[80:83], v[84:85], off
	global_load_dwordx4 v[84:87], v[84:85], off offset:16
	s_andn2_b64 vcc, exec, s[64:65]
	s_waitcnt vmcnt(0) lgkmcnt(0)
	v_pk_add_f32 v[82:83], v[78:79], v[82:83]
	v_pk_add_f32 v[80:81], v[76:77], v[80:81]
	v_pk_add_f32 v[86:87], v[74:75], v[86:87]
	v_pk_add_f32 v[84:85], v[72:73], v[84:85]
	s_cbranch_vccnz .LBB0_497
	s_and_saveexec_b64 s[74:75], s[0:1]
	s_cbranch_execz .LBB0_496
	v_lshl_add_u64 v[98:99], v[92:93], 2, s[84:85]
	v_lshl_add_u64 v[98:99], v[96:97], 2, v[98:99]
	global_store_dwordx4 v[98:99], v[80:83], off
	global_store_dwordx4 v[98:99], v[84:87], off offset:16

; __device__ __forceinline__ void epi8(const Desc& d, int pb, int row, int col, f32x4 v0, f32x4 v1) {
;     ...
;     } else {
;         float* hp = (float*)d.o0 + (size_t)row * DM + col;
;         const float* rp = (row < LREAL ? (const float*)d.o2 + (size_t)row * DM : (const float*)d.gate + (size_t)(row - LREAL) * DM) + col;
;         v0 += *(const f32x4*)rp; v1 += *(const f32x4*)(rp + 4);
;         if (d.epi == EPI_RESID) { *(f32x4*)hp = v0; *(f32x4*)(hp + 4) = v1; }
;         else if (row < LREAL) { float* op = (float*)d.o1 + (size_t)row * DM + col; *(f32x4*)op = v0; *(f32x4*)(op + 4) = v1; }
.LBB0_518:
	s_cmp_lt_i32 s26, 2
	s_cbranch_scc1 .LBB0_533
	s_cmp_gt_i32 s26, 4
	s_cbranch_scc0 .LBB0_527
	v_lshl_add_u64 v[72:73], v[92:93], 2, s[86:87]
	v_lshl_add_u64 v[74:75], s[82:83], 0, v[94:95]
	v_cndmask_b32_e64 v73, v75, v73, s[0:1]
	v_cndmask_b32_e64 v72, v74, v72, s[0:1]
	v_ashrrev_i32_e32 v85, 31, v144
	v_mov_b32_e32 v84, v144
	v_lshl_add_u64 v[76:77], v[84:85], 2, v[72:73]
	global_load_dwordx4 v[72:75], v[76:77], off offset:512
	global_load_dwordx4 v[76:79], v[76:77], off offset:528
	s_andn2_b64 vcc, exec, s[64:65]
	s_waitcnt vmcnt(0) lgkmcnt(0)
	v_pk_add_f32 v[74:75], v[70:71], v[74:75]
	v_pk_add_f32 v[72:73], v[68:69], v[72:73]
	v_pk_add_f32 v[78:79], v[66:67], v[78:79]
	v_pk_add_f32 v[76:77], v[64:65], v[76:77]
	s_cbranch_vccnz .LBB0_524
	s_and_saveexec_b64 s[74:75], s[0:1]
	s_cbranch_execz .LBB0_523
	v_lshl_add_u64 v[86:87], v[92:93], 2, s[84:85]
	v_lshl_add_u64 v[86:87], v[84:85], 2, v[86:87]
	global_store_dwordx4 v[86:87], v[72:75], off offset:512
	global_store_dwordx4 v[86:87], v[76:79], off offset:528

; __device__ __forceinline__ void epi8(const Desc& d, int pb, int row, int col, f32x4 v0, f32x4 v1) {
;     ...
;     } else {
;         float* hp = (float*)d.o0 + (size_t)row * DM + col;
;         const float* rp = (row < LREAL ? (const float*)d.o2 + (size_t)row * DM : (const float*)d.gate + (size_t)(row - LREAL) * DM) + col;
;         v0 += *(const f32x4*)rp; v1 += *(const f32x4*)(rp + 4);
;         if (d.epi == EPI_RESID) { *(f32x4*)hp = v0; *(f32x4*)(hp + 4) = v1; }
;         else if (row < LREAL) { float* op = (float*)d.o1 + (size_t)row * DM + col; *(f32x4*)op = v0; *(f32x4*)(op + 4) = v1; }
.LBB0_549:
	s_cmp_lt_i32 s26, 2
	s_cbranch_scc1 .LBB0_564
	s_cmp_gt_i32 s26, 4
	s_cbranch_scc0 .LBB0_558
	v_lshl_add_u64 v[64:65], v[76:77], 2, s[86:87]
	v_lshl_add_u64 v[66:67], s[82:83], 0, v[78:79]
	v_ashrrev_i32_e32 v81, 31, v144
	v_mov_b32_e32 v80, v144
	v_cndmask_b32_e64 v65, v67, v65, s[0:1]
	v_cndmask_b32_e64 v64, v66, v64, s[0:1]
	v_lshl_add_u64 v[68:69], v[80:81], 2, v[64:65]
	global_load_dwordx4 v[64:67], v[68:69], off
	global_load_dwordx4 v[68:71], v[68:69], off offset:16
	s_andn2_b64 vcc, exec, s[64:65]
	s_waitcnt vmcnt(0) lgkmcnt(0)
	v_pk_add_f32 v[66:67], v[62:63], v[66:67]
	v_pk_add_f32 v[64:65], v[60:61], v[64:65]
	v_pk_add_f32 v[70:71], v[58:59], v[70:71]
	v_pk_add_f32 v[68:69], v[56:57], v[68:69]
	s_cbranch_vccnz .LBB0_555
	s_and_saveexec_b64 s[74:75], s[0:1]
	s_cbranch_execz .LBB0_554
	v_lshl_add_u64 v[82:83], v[76:77], 2, s[84:85]
	v_lshl_add_u64 v[82:83], v[80:81], 2, v[82:83]
	global_store_dwordx4 v[82:83], v[64:67], off
	global_store_dwordx4 v[82:83], v[68:71], off offset:16

; __device__ __forceinline__ void epi8(const Desc& d, int pb, int row, int col, f32x4 v0, f32x4 v1) {
;     ...
;     } else {
;         float* hp = (float*)d.o0 + (size_t)row * DM + col;
;         const float* rp = (row < LREAL ? (const float*)d.o2 + (size_t)row * DM : (const float*)d.gate + (size_t)(row - LREAL) * DM) + col;
;         v0 += *(const f32x4*)rp; v1 += *(const f32x4*)(rp + 4);
;         if (d.epi == EPI_RESID) { *(f32x4*)hp = v0; *(f32x4*)(hp + 4) = v1; }
;         else if (row < LREAL) { float* op = (float*)d.o1 + (size_t)row * DM + col; *(f32x4*)op = v0; *(f32x4*)(op + 4) = v1; }
.LBB0_576:
	s_cmp_lt_i32 s26, 2
	s_cbranch_scc1 .LBB0_591
	s_cmp_gt_i32 s26, 4
	s_cbranch_scc0 .LBB0_585
	v_lshl_add_u64 v[56:57], v[76:77], 2, s[86:87]
	v_lshl_add_u64 v[58:59], s[82:83], 0, v[78:79]
	v_cndmask_b32_e64 v57, v59, v57, s[0:1]
	v_cndmask_b32_e64 v56, v58, v56, s[0:1]
	v_ashrrev_i32_e32 v69, 31, v144
	v_mov_b32_e32 v68, v144
	v_lshl_add_u64 v[60:61], v[68:69], 2, v[56:57]
	global_load_dwordx4 v[56:59], v[60:61], off offset:512
	global_load_dwordx4 v[60:63], v[60:61], off offset:528
	s_andn2_b64 vcc, exec, s[64:65]
	s_waitcnt vmcnt(0) lgkmcnt(0)
	v_pk_add_f32 v[58:59], v[54:55], v[58:59]
	v_pk_add_f32 v[56:57], v[52:53], v[56:57]
	v_pk_add_f32 v[62:63], v[50:51], v[62:63]
	v_pk_add_f32 v[60:61], v[48:49], v[60:61]
	s_cbranch_vccnz .LBB0_582
	s_and_saveexec_b64 s[74:75], s[0:1]
	s_cbranch_execz .LBB0_581
	v_lshl_add_u64 v[70:71], v[76:77], 2, s[84:85]
	v_lshl_add_u64 v[70:71], v[68:69], 2, v[70:71]
	global_store_dwordx4 v[70:71], v[56:59], off offset:512
	global_store_dwordx4 v[70:71], v[60:63], off offset:528

; __device__ __forceinline__ void epi8(const Desc& d, int pb, int row, int col, f32x4 v0, f32x4 v1) {
;     ...
;     } else {
;         float* hp = (float*)d.o0 + (size_t)row * DM + col;
;         const float* rp = (row < LREAL ? (const float*)d.o2 + (size_t)row * DM : (const float*)d.gate + (size_t)(row - LREAL) * DM) + col;
;         v0 += *(const f32x4*)rp; v1 += *(const f32x4*)(rp + 4);
;         if (d.epi == EPI_RESID) { *(f32x4*)hp = v0; *(f32x4*)(hp + 4) = v1; }
;         else if (row < LREAL) { float* op = (float*)d.o1 + (size_t)row * DM + col; *(f32x4*)op = v0; *(f32x4*)(op + 4) = v1; }
.LBB0_607:
	s_cmp_lt_i32 s26, 2
	s_cbranch_scc1 .LBB0_622
	s_cmp_gt_i32 s26, 4
	s_cbranch_scc0 .LBB0_616
	v_lshl_add_u64 v[48:49], v[60:61], 2, s[86:87]
	v_lshl_add_u64 v[50:51], s[82:83], 0, v[62:63]
	v_ashrrev_i32_e32 v65, 31, v144
	v_mov_b32_e32 v64, v144
	v_cndmask_b32_e64 v49, v51, v49, s[0:1]
	v_cndmask_b32_e64 v48, v50, v48, s[0:1]
	v_lshl_add_u64 v[52:53], v[64:65], 2, v[48:49]
	global_load_dwordx4 v[48:51], v[52:53], off
	global_load_dwordx4 v[52:55], v[52:53], off offset:16
	s_andn2_b64 vcc, exec, s[64:65]
	s_waitcnt vmcnt(0) lgkmcnt(0)
	v_pk_add_f32 v[50:51], v[46:47], v[50:51]
	v_pk_add_f32 v[48:49], v[44:45], v[48:49]
	v_pk_add_f32 v[54:55], v[42:43], v[54:55]
	v_pk_add_f32 v[52:53], v[40:41], v[52:53]
	s_cbranch_vccnz .LBB0_613
	s_and_saveexec_b64 s[74:75], s[0:1]
	s_cbranch_execz .LBB0_612
	v_lshl_add_u64 v[66:67], v[60:61], 2, s[84:85]
	v_lshl_add_u64 v[66:67], v[64:65], 2, v[66:67]
	global_store_dwordx4 v[66:67], v[48:51], off
	global_store_dwordx4 v[66:67], v[52:55], off offset:16

; __device__ __forceinline__ void epi8(const Desc& d, int pb, int row, int col, f32x4 v0, f32x4 v1) {
;     ...
;     } else {
;         float* hp = (float*)d.o0 + (size_t)row * DM + col;
;         const float* rp = (row < LREAL ? (const float*)d.o2 + (size_t)row * DM : (const float*)d.gate + (size_t)(row - LREAL) * DM) + col;
;         v0 += *(const f32x4*)rp; v1 += *(const f32x4*)(rp + 4);
;         if (d.epi == EPI_RESID) { *(f32x4*)hp = v0; *(f32x4*)(hp + 4) = v1; }
;         else if (row < LREAL) { float* op = (float*)d.o1 + (size_t)row * DM + col; *(f32x4*)op = v0; *(f32x4*)(op + 4) = v1; }
.LBB0_634:
	s_cmp_lt_i32 s26, 2
	s_cbranch_scc1 .LBB0_649
	s_cmp_gt_i32 s26, 4
	s_cbranch_scc0 .LBB0_643
	v_lshl_add_u64 v[40:41], v[60:61], 2, s[86:87]
	v_lshl_add_u64 v[42:43], s[82:83], 0, v[62:63]
	v_cndmask_b32_e64 v41, v43, v41, s[0:1]
	v_cndmask_b32_e64 v40, v42, v40, s[0:1]
	v_ashrrev_i32_e32 v53, 31, v144
	v_mov_b32_e32 v52, v144
	v_lshl_add_u64 v[44:45], v[52:53], 2, v[40:41]
	global_load_dwordx4 v[40:43], v[44:45], off offset:512
	global_load_dwordx4 v[44:47], v[44:45], off offset:528
	s_andn2_b64 vcc, exec, s[64:65]
	s_waitcnt vmcnt(0) lgkmcnt(0)
	v_pk_add_f32 v[42:43], v[38:39], v[42:43]
	v_pk_add_f32 v[40:41], v[36:37], v[40:41]
	v_pk_add_f32 v[46:47], v[34:35], v[46:47]
	v_pk_add_f32 v[44:45], v[32:33], v[44:45]
	s_cbranch_vccnz .LBB0_640
	s_and_saveexec_b64 s[74:75], s[0:1]
	s_cbranch_execz .LBB0_639
	v_lshl_add_u64 v[54:55], v[60:61], 2, s[84:85]
	v_lshl_add_u64 v[54:55], v[52:53], 2, v[54:55]
	global_store_dwordx4 v[54:55], v[40:43], off offset:512
	global_store_dwordx4 v[54:55], v[44:47], off offset:528

; __device__ __forceinline__ void epi8(const Desc& d, int pb, int row, int col, f32x4 v0, f32x4 v1) {
;     ...
;     } else {
;         float* hp = (float*)d.o0 + (size_t)row * DM + col;
;         const float* rp = (row < LREAL ? (const float*)d.o2 + (size_t)row * DM : (const float*)d.gate + (size_t)(row - LREAL) * DM) + col;
;         v0 += *(const f32x4*)rp; v1 += *(const f32x4*)(rp + 4);
;         if (d.epi == EPI_RESID) { *(f32x4*)hp = v0; *(f32x4*)(hp + 4) = v1; }
;         else if (row < LREAL) { float* op = (float*)d.o1 + (size_t)row * DM + col; *(f32x4*)op = v0; *(f32x4*)(op + 4) = v1; }
.LBB0_665:
	s_cmp_lt_i32 s26, 2
	s_cbranch_scc1 .LBB0_680
	s_cmp_gt_i32 s26, 4
	s_cbranch_scc0 .LBB0_674
	v_lshl_add_u64 v[32:33], v[44:45], 2, s[86:87]
	v_lshl_add_u64 v[34:35], s[82:83], 0, v[46:47]
	v_ashrrev_i32_e32 v49, 31, v144
	v_mov_b32_e32 v48, v144
	v_cndmask_b32_e64 v33, v35, v33, s[0:1]
	v_cndmask_b32_e64 v32, v34, v32, s[0:1]
	v_lshl_add_u64 v[36:37], v[48:49], 2, v[32:33]
	global_load_dwordx4 v[32:35], v[36:37], off
	global_load_dwordx4 v[36:39], v[36:37], off offset:16
	s_andn2_b64 vcc, exec, s[64:65]
	s_waitcnt vmcnt(0) lgkmcnt(0)
	v_pk_add_f32 v[34:35], v[30:31], v[34:35]
	v_pk_add_f32 v[32:33], v[28:29], v[32:33]
	v_pk_add_f32 v[38:39], v[26:27], v[38:39]
	v_pk_add_f32 v[36:37], v[24:25], v[36:37]
	s_cbranch_vccnz .LBB0_671
	s_and_saveexec_b64 s[74:75], s[0:1]
	s_cbranch_execz .LBB0_670
	v_lshl_add_u64 v[50:51], v[44:45], 2, s[84:85]
	v_lshl_add_u64 v[50:51], v[48:49], 2, v[50:51]
	global_store_dwordx4 v[50:51], v[32:35], off
	global_store_dwordx4 v[50:51], v[36:39], off offset:16

; __device__ __forceinline__ void epi8(const Desc& d, int pb, int row, int col, f32x4 v0, f32x4 v1) {
;     ...
;     } else {
;         float* hp = (float*)d.o0 + (size_t)row * DM + col;
;         const float* rp = (row < LREAL ? (const float*)d.o2 + (size_t)row * DM : (const float*)d.gate + (size_t)(row - LREAL) * DM) + col;
;         v0 += *(const f32x4*)rp; v1 += *(const f32x4*)(rp + 4);
;         if (d.epi == EPI_RESID) { *(f32x4*)hp = v0; *(f32x4*)(hp + 4) = v1; }
;         else if (row < LREAL) { float* op = (float*)d.o1 + (size_t)row * DM + col; *(f32x4*)op = v0; *(f32x4*)(op + 4) = v1; }
.LBB0_692:
	s_cmp_lt_i32 s26, 2
	s_cbranch_scc1 .LBB0_707
	s_cmp_gt_i32 s26, 4
	s_cbranch_scc0 .LBB0_701
	v_lshl_add_u64 v[24:25], v[44:45], 2, s[86:87]
	v_lshl_add_u64 v[26:27], s[82:83], 0, v[46:47]
	v_cndmask_b32_e64 v25, v27, v25, s[0:1]
	v_cndmask_b32_e64 v24, v26, v24, s[0:1]
	v_ashrrev_i32_e32 v37, 31, v144
	v_mov_b32_e32 v36, v144
	v_lshl_add_u64 v[28:29], v[36:37], 2, v[24:25]
	global_load_dwordx4 v[24:27], v[28:29], off offset:512
	global_load_dwordx4 v[28:31], v[28:29], off offset:528
	s_andn2_b64 vcc, exec, s[64:65]
	s_waitcnt vmcnt(0) lgkmcnt(0)
	v_pk_add_f32 v[26:27], v[22:23], v[26:27]
	v_pk_add_f32 v[24:25], v[20:21], v[24:25]
	v_pk_add_f32 v[30:31], v[18:19], v[30:31]
	v_pk_add_f32 v[28:29], v[16:17], v[28:29]
	s_cbranch_vccnz .LBB0_698
	s_and_saveexec_b64 s[74:75], s[0:1]
	s_cbranch_execz .LBB0_697
	v_lshl_add_u64 v[38:39], v[44:45], 2, s[84:85]
	v_lshl_add_u64 v[38:39], v[36:37], 2, v[38:39]
	global_store_dwordx4 v[38:39], v[24:27], off offset:512
	global_store_dwordx4 v[38:39], v[28:31], off offset:528

; __device__ __forceinline__ void epi8(const Desc& d, int pb, int row, int col, f32x4 v0, f32x4 v1) {
;     ...
;     } else {
;         float* hp = (float*)d.o0 + (size_t)row * DM + col;
;         const float* rp = (row < LREAL ? (const float*)d.o2 + (size_t)row * DM : (const float*)d.gate + (size_t)(row - LREAL) * DM) + col;
;         v0 += *(const f32x4*)rp; v1 += *(const f32x4*)(rp + 4);
;         if (d.epi == EPI_RESID) { *(f32x4*)hp = v0; *(f32x4*)(hp + 4) = v1; }
;         else if (row < LREAL) { float* op = (float*)d.o1 + (size_t)row * DM + col; *(f32x4*)op = v0; *(f32x4*)(op + 4) = v1; }
.LBB0_723:
	s_cmp_lt_i32 s26, 2
	s_cbranch_scc1 .LBB0_738
	s_cmp_gt_i32 s26, 4
	s_cbranch_scc0 .LBB0_732
	v_lshl_add_u64 v[16:17], v[28:29], 2, s[86:87]
	v_lshl_add_u64 v[18:19], s[82:83], 0, v[30:31]
	v_ashrrev_i32_e32 v33, 31, v144
	v_mov_b32_e32 v32, v144
	v_cndmask_b32_e64 v17, v19, v17, s[0:1]
	v_cndmask_b32_e64 v16, v18, v16, s[0:1]
	v_lshl_add_u64 v[20:21], v[32:33], 2, v[16:17]
	global_load_dwordx4 v[16:19], v[20:21], off
	global_load_dwordx4 v[20:23], v[20:21], off offset:16
	s_andn2_b64 vcc, exec, s[64:65]
	s_waitcnt vmcnt(0) lgkmcnt(0)
	v_pk_add_f32 v[18:19], v[14:15], v[18:19]
	v_pk_add_f32 v[16:17], v[12:13], v[16:17]
	v_pk_add_f32 v[22:23], v[10:11], v[22:23]
	v_pk_add_f32 v[20:21], v[8:9], v[20:21]
	s_cbranch_vccnz .LBB0_729
	s_and_saveexec_b64 s[74:75], s[0:1]
	s_cbranch_execz .LBB0_728
	v_lshl_add_u64 v[34:35], v[28:29], 2, s[84:85]
	v_lshl_add_u64 v[34:35], v[32:33], 2, v[34:35]
	global_store_dwordx4 v[34:35], v[16:19], off
	global_store_dwordx4 v[34:35], v[20:23], off offset:16

; __device__ __forceinline__ void epi8(const Desc& d, int pb, int row, int col, f32x4 v0, f32x4 v1) {
;     ...
;     } else {
;         float* hp = (float*)d.o0 + (size_t)row * DM + col;
;         const float* rp = (row < LREAL ? (const float*)d.o2 + (size_t)row * DM : (const float*)d.gate + (size_t)(row - LREAL) * DM) + col;
;         v0 += *(const f32x4*)rp; v1 += *(const f32x4*)(rp + 4);
;         if (d.epi == EPI_RESID) { *(f32x4*)hp = v0; *(f32x4*)(hp + 4) = v1; }
;         else if (row < LREAL) { float* op = (float*)d.o1 + (size_t)row * DM + col; *(f32x4*)op = v0; *(f32x4*)(op + 4) = v1; }
.LBB0_750:
	s_cmp_lt_i32 s26, 2
	s_cbranch_scc1 .LBB0_765
	s_cmp_gt_i32 s26, 4
	s_cbranch_scc0 .LBB0_759
	v_lshl_add_u64 v[8:9], v[28:29], 2, s[86:87]
	v_lshl_add_u64 v[10:11], s[82:83], 0, v[30:31]
	v_cndmask_b32_e64 v9, v11, v9, s[0:1]
	v_cndmask_b32_e64 v8, v10, v8, s[0:1]
	v_ashrrev_i32_e32 v21, 31, v144
	v_mov_b32_e32 v20, v144
	v_lshl_add_u64 v[12:13], v[20:21], 2, v[8:9]
	global_load_dwordx4 v[8:11], v[12:13], off offset:512
	global_load_dwordx4 v[12:15], v[12:13], off offset:528
	s_andn2_b64 vcc, exec, s[64:65]
	s_waitcnt vmcnt(0) lgkmcnt(0)
	v_pk_add_f32 v[10:11], v[2:3], v[10:11]
	v_pk_add_f32 v[8:9], v[0:1], v[8:9]
	v_pk_add_f32 v[14:15], v[6:7], v[14:15]
	v_pk_add_f32 v[12:13], v[4:5], v[12:13]
	s_cbranch_vccnz .LBB0_756
	s_and_saveexec_b64 s[74:75], s[0:1]
	s_cbranch_execz .LBB0_755
	v_lshl_add_u64 v[22:23], v[28:29], 2, s[84:85]
	v_lshl_add_u64 v[22:23], v[20:21], 2, v[22:23]
	global_store_dwordx4 v[22:23], v[8:11], off offset:512
	global_store_dwordx4 v[22:23], v[12:15], off offset:528

; __device__ __forceinline__ void epi8(const Desc& d, int pb, int row, int col, f32x4 v0, f32x4 v1) {
;     ...
;     } else {
;         float* hp = (float*)d.o0 + (size_t)row * DM + col;
;         const float* rp = (row < LREAL ? (const float*)d.o2 + (size_t)row * DM : (const float*)d.gate + (size_t)(row - LREAL) * DM) + col;
;         v0 += *(const f32x4*)rp; v1 += *(const f32x4*)(rp + 4);
;         if (d.epi == EPI_RESID) { *(f32x4*)hp = v0; *(f32x4*)(hp + 4) = v1; }
; __device__ __forceinline__ void skinny_phase(LAS unsigned char* lds, const Desc& g, int G, int bx, int wave, int lane) {
;     ...
;         red[(wave * 64 + lane) * 2] = a0; red[(wave * 64 + lane) * 2 + 1] = a1;
;         __syncthreads();
;         if (wave == 0) {
; #pragma unroll
;             for (int w = 1; w < 8; ++w) { a0 += red[(w * 64 + lane) * 2]; a1 += red[(w * 64 + lane) * 2 + 1]; }
;             epi8(g, 0, LREAL + fr, c0 + 8 * fq, a0, a1);
.Lsk_done:
	s_nop 7
	s_andn2_b64 vcc, exec, s[4:5]
	s_nop 1
	ds_write_b128 v9, v[0:3]
	s_nop 2
	ds_write_b128 v9, v[4:7] offset:16
	s_waitcnt lgkmcnt(0)
	s_barrier
	s_cbranch_vccnz .LBB0_821
	ds_read_b128 v[32:35], v44 offset:2048
	ds_read_b128 v[36:39], v44 offset:2064
	v_lshl_add_u32 v144, s6, 5, v8
	s_mov_b64 s[8:9], -1
	s_cmp_lt_i32 s26, 2
	s_waitcnt lgkmcnt(1)
	v_pk_add_f32 v[34:35], v[2:3], v[34:35]
	v_pk_add_f32 v[32:33], v[0:1], v[32:33]
	ds_read_b128 v[0:3], v44 offset:4096
	s_waitcnt lgkmcnt(1)
	v_pk_add_f32 v[6:7], v[6:7], v[38:39]
	v_pk_add_f32 v[4:5], v[4:5], v[36:37]
	s_waitcnt lgkmcnt(0)
	v_pk_add_f32 v[34:35], v[34:35], v[2:3]
	v_pk_add_f32 v[32:33], v[32:33], v[0:1]
	ds_read_b128 v[0:3], v44 offset:4112
	s_waitcnt lgkmcnt(0)
	v_pk_add_f32 v[6:7], v[6:7], v[2:3]
	v_pk_add_f32 v[4:5], v[4:5], v[0:1]
	ds_read_b128 v[0:3], v44 offset:6144
	s_waitcnt lgkmcnt(0)
	v_pk_add_f32 v[34:35], v[34:35], v[2:3]
	v_pk_add_f32 v[32:33], v[32:33], v[0:1]
	ds_read_b128 v[0:3], v44 offset:6160
	s_waitcnt lgkmcnt(0)
	v_pk_add_f32 v[6:7], v[6:7], v[2:3]
	v_pk_add_f32 v[4:5], v[4:5], v[0:1]
	ds_read_b128 v[0:3], v44 offset:8192
	s_waitcnt lgkmcnt(0)
	v_pk_add_f32 v[34:35], v[34:35], v[2:3]
	v_pk_add_f32 v[32:33], v[32:33], v[0:1]
	ds_read_b128 v[0:3], v44 offset:8208
	s_waitcnt lgkmcnt(0)
	v_pk_add_f32 v[6:7], v[6:7], v[2:3]
	v_pk_add_f32 v[4:5], v[4:5], v[0:1]
	ds_read_b128 v[0:3], v44 offset:10240
	s_waitcnt lgkmcnt(0)
	v_pk_add_f32 v[34:35], v[34:35], v[2:3]
	v_pk_add_f32 v[32:33], v[32:33], v[0:1]
	ds_read_b128 v[0:3], v44 offset:10256
	s_waitcnt lgkmcnt(0)
	v_pk_add_f32 v[6:7], v[6:7], v[2:3]
	v_pk_add_f32 v[4:5], v[4:5], v[0:1]
	ds_read_b128 v[0:3], v44 offset:12288
	s_waitcnt lgkmcnt(0)
	v_pk_add_f32 v[34:35], v[34:35], v[2:3]
	v_pk_add_f32 v[32:33], v[32:33], v[0:1]
	ds_read_b128 v[0:3], v44 offset:12304
	s_waitcnt lgkmcnt(0)
	v_pk_add_f32 v[6:7], v[6:7], v[2:3]
	v_pk_add_f32 v[36:37], v[4:5], v[0:1]
	ds_read_b128 v[2:5], v44 offset:14336
	s_waitcnt lgkmcnt(0)
	v_pk_add_f32 v[0:1], v[34:35], v[4:5]
	v_pk_add_f32 v[2:3], v[32:33], v[2:3]
	ds_read_b128 v[32:35], v44 offset:14352
	s_waitcnt lgkmcnt(0)
	v_pk_add_f32 v[4:5], v[6:7], v[34:35]
	v_pk_add_f32 v[6:7], v[36:37], v[32:33]
	s_cbranch_scc1 .LBB0_836
	s_cmp_lt_i32 s26, 5
	s_cbranch_scc1 .LBB0_830
	s_cmp_eq_u32 s26, 5
	s_cbranch_scc0 .LBB0_829
	v_ashrrev_i32_e32 v33, 31, v144
	v_mov_b32_e32 v32, v144
	v_lshlrev_b64 v[40:41], 2, v[32:33]
	v_lshl_add_u64 v[36:37], v[14:15], 0, v[40:41]
	global_load_dwordx4 v[32:35], v[36:37], off offset:16
	global_load_dwordx4 v[36:39], v[36:37], off
	v_lshl_add_u64 v[40:41], v[12:13], 0, v[40:41]
	s_waitcnt vmcnt(0) lgkmcnt(0)
	v_pk_add_f32 v[34:35], v[4:5], v[34:35]
	v_pk_add_f32 v[38:39], v[0:1], v[38:39]
	v_pk_add_f32 v[36:37], v[2:3], v[36:37]
	v_pk_add_f32 v[32:33], v[6:7], v[32:33]
	global_store_dwordx4 v[40:41], v[36:39], off
	global_store_dwordx4 v[40:41], v[32:35], off offset:16

; #define LAS __attribute__((address_space(3)))
; __device__ __forceinline__ void tr_item(const float* __restrict__ W, int K, int N, bf16_t* __restrict__ WT, int dst_row0, int src_col0, int k0, LAS float* scr, int lane) {
;     if (src_col0 >= 0) {
;         const float* wp = W + (size_t)(k0 + (lane >> 5)) * N + src_col0 + (lane & 31);
;         float t[32];
; #pragma unroll
;         for (int i = 0; i < 32; ++i) t[i] = __builtin_nontemporal_load(wp + (size_t)(2 * i) * N);
; #pragma unroll
;         for (int i = 0; i < 32; ++i) scr[(2 * i + (lane >> 5)) * 33 + (lane & 31)] = t[i];
.LBB0_889:
	s_lshl_b32 s44, s18, 5
	s_lshl_b32 s13, s13, 6
	s_and_b64 vcc, exec, s[46:47]
	s_cbranch_vccz .LBB0_891
	v_add_u32_e32 v40, s13, v0
	v_mov_b64_e32 v[38:39], s[2:3]
	v_mad_i64_i32 v[38:39], s[28:29], v40, s17, v[38:39]
	s_mov_b32 s45, s12
	v_lshl_add_u64 v[38:39], s[44:45], 2, v[38:39]
	v_lshlrev_b32_e32 v144, 2, v2
	v_lshl_add_u64 v[38:39], v[38:39], 0, v[144:145]
	v_add_co_u32_e32 v40, vcc, 0x6000, v38
	s_mov_b32 s4, 0xc000
	s_nop 0
	v_addc_co_u32_e32 v41, vcc, 0, v39, vcc
	v_add_co_u32_e32 v42, vcc, s4, v38
	s_mov_b32 s18, 0x12000
	s_nop 0
	v_addc_co_u32_e32 v43, vcc, 0, v39, vcc
	v_add_co_u32_e32 v44, vcc, s18, v38
	s_mov_b32 s18, 0x42000
	s_nop 0
	v_addc_co_u32_e32 v45, vcc, 0, v39, vcc
	v_add_co_u32_e32 v46, vcc, 0x18000, v38
	s_mov_b32 s4, 0x48000
	s_nop 0
	v_addc_co_u32_e32 v47, vcc, 0, v39, vcc
	s_waitcnt vmcnt(0)
	v_add_co_u32_e32 v48, vcc, 0x1e000, v38
	s_nop 1
	v_addc_co_u32_e32 v49, vcc, 0, v39, vcc
	v_add_co_u32_e32 v50, vcc, 0x24000, v38
	s_nop 1
	v_addc_co_u32_e32 v51, vcc, 0, v39, vcc
	v_add_co_u32_e32 v52, vcc, 0x2a000, v38
	s_nop 1
	v_addc_co_u32_e32 v53, vcc, 0, v39, vcc
	global_load_dword v56, v[38:39], off nt
	global_load_dword v57, v[40:41], off nt
	global_load_dword v59, v[42:43], off nt
	global_load_dword v60, v[44:45], off nt
	global_load_dword v61, v[46:47], off nt
	global_load_dword v62, v[48:49], off nt
	global_load_dword v63, v[50:51], off nt
	global_load_dword v64, v[52:53], off nt
	v_add_co_u32_e32 v40, vcc, 0x30000, v38
	s_nop 1
	v_addc_co_u32_e32 v41, vcc, 0, v39, vcc
	v_add_co_u32_e32 v42, vcc, 0x36000, v38
	s_nop 1
	v_addc_co_u32_e32 v43, vcc, 0, v39, vcc
	v_add_co_u32_e32 v44, vcc, 0x3c000, v38
	s_nop 1
	v_addc_co_u32_e32 v45, vcc, 0, v39, vcc
	v_add_co_u32_e32 v46, vcc, s18, v38
	s_mov_b32 s18, 0x84000
	s_nop 0
	v_addc_co_u32_e32 v47, vcc, 0, v39, vcc
	v_add_co_u32_e32 v48, vcc, s4, v38
	s_mov_b32 s4, 0x54000
	s_nop 0
	v_addc_co_u32_e32 v49, vcc, 0, v39, vcc
	v_add_co_u32_e32 v50, vcc, 0x4e000, v38
	s_nop 1
	v_addc_co_u32_e32 v51, vcc, 0, v39, vcc
	v_add_co_u32_e32 v52, vcc, s4, v38
	s_mov_b32 s4, 0x60000
	s_nop 0
	v_addc_co_u32_e32 v53, vcc, 0, v39, vcc
	v_add_co_u32_e32 v54, vcc, 0x5a000, v38
	s_nop 1
	v_addc_co_u32_e32 v55, vcc, 0, v39, vcc
	global_load_dword v65, v[40:41], off nt
	global_load_dword v66, v[42:43], off nt
	global_load_dword v67, v[44:45], off nt
	global_load_dword v68, v[46:47], off nt
	global_load_dword v69, v[48:49], off nt
	global_load_dword v70, v[50:51], off nt
	global_load_dword v71, v[52:53], off nt
	global_load_dword v72, v[54:55], off nt
	v_add_co_u32_e32 v40, vcc, s4, v38
	s_mov_b32 s4, 0x6c000
	s_nop 0
	v_addc_co_u32_e32 v41, vcc, 0, v39, vcc
	v_add_co_u32_e32 v42, vcc, 0x66000, v38
	s_nop 1
	v_addc_co_u32_e32 v43, vcc, 0, v39, vcc
	v_add_co_u32_e32 v44, vcc, s4, v38
	s_mov_b32 s4, 0x78000
	s_nop 0
	v_addc_co_u32_e32 v45, vcc, 0, v39, vcc
	v_add_co_u32_e32 v46, vcc, 0x72000, v38
	s_nop 1
	v_addc_co_u32_e32 v47, vcc, 0, v39, vcc
	v_add_co_u32_e32 v48, vcc, s4, v38
	s_nop 1
	v_addc_co_u32_e32 v49, vcc, 0, v39, vcc
	v_add_co_u32_e32 v50, vcc, 0x7e000, v38
	s_nop 1
	v_addc_co_u32_e32 v51, vcc, 0, v39, vcc
	v_add_co_u32_e32 v52, vcc, s18, v38
	s_nop 1
	v_addc_co_u32_e32 v53, vcc, 0, v39, vcc
	v_add_co_u32_e32 v54, vcc, 0x8a000, v38
	s_nop 1
	v_addc_co_u32_e32 v55, vcc, 0, v39, vcc
	global_load_dword v73, v[40:41], off nt
	global_load_dword v74, v[42:43], off nt
	global_load_dword v75, v[44:45], off nt
	global_load_dword v76, v[46:47], off nt
	global_load_dword v77, v[48:49], off nt
	global_load_dword v78, v[50:51], off nt
	global_load_dword v79, v[52:53], off nt
	global_load_dword v54, v[54:55], off nt
	v_add_co_u32_e32 v40, vcc, 0x90000, v38
	s_nop 1
	v_addc_co_u32_e32 v41, vcc, 0, v39, vcc
	v_add_co_u32_e32 v42, vcc, 0x96000, v38
	s_nop 1
	v_addc_co_u32_e32 v43, vcc, 0, v39, vcc
	v_add_co_u32_e32 v44, vcc, 0x9c000, v38
	s_nop 1
	v_addc_co_u32_e32 v45, vcc, 0, v39, vcc
	v_add_co_u32_e32 v46, vcc, 0xa2000, v38
	s_nop 1
	v_addc_co_u32_e32 v47, vcc, 0, v39, vcc
	v_add_co_u32_e32 v48, vcc, 0xa8000, v38
	s_nop 1
	v_addc_co_u32_e32 v49, vcc, 0, v39, vcc
	v_add_co_u32_e32 v50, vcc, 0xae000, v38
	s_nop 1
	v_addc_co_u32_e32 v51, vcc, 0, v39, vcc
	v_add_co_u32_e32 v52, vcc, 0xb4000, v38
	s_nop 1
	v_addc_co_u32_e32 v53, vcc, 0, v39, vcc
	v_add_co_u32_e32 v38, vcc, 0xba000, v38
	s_nop 1
	v_addc_co_u32_e32 v39, vcc, 0, v39, vcc
	global_load_dword v40, v[40:41], off nt
	global_load_dword v41, v[42:43], off nt
	global_load_dword v42, v[44:45], off nt
	global_load_dword v43, v[46:47], off nt
	global_load_dword v44, v[48:49], off nt
	global_load_dword v45, v[50:51], off nt
	global_load_dword v46, v[52:53], off nt
	global_load_dword v38, v[38:39], off nt
	v_add_u32_e32 v39, 0x400, v6
	s_waitcnt vmcnt(0)
	ds_write2_b32 v6, v56, v57 offset1:66
	s_waitcnt vmcnt(28)
	ds_write2_b32 v6, v59, v60 offset0:132 offset1:198
	s_waitcnt vmcnt(26)
	ds_write2_b32 v39, v61, v62 offset0:8 offset1:74
	s_waitcnt vmcnt(24)
	ds_write2_b32 v39, v63, v64 offset0:140 offset1:206
	v_add_u32_e32 v39, 0x800, v6
	s_waitcnt vmcnt(22)
	ds_write2_b32 v39, v65, v66 offset0:16 offset1:82
	s_waitcnt vmcnt(20)
	ds_write2_b32 v39, v67, v68 offset0:148 offset1:214
	v_add_u32_e32 v39, 0xc00, v6
	s_waitcnt vmcnt(18)
	ds_write2_b32 v39, v69, v70 offset0:24 offset1:90
	s_waitcnt vmcnt(16)
	ds_write2_b32 v39, v71, v72 offset0:156 offset1:222
	v_add_u32_e32 v39, 0x1000, v6
	s_waitcnt vmcnt(14)
	ds_write2_b32 v39, v73, v74 offset0:32 offset1:98
	s_waitcnt vmcnt(12)
	ds_write2_b32 v39, v75, v76 offset0:164 offset1:230
	v_add_u32_e32 v39, 0x1400, v6
	s_waitcnt vmcnt(10)
	ds_write2_b32 v39, v77, v78 offset0:40 offset1:106
	s_waitcnt vmcnt(8)
	ds_write2_b32 v39, v79, v54 offset0:172 offset1:238
	v_add_u32_e32 v39, 0x1800, v6
	s_waitcnt vmcnt(6)
	ds_write2_b32 v39, v40, v41 offset0:48 offset1:114
	s_waitcnt vmcnt(4)
	ds_write2_b32 v39, v42, v43 offset0:180 offset1:246
	v_add_u32_e32 v39, 0x1c00, v6
	s_waitcnt vmcnt(2)
	ds_write2_b32 v39, v44, v45 offset0:56 offset1:122
	s_waitcnt vmcnt(0)
	ds_write2_b32 v39, v46, v38 offset0:188 offset1:254

; #define LAS __attribute__((address_space(3)))
; __device__ __forceinline__ void tr_item(const float* __restrict__ W, int K, int N, bf16_t* __restrict__ WT, int dst_row0, int src_col0, int k0, LAS float* scr, int lane) {
;     if (src_col0 >= 0) {
;         const float* wp = W + (size_t)(k0 + (lane >> 5)) * N + src_col0 + (lane & 31);
;         float t[32];
; #pragma unroll
;         for (int i = 0; i < 32; ++i) t[i] = __builtin_nontemporal_load(wp + (size_t)(2 * i) * N);
; #pragma unroll
;         for (int i = 0; i < 32; ++i) scr[(2 * i + (lane >> 5)) * 33 + (lane & 31)] = t[i];
.LBB0_896:
	s_lshr_b32 s18, s13, 1
	s_and_b32 s18, s18, 0x1c0
	v_add_u32_e32 v38, s18, v0
	s_lshl_b32 s7, s13, 5
	v_ashrrev_i32_e32 v39, 31, v38
	s_and_b32 s7, s7, 0xfe0
	v_lshlrev_b64 v[38:39], 14, v[38:39]
	v_lshl_add_u64 v[38:39], s[8:9], 0, v[38:39]
	s_lshl_b32 s28, s7, 2
	s_mov_b32 s29, s12
	v_lshl_add_u64 v[38:39], v[38:39], 0, s[28:29]
	v_lshlrev_b32_e32 v144, 2, v2
	v_lshl_add_u64 v[38:39], v[38:39], 0, v[144:145]
	s_mov_b32 s4, 0x8000
	v_add_co_u32_e32 v40, vcc, s4, v38
	s_mov_b32 s4, 0x18000
	s_nop 0
	v_addc_co_u32_e32 v41, vcc, 0, v39, vcc
	v_add_co_u32_e32 v42, vcc, s52, v38
	s_mov_b32 s24, 0x80000
	s_nop 0
	v_addc_co_u32_e32 v43, vcc, 0, v39, vcc
	v_add_co_u32_e32 v44, vcc, s4, v38
	s_mov_b32 s4, 0x20000
	s_nop 0
	v_addc_co_u32_e32 v45, vcc, 0, v39, vcc
	v_add_co_u32_e32 v46, vcc, s4, v38
	s_mov_b32 s4, 0x28000
	s_nop 0
	v_addc_co_u32_e32 v47, vcc, 0, v39, vcc
	s_waitcnt vmcnt(0)
	v_add_co_u32_e32 v48, vcc, s4, v38
	s_mov_b32 s4, 0x30000
	s_nop 0
	v_addc_co_u32_e32 v49, vcc, 0, v39, vcc
	v_add_co_u32_e32 v50, vcc, s4, v38
	s_mov_b32 s4, 0x38000
	s_nop 0
	v_addc_co_u32_e32 v51, vcc, 0, v39, vcc
	v_add_co_u32_e32 v52, vcc, s4, v38
	s_mov_b32 s4, 0x40000
	s_nop 0
	v_addc_co_u32_e32 v53, vcc, 0, v39, vcc
	global_load_dword v56, v[38:39], off nt
	global_load_dword v57, v[40:41], off nt
	global_load_dword v59, v[42:43], off nt
	global_load_dword v60, v[44:45], off nt
	global_load_dword v61, v[46:47], off nt
	global_load_dword v62, v[48:49], off nt
	global_load_dword v63, v[50:51], off nt
	global_load_dword v64, v[52:53], off nt
	v_add_co_u32_e32 v40, vcc, s4, v38
	s_mov_b32 s4, 0x48000
	s_nop 0
	v_addc_co_u32_e32 v41, vcc, 0, v39, vcc
	v_add_co_u32_e32 v42, vcc, s4, v38
	s_mov_b32 s4, 0x50000
	s_nop 0
	v_addc_co_u32_e32 v43, vcc, 0, v39, vcc
	v_add_co_u32_e32 v44, vcc, s4, v38
	s_mov_b32 s4, 0x58000
	s_nop 0
	v_addc_co_u32_e32 v45, vcc, 0, v39, vcc
	v_add_co_u32_e32 v46, vcc, s4, v38
	s_mov_b32 s4, 0x60000
	s_nop 0
	v_addc_co_u32_e32 v47, vcc, 0, v39, vcc
	v_add_co_u32_e32 v48, vcc, s4, v38
	s_mov_b32 s4, 0x68000
	s_nop 0
	v_addc_co_u32_e32 v49, vcc, 0, v39, vcc
	v_add_co_u32_e32 v50, vcc, s4, v38
	s_mov_b32 s4, 0x70000
	s_nop 0
	v_addc_co_u32_e32 v51, vcc, 0, v39, vcc
	v_add_co_u32_e32 v52, vcc, s4, v38
	s_mov_b32 s4, 0x78000
	s_nop 0
	v_addc_co_u32_e32 v53, vcc, 0, v39, vcc
	v_add_co_u32_e32 v54, vcc, s4, v38
	s_mov_b32 s4, 0xf8000
	s_nop 0
	v_addc_co_u32_e32 v55, vcc, 0, v39, vcc
	global_load_dword v65, v[40:41], off nt
	global_load_dword v66, v[42:43], off nt
	global_load_dword v67, v[44:45], off nt
	global_load_dword v68, v[46:47], off nt
	global_load_dword v69, v[48:49], off nt
	global_load_dword v70, v[50:51], off nt
	global_load_dword v71, v[52:53], off nt
	global_load_dword v72, v[54:55], off nt
	v_add_co_u32_e32 v40, vcc, s24, v38
	s_mov_b32 s24, 0x88000
	s_nop 0
	v_addc_co_u32_e32 v41, vcc, 0, v39, vcc
	v_add_co_u32_e32 v42, vcc, s24, v38
	s_mov_b32 s24, 0x90000
	s_nop 0
	v_addc_co_u32_e32 v43, vcc, 0, v39, vcc
	v_add_co_u32_e32 v44, vcc, s24, v38
	s_mov_b32 s24, 0x98000
	s_nop 0
	v_addc_co_u32_e32 v45, vcc, 0, v39, vcc
	v_add_co_u32_e32 v46, vcc, s24, v38
	s_mov_b32 s24, 0xa0000
	s_nop 0
	v_addc_co_u32_e32 v47, vcc, 0, v39, vcc
	v_add_co_u32_e32 v48, vcc, s24, v38
	s_mov_b32 s24, 0xa8000
	s_nop 0
	v_addc_co_u32_e32 v49, vcc, 0, v39, vcc
	v_add_co_u32_e32 v50, vcc, s24, v38
	s_mov_b32 s24, 0xb0000
	s_nop 0
	v_addc_co_u32_e32 v51, vcc, 0, v39, vcc
	v_add_co_u32_e32 v52, vcc, s24, v38
	s_mov_b32 s24, 0xb8000
	s_nop 0
	v_addc_co_u32_e32 v53, vcc, 0, v39, vcc
	v_add_co_u32_e32 v54, vcc, s24, v38
	s_mov_b32 s24, 0xc0000
	s_nop 0
	v_addc_co_u32_e32 v55, vcc, 0, v39, vcc
	global_load_dword v73, v[40:41], off nt
	global_load_dword v74, v[42:43], off nt
	global_load_dword v75, v[44:45], off nt
	global_load_dword v76, v[46:47], off nt
	global_load_dword v77, v[48:49], off nt
	global_load_dword v78, v[50:51], off nt
	global_load_dword v79, v[52:53], off nt
	global_load_dword v54, v[54:55], off nt
	v_add_co_u32_e32 v40, vcc, s24, v38
	s_mov_b32 s24, 0xc8000
	s_nop 0
	v_addc_co_u32_e32 v41, vcc, 0, v39, vcc
	v_add_co_u32_e32 v42, vcc, s24, v38
	s_mov_b32 s24, 0xd0000
	s_nop 0
	v_addc_co_u32_e32 v43, vcc, 0, v39, vcc
	v_add_co_u32_e32 v44, vcc, s24, v38
	s_mov_b32 s24, 0xd8000
	s_nop 0
	v_addc_co_u32_e32 v45, vcc, 0, v39, vcc
	v_add_co_u32_e32 v46, vcc, s24, v38
	s_mov_b32 s24, 0xe0000
	s_nop 0
	v_addc_co_u32_e32 v47, vcc, 0, v39, vcc
	v_add_co_u32_e32 v48, vcc, s24, v38
	s_mov_b32 s24, 0xe8000
	s_nop 0
	v_addc_co_u32_e32 v49, vcc, 0, v39, vcc
	v_add_co_u32_e32 v50, vcc, s24, v38
	s_mov_b32 s24, 0xf0000
	s_nop 0
	v_addc_co_u32_e32 v51, vcc, 0, v39, vcc
	v_add_co_u32_e32 v52, vcc, s24, v38
	s_lshl_b32 s28, s18, 1
	s_nop 0
	v_addc_co_u32_e32 v53, vcc, 0, v39, vcc
	v_add_co_u32_e32 v38, vcc, s4, v38
	s_nop 1
	v_addc_co_u32_e32 v39, vcc, 0, v39, vcc
	global_load_dword v40, v[40:41], off nt
	global_load_dword v41, v[42:43], off nt
	global_load_dword v42, v[44:45], off nt
	global_load_dword v43, v[46:47], off nt
	global_load_dword v44, v[48:49], off nt
	global_load_dword v45, v[50:51], off nt
	global_load_dword v46, v[52:53], off nt
	global_load_dword v38, v[38:39], off nt
	v_add_u32_e32 v39, 0x400, v6
	s_waitcnt vmcnt(0)
; #define LAS __attribute__((address_space(3)))
; __device__ __forceinline__ unsigned cvt_pk_bf16(float lo, float hi) { unsigned r; asm volatile("v_cvt_pk_bf16_f32 %0, %1, %2" : "=v"(r) : "v"(lo), "v"(hi)); return r; }
; #define LDS_WAIT() asm volatile("s_waitcnt lgkmcnt(0)" ::: "memory")
; __device__ __forceinline__ void tr_item(const float* __restrict__ W, int K, int N, bf16_t* __restrict__ WT, int dst_row0, int src_col0, int k0, LAS float* scr, int lane) {
;     ...
;         for (int i = 0; i < 32; ++i) scr[(2 * i + (lane >> 5)) * 33 + (lane & 31)] = t[i];
;     } else {
; #pragma unroll 8
;         for (int i = 0; i < 32; ++i) { const int kk = 2 * i + (lane >> 5); scr[kk * 33 + (lane & 31)] = 0.f; }
;     }
;     LDS_WAIT(); asm volatile("" ::: "memory");
;     const int c = lane & 7;
; #pragma unroll
;     for (int j = 0; j < 4; ++j) { const int n = (lane >> 3) + 8 * j; const LAS float* s = scr + (8 * c) * 33 + n;
;         u32x4 o; o.x = cvt_pk_bf16(s[0 * 33], s[1 * 33]); o.y = cvt_pk_bf16(s[2 * 33], s[3 * 33]); o.z = cvt_pk_bf16(s[4 * 33], s[5 * 33]); o.w = cvt_pk_bf16(s[6 * 33], s[7 * 33]);
;         *(u32x4*)(WT + (size_t)(dst_row0 + n) * K + k0 + 8 * c) = o; }
;     LDS_WAIT(); asm volatile("" ::: "memory");
	ds_write2_b32 v6, v56, v57 offset1:66
	ds_write2_b32 v6, v59, v60 offset0:132 offset1:198
	ds_write2_b32 v39, v61, v62 offset0:8 offset1:74
	ds_write2_b32 v39, v63, v64 offset0:140 offset1:206
	v_add_u32_e32 v39, 0x800, v6
	ds_write2_b32 v39, v65, v66 offset0:16 offset1:82
	ds_write2_b32 v39, v67, v68 offset0:148 offset1:214
	v_add_u32_e32 v39, 0xc00, v6
	ds_write2_b32 v39, v69, v70 offset0:24 offset1:90
	ds_write2_b32 v39, v71, v72 offset0:156 offset1:222
	v_add_u32_e32 v39, 0x1000, v6
	ds_write2_b32 v39, v73, v74 offset0:32 offset1:98
	ds_write2_b32 v39, v75, v76 offset0:164 offset1:230
	v_add_u32_e32 v39, 0x1400, v6
	ds_write2_b32 v39, v77, v78 offset0:40 offset1:106
	ds_write2_b32 v39, v79, v54 offset0:172 offset1:238
	v_add_u32_e32 v39, 0x1800, v6
	ds_write2_b32 v39, v40, v41 offset0:48 offset1:114
	ds_write2_b32 v39, v42, v43 offset0:180 offset1:246
	v_add_u32_e32 v39, 0x1c00, v6
	ds_write2_b32 v39, v44, v45 offset0:56 offset1:122
	ds_write2_b32 v39, v46, v38 offset0:188 offset1:254
	s_waitcnt lgkmcnt(0)
	ds_read2_b32 v[56:57], v33 offset1:33
	ds_read2_b32 v[60:61], v33 offset0:66 offset1:99
	ds_read2_b32 v[62:63], v33 offset0:132 offset1:165
	ds_read2_b32 v[64:65], v33 offset0:198 offset1:231
	ds_read2_b32 v[66:67], v33 offset0:8 offset1:41
	ds_read2_b32 v[68:69], v33 offset0:74 offset1:107
	ds_read2_b32 v[70:71], v33 offset0:140 offset1:173
	ds_read2_b32 v[72:73], v33 offset0:206 offset1:239
	s_waitcnt lgkmcnt(7)
	v_cvt_pk_bf16_f32 v38, v56, v57
	s_waitcnt lgkmcnt(6)
	v_cvt_pk_bf16_f32 v39, v60, v61
	s_waitcnt lgkmcnt(5)
	v_cvt_pk_bf16_f32 v40, v62, v63
	s_waitcnt lgkmcnt(4)
	v_cvt_pk_bf16_f32 v41, v64, v65
	v_add_u32_e32 v42, s7, v31
	v_ashrrev_i32_e32 v43, 31, v42
	v_lshl_add_u64 v[44:45], v[12:13], 0, s[28:29]
	v_lshlrev_b64 v[42:43], 10, v[42:43]
	v_lshl_add_u64 v[42:43], v[44:45], 0, v[42:43]
	global_store_dwordx4 v[42:43], v[38:41], off
	s_nop 1
	s_waitcnt lgkmcnt(3)
	s_nop 0
	v_cvt_pk_bf16_f32 v38, v66, v67
	s_waitcnt lgkmcnt(2)
	v_cvt_pk_bf16_f32 v39, v68, v69
	s_waitcnt lgkmcnt(1)
	v_cvt_pk_bf16_f32 v40, v70, v71
	s_waitcnt lgkmcnt(0)
	v_cvt_pk_bf16_f32 v41, v72, v73
	v_add_u32_e32 v42, s7, v35
	v_ashrrev_i32_e32 v43, 31, v42
	v_lshlrev_b64 v[42:43], 10, v[42:43]
	v_lshl_add_u64 v[42:43], v[44:45], 0, v[42:43]
	ds_read2_b32 v[56:57], v33 offset0:16 offset1:49
	ds_read2_b32 v[60:61], v33 offset0:82 offset1:115
	ds_read2_b32 v[62:63], v33 offset0:148 offset1:181
	ds_read2_b32 v[64:65], v33 offset0:214 offset1:247
	ds_read2_b32 v[66:67], v33 offset0:24 offset1:57
	ds_read2_b32 v[68:69], v33 offset0:90 offset1:123
	ds_read2_b32 v[70:71], v33 offset0:156 offset1:189
	ds_read2_b32 v[72:73], v33 offset0:222 offset1:255
	global_store_dwordx4 v[42:43], v[38:41], off
	s_nop 1
	s_waitcnt lgkmcnt(7)
	s_nop 0
	v_cvt_pk_bf16_f32 v38, v56, v57
	s_waitcnt lgkmcnt(6)
	v_cvt_pk_bf16_f32 v39, v60, v61
	s_waitcnt lgkmcnt(5)
	v_cvt_pk_bf16_f32 v40, v62, v63
	s_waitcnt lgkmcnt(4)
	v_cvt_pk_bf16_f32 v41, v64, v65
	v_add_u32_e32 v42, s7, v36
	v_ashrrev_i32_e32 v43, 31, v42
	v_lshlrev_b64 v[42:43], 10, v[42:43]
	v_lshl_add_u64 v[42:43], v[44:45], 0, v[42:43]
	global_store_dwordx4 v[42:43], v[38:41], off
	s_nop 1
	s_waitcnt lgkmcnt(3)
	s_nop 0
	v_cvt_pk_bf16_f32 v38, v66, v67
	s_waitcnt lgkmcnt(2)
	v_cvt_pk_bf16_f32 v39, v68, v69
	s_waitcnt lgkmcnt(1)
	v_cvt_pk_bf16_f32 v40, v70, v71
	s_waitcnt lgkmcnt(0)
	v_cvt_pk_bf16_f32 v41, v72, v73
	v_add_u32_e32 v42, s7, v37
	v_ashrrev_i32_e32 v43, 31, v42
	v_lshlrev_b64 v[42:43], 10, v[42:43]
	v_lshl_add_u64 v[42:43], v[44:45], 0, v[42:43]
	global_store_dwordx4 v[42:43], v[38:41], off
	s_nop 1
	s_waitcnt lgkmcnt(0)
	s_mov_b32 s7, s13
	s_andn2_b64 vcc, exec, s[40:41]
	s_cbranch_vccnz .LBB0_911

; #define LAS __attribute__((address_space(3)))
; __device__ __forceinline__ void tr_item(const float* __restrict__ W, int K, int N, bf16_t* __restrict__ WT, int dst_row0, int src_col0, int k0, LAS float* scr, int lane) {
;     if (src_col0 >= 0) {
;         const float* wp = W + (size_t)(k0 + (lane >> 5)) * N + src_col0 + (lane & 31);
;         float t[32];
; #pragma unroll
;         for (int i = 0; i < 32; ++i) t[i] = __builtin_nontemporal_load(wp + (size_t)(2 * i) * N);
; #pragma unroll
;         for (int i = 0; i < 32; ++i) scr[(2 * i + (lane >> 5)) * 33 + (lane & 31)] = t[i];
.LBB0_901:
	s_and_b32 s18, s7, 0x3c0
	v_add_u32_e32 v38, s18, v0
	s_lshl_b32 s13, s7, 5
	v_ashrrev_i32_e32 v39, 31, v38
	s_and_b32 s13, s13, 0x7e0
	v_lshlrev_b64 v[38:39], 13, v[38:39]
	v_lshl_add_u64 v[38:39], s[14:15], 0, v[38:39]
	s_lshl_b32 s28, s13, 2
	s_mov_b32 s29, s12
	v_lshl_add_u64 v[38:39], v[38:39], 0, s[28:29]
	v_lshlrev_b32_e32 v144, 2, v2
	v_lshl_add_u64 v[38:39], v[38:39], 0, v[144:145]
	s_movk_i32 s4, 0x4000
	v_add_co_u32_e32 v40, vcc, s4, v38
	s_mov_b32 s4, 0x8000
	s_nop 0
	v_addc_co_u32_e32 v41, vcc, 0, v39, vcc
	v_add_co_u32_e32 v42, vcc, s4, v38
	s_mov_b32 s4, 0xc000
	s_nop 0
	v_addc_co_u32_e32 v43, vcc, 0, v39, vcc
	v_add_co_u32_e32 v44, vcc, s4, v38
	s_mov_b32 s4, 0x14000
	s_nop 0
	v_addc_co_u32_e32 v45, vcc, 0, v39, vcc
	v_add_co_u32_e32 v46, vcc, s52, v38
	s_lshl_b32 s28, s18, 1
	s_nop 0
	v_addc_co_u32_e32 v47, vcc, 0, v39, vcc
	s_waitcnt vmcnt(0)
	v_add_co_u32_e32 v48, vcc, s4, v38
	s_mov_b32 s4, 0x18000
	s_nop 0
	v_addc_co_u32_e32 v49, vcc, 0, v39, vcc
	v_add_co_u32_e32 v50, vcc, s4, v38
	s_mov_b32 s4, 0x1c000
	s_nop 0
	v_addc_co_u32_e32 v51, vcc, 0, v39, vcc
	v_add_co_u32_e32 v52, vcc, s4, v38
	s_mov_b32 s4, 0x20000
	s_nop 0
	v_addc_co_u32_e32 v53, vcc, 0, v39, vcc
	global_load_dword v56, v[38:39], off nt
	global_load_dword v57, v[40:41], off nt
	global_load_dword v59, v[42:43], off nt
	global_load_dword v60, v[44:45], off nt
	global_load_dword v61, v[46:47], off nt
	global_load_dword v62, v[48:49], off nt
	global_load_dword v63, v[50:51], off nt
	global_load_dword v64, v[52:53], off nt
	v_add_co_u32_e32 v40, vcc, s4, v38
	s_mov_b32 s4, 0x24000
	s_nop 0
	v_addc_co_u32_e32 v41, vcc, 0, v39, vcc
	v_add_co_u32_e32 v42, vcc, s4, v38
	s_mov_b32 s4, 0x28000
	s_nop 0
	v_addc_co_u32_e32 v43, vcc, 0, v39, vcc
	v_add_co_u32_e32 v44, vcc, s4, v38
	s_mov_b32 s4, 0x2c000
	s_nop 0
	v_addc_co_u32_e32 v45, vcc, 0, v39, vcc
	v_add_co_u32_e32 v46, vcc, s4, v38
	s_mov_b32 s4, 0x30000
	s_nop 0
	v_addc_co_u32_e32 v47, vcc, 0, v39, vcc
	v_add_co_u32_e32 v48, vcc, s4, v38
	s_mov_b32 s4, 0x34000
	s_nop 0
	v_addc_co_u32_e32 v49, vcc, 0, v39, vcc
	v_add_co_u32_e32 v50, vcc, s4, v38
	s_mov_b32 s4, 0x38000
	s_nop 0
	v_addc_co_u32_e32 v51, vcc, 0, v39, vcc
	v_add_co_u32_e32 v52, vcc, s4, v38
	s_mov_b32 s4, 0x3c000
	s_nop 0
	v_addc_co_u32_e32 v53, vcc, 0, v39, vcc
	v_add_co_u32_e32 v54, vcc, s4, v38
	s_mov_b32 s4, 0x40000
	s_nop 0
	v_addc_co_u32_e32 v55, vcc, 0, v39, vcc
	global_load_dword v65, v[40:41], off nt
	global_load_dword v66, v[42:43], off nt
	global_load_dword v67, v[44:45], off nt
	global_load_dword v68, v[46:47], off nt
	global_load_dword v69, v[48:49], off nt
	global_load_dword v70, v[50:51], off nt
	global_load_dword v71, v[52:53], off nt
	global_load_dword v72, v[54:55], off nt
	v_add_co_u32_e32 v40, vcc, s4, v38
	s_mov_b32 s4, 0x44000
	s_nop 0
	v_addc_co_u32_e32 v41, vcc, 0, v39, vcc
	v_add_co_u32_e32 v42, vcc, s4, v38
	s_mov_b32 s4, 0x48000
	s_nop 0
	v_addc_co_u32_e32 v43, vcc, 0, v39, vcc
	v_add_co_u32_e32 v44, vcc, s4, v38
	s_mov_b32 s4, 0x4c000
	s_nop 0
	v_addc_co_u32_e32 v45, vcc, 0, v39, vcc
	v_add_co_u32_e32 v46, vcc, s4, v38
	s_mov_b32 s4, 0x50000
	s_nop 0
	v_addc_co_u32_e32 v47, vcc, 0, v39, vcc
	v_add_co_u32_e32 v48, vcc, s4, v38
	s_mov_b32 s4, 0x54000
	s_nop 0
	v_addc_co_u32_e32 v49, vcc, 0, v39, vcc
	v_add_co_u32_e32 v50, vcc, s4, v38
	s_mov_b32 s4, 0x58000
	s_nop 0
	v_addc_co_u32_e32 v51, vcc, 0, v39, vcc
	v_add_co_u32_e32 v52, vcc, s4, v38
	s_mov_b32 s4, 0x5c000
	s_nop 0
	v_addc_co_u32_e32 v53, vcc, 0, v39, vcc
	v_add_co_u32_e32 v54, vcc, s4, v38
	s_mov_b32 s4, 0x60000
	s_nop 0
	v_addc_co_u32_e32 v55, vcc, 0, v39, vcc
	global_load_dword v73, v[40:41], off nt
	global_load_dword v74, v[42:43], off nt
	global_load_dword v75, v[44:45], off nt
	global_load_dword v76, v[46:47], off nt
	global_load_dword v77, v[48:49], off nt
	global_load_dword v78, v[50:51], off nt
	global_load_dword v79, v[52:53], off nt
	global_load_dword v54, v[54:55], off nt
	v_add_co_u32_e32 v40, vcc, s4, v38
	s_mov_b32 s4, 0x64000
	s_nop 0
	v_addc_co_u32_e32 v41, vcc, 0, v39, vcc
	v_add_co_u32_e32 v42, vcc, s4, v38
	s_mov_b32 s4, 0x68000
	s_nop 0
	v_addc_co_u32_e32 v43, vcc, 0, v39, vcc
	v_add_co_u32_e32 v44, vcc, s4, v38
	s_mov_b32 s4, 0x6c000
	s_nop 0
	v_addc_co_u32_e32 v45, vcc, 0, v39, vcc
	v_add_co_u32_e32 v46, vcc, s4, v38
	s_mov_b32 s4, 0x70000
	s_nop 0
	v_addc_co_u32_e32 v47, vcc, 0, v39, vcc
	v_add_co_u32_e32 v48, vcc, s4, v38
	s_mov_b32 s4, 0x74000
	s_nop 0
	v_addc_co_u32_e32 v49, vcc, 0, v39, vcc
	v_add_co_u32_e32 v50, vcc, s4, v38
	s_mov_b32 s4, 0x78000
	s_nop 0
	v_addc_co_u32_e32 v51, vcc, 0, v39, vcc
	v_add_co_u32_e32 v52, vcc, s4, v38
	s_mov_b32 s4, 0x7c000
	s_nop 0
	v_addc_co_u32_e32 v53, vcc, 0, v39, vcc
	v_add_co_u32_e32 v38, vcc, s4, v38
	s_nop 1
	v_addc_co_u32_e32 v39, vcc, 0, v39, vcc
	global_load_dword v40, v[40:41], off nt
	global_load_dword v41, v[42:43], off nt
	global_load_dword v42, v[44:45], off nt
	global_load_dword v43, v[46:47], off nt
	global_load_dword v44, v[48:49], off nt
	global_load_dword v45, v[50:51], off nt
	global_load_dword v46, v[52:53], off nt
	global_load_dword v38, v[38:39], off nt
	v_add_u32_e32 v39, 0x400, v6
	s_waitcnt vmcnt(0)
; #define LAS __attribute__((address_space(3)))
; __device__ __forceinline__ unsigned cvt_pk_bf16(float lo, float hi) { unsigned r; asm volatile("v_cvt_pk_bf16_f32 %0, %1, %2" : "=v"(r) : "v"(lo), "v"(hi)); return r; }
; #define LDS_WAIT() asm volatile("s_waitcnt lgkmcnt(0)" ::: "memory")
; __device__ __forceinline__ void tr_item(const float* __restrict__ W, int K, int N, bf16_t* __restrict__ WT, int dst_row0, int src_col0, int k0, LAS float* scr, int lane) {
;     ...
;         for (int i = 0; i < 32; ++i) scr[(2 * i + (lane >> 5)) * 33 + (lane & 31)] = t[i];
;     } else {
; #pragma unroll 8
;         for (int i = 0; i < 32; ++i) { const int kk = 2 * i + (lane >> 5); scr[kk * 33 + (lane & 31)] = 0.f; }
;     }
;     LDS_WAIT(); asm volatile("" ::: "memory");
;     const int c = lane & 7;
; #pragma unroll
;     for (int j = 0; j < 4; ++j) { const int n = (lane >> 3) + 8 * j; const LAS float* s = scr + (8 * c) * 33 + n;
;         u32x4 o; o.x = cvt_pk_bf16(s[0 * 33], s[1 * 33]); o.y = cvt_pk_bf16(s[2 * 33], s[3 * 33]); o.z = cvt_pk_bf16(s[4 * 33], s[5 * 33]); o.w = cvt_pk_bf16(s[6 * 33], s[7 * 33]);
;         *(u32x4*)(WT + (size_t)(dst_row0 + n) * K + k0 + 8 * c) = o; }
;     LDS_WAIT(); asm volatile("" ::: "memory");
	ds_write2_b32 v6, v56, v57 offset1:66
	ds_write2_b32 v6, v59, v60 offset0:132 offset1:198
	ds_write2_b32 v39, v61, v62 offset0:8 offset1:74
	ds_write2_b32 v39, v63, v64 offset0:140 offset1:206
	v_add_u32_e32 v39, 0x800, v6
	ds_write2_b32 v39, v65, v66 offset0:16 offset1:82
	ds_write2_b32 v39, v67, v68 offset0:148 offset1:214
	v_add_u32_e32 v39, 0xc00, v6
	ds_write2_b32 v39, v69, v70 offset0:24 offset1:90
	ds_write2_b32 v39, v71, v72 offset0:156 offset1:222
	v_add_u32_e32 v39, 0x1000, v6
	ds_write2_b32 v39, v73, v74 offset0:32 offset1:98
	ds_write2_b32 v39, v75, v76 offset0:164 offset1:230
	v_add_u32_e32 v39, 0x1400, v6
	ds_write2_b32 v39, v77, v78 offset0:40 offset1:106
	ds_write2_b32 v39, v79, v54 offset0:172 offset1:238
	v_add_u32_e32 v39, 0x1800, v6
	ds_write2_b32 v39, v40, v41 offset0:48 offset1:114
	ds_write2_b32 v39, v42, v43 offset0:180 offset1:246
	v_add_u32_e32 v39, 0x1c00, v6
	ds_write2_b32 v39, v44, v45 offset0:56 offset1:122
	ds_write2_b32 v39, v46, v38 offset0:188 offset1:254
	s_waitcnt lgkmcnt(0)
	ds_read2_b32 v[56:57], v33 offset1:33
	ds_read2_b32 v[60:61], v33 offset0:66 offset1:99
	ds_read2_b32 v[62:63], v33 offset0:132 offset1:165
	ds_read2_b32 v[64:65], v33 offset0:198 offset1:231
	ds_read2_b32 v[66:67], v33 offset0:8 offset1:41
	ds_read2_b32 v[68:69], v33 offset0:74 offset1:107
	ds_read2_b32 v[70:71], v33 offset0:140 offset1:173
	ds_read2_b32 v[72:73], v33 offset0:206 offset1:239
	s_waitcnt lgkmcnt(7)
	v_cvt_pk_bf16_f32 v38, v56, v57
	s_waitcnt lgkmcnt(6)
	v_cvt_pk_bf16_f32 v39, v60, v61
	s_waitcnt lgkmcnt(5)
	v_cvt_pk_bf16_f32 v40, v62, v63
	s_waitcnt lgkmcnt(4)
	v_cvt_pk_bf16_f32 v41, v64, v65
	v_add_u32_e32 v42, s13, v31
	v_ashrrev_i32_e32 v43, 31, v42
	v_lshl_add_u64 v[44:45], v[14:15], 0, s[28:29]
	v_lshlrev_b64 v[42:43], 11, v[42:43]
	v_lshl_add_u64 v[42:43], v[44:45], 0, v[42:43]
	global_store_dwordx4 v[42:43], v[38:41], off
	s_nop 1
	s_waitcnt lgkmcnt(3)
	s_nop 0
	v_cvt_pk_bf16_f32 v38, v66, v67
	s_waitcnt lgkmcnt(2)
	v_cvt_pk_bf16_f32 v39, v68, v69
	s_waitcnt lgkmcnt(1)
	v_cvt_pk_bf16_f32 v40, v70, v71
	s_waitcnt lgkmcnt(0)
	v_cvt_pk_bf16_f32 v41, v72, v73
	v_add_u32_e32 v42, s13, v35
	v_ashrrev_i32_e32 v43, 31, v42
	v_lshlrev_b64 v[42:43], 11, v[42:43]
	v_lshl_add_u64 v[42:43], v[44:45], 0, v[42:43]
	ds_read2_b32 v[56:57], v33 offset0:16 offset1:49
	ds_read2_b32 v[60:61], v33 offset0:82 offset1:115
	ds_read2_b32 v[62:63], v33 offset0:148 offset1:181
	ds_read2_b32 v[64:65], v33 offset0:214 offset1:247
	ds_read2_b32 v[66:67], v33 offset0:24 offset1:57
	ds_read2_b32 v[68:69], v33 offset0:90 offset1:123
	ds_read2_b32 v[70:71], v33 offset0:156 offset1:189
	ds_read2_b32 v[72:73], v33 offset0:222 offset1:255
	global_store_dwordx4 v[42:43], v[38:41], off
	s_nop 1
	s_waitcnt lgkmcnt(7)
	s_nop 0
	v_cvt_pk_bf16_f32 v38, v56, v57
	s_waitcnt lgkmcnt(6)
	v_cvt_pk_bf16_f32 v39, v60, v61
	s_waitcnt lgkmcnt(5)
	v_cvt_pk_bf16_f32 v40, v62, v63
	s_waitcnt lgkmcnt(4)
	v_cvt_pk_bf16_f32 v41, v64, v65
	v_add_u32_e32 v42, s13, v36
	v_ashrrev_i32_e32 v43, 31, v42
	v_lshlrev_b64 v[42:43], 11, v[42:43]
	v_lshl_add_u64 v[42:43], v[44:45], 0, v[42:43]
	global_store_dwordx4 v[42:43], v[38:41], off
	s_nop 1
	s_waitcnt lgkmcnt(3)
	s_nop 0
	v_cvt_pk_bf16_f32 v38, v66, v67
	s_waitcnt lgkmcnt(2)
	v_cvt_pk_bf16_f32 v39, v68, v69
	s_waitcnt lgkmcnt(1)
	v_cvt_pk_bf16_f32 v40, v70, v71
	s_waitcnt lgkmcnt(0)
	v_cvt_pk_bf16_f32 v41, v72, v73
	v_add_u32_e32 v42, s13, v37
	v_ashrrev_i32_e32 v43, 31, v42
	v_lshlrev_b64 v[42:43], 11, v[42:43]
	v_lshl_add_u64 v[42:43], v[44:45], 0, v[42:43]
	global_store_dwordx4 v[42:43], v[38:41], off
	s_nop 1
	s_waitcnt lgkmcnt(0)
	s_mov_b32 s13, s7
	s_andn2_b64 vcc, exec, s[40:41]
	s_cbranch_vccnz .LBB0_911

; #define LAS __attribute__((address_space(3)))
; __device__ __forceinline__ void tr_item(const float* __restrict__ W, int K, int N, bf16_t* __restrict__ WT, int dst_row0, int src_col0, int k0, LAS float* scr, int lane) {
;     if (src_col0 >= 0) {
;         const float* wp = W + (size_t)(k0 + (lane >> 5)) * N + src_col0 + (lane & 31);
;         float t[32];
; #pragma unroll
;         for (int i = 0; i < 32; ++i) t[i] = __builtin_nontemporal_load(wp + (size_t)(2 * i) * N);
; #pragma unroll
;         for (int i = 0; i < 32; ++i) scr[(2 * i + (lane >> 5)) * 33 + (lane & 31)] = t[i];
.LBB0_906:
	s_and_b32 s18, s13, 0x7c0
	v_add_u32_e32 v38, s18, v0
	s_lshl_b32 s7, s13, 5
	v_ashrrev_i32_e32 v39, 31, v38
	s_and_b32 s7, s7, 0x7e0
	v_lshlrev_b64 v[38:39], 13, v[38:39]
	v_lshl_add_u64 v[38:39], s[34:35], 0, v[38:39]
	s_lshl_b32 s28, s7, 2
	s_mov_b32 s29, s12
	v_lshl_add_u64 v[38:39], v[38:39], 0, s[28:29]
	v_lshlrev_b32_e32 v144, 2, v2
	v_lshl_add_u64 v[38:39], v[38:39], 0, v[144:145]
	s_movk_i32 s4, 0x4000
	v_add_co_u32_e32 v40, vcc, s4, v38
	s_mov_b32 s4, 0x8000
	s_nop 0
	v_addc_co_u32_e32 v41, vcc, 0, v39, vcc
	v_add_co_u32_e32 v42, vcc, s4, v38
	s_mov_b32 s4, 0xc000
	s_nop 0
	v_addc_co_u32_e32 v43, vcc, 0, v39, vcc
	v_add_co_u32_e32 v44, vcc, s4, v38
	s_mov_b32 s4, 0x14000
	s_nop 0
	v_addc_co_u32_e32 v45, vcc, 0, v39, vcc
	v_add_co_u32_e32 v46, vcc, s52, v38
	s_lshl_b32 s28, s18, 1
	s_nop 0
	v_addc_co_u32_e32 v47, vcc, 0, v39, vcc
	s_waitcnt vmcnt(0)
	v_add_co_u32_e32 v48, vcc, s4, v38
	s_mov_b32 s4, 0x18000
	s_nop 0
	v_addc_co_u32_e32 v49, vcc, 0, v39, vcc
	v_add_co_u32_e32 v50, vcc, s4, v38
	s_mov_b32 s4, 0x1c000
	s_nop 0
	v_addc_co_u32_e32 v51, vcc, 0, v39, vcc
	v_add_co_u32_e32 v52, vcc, s4, v38
	s_mov_b32 s4, 0x20000
	s_nop 0
	v_addc_co_u32_e32 v53, vcc, 0, v39, vcc
	global_load_dword v56, v[38:39], off nt
	global_load_dword v57, v[40:41], off nt
	global_load_dword v59, v[42:43], off nt
	global_load_dword v60, v[44:45], off nt
	global_load_dword v61, v[46:47], off nt
	global_load_dword v62, v[48:49], off nt
	global_load_dword v63, v[50:51], off nt
	global_load_dword v64, v[52:53], off nt
	v_add_co_u32_e32 v40, vcc, s4, v38
	s_mov_b32 s4, 0x24000
	s_nop 0
	v_addc_co_u32_e32 v41, vcc, 0, v39, vcc
	v_add_co_u32_e32 v42, vcc, s4, v38
	s_mov_b32 s4, 0x28000
	s_nop 0
	v_addc_co_u32_e32 v43, vcc, 0, v39, vcc
	v_add_co_u32_e32 v44, vcc, s4, v38
	s_mov_b32 s4, 0x2c000
	s_nop 0
	v_addc_co_u32_e32 v45, vcc, 0, v39, vcc
	v_add_co_u32_e32 v46, vcc, s4, v38
	s_mov_b32 s4, 0x30000
	s_nop 0
	v_addc_co_u32_e32 v47, vcc, 0, v39, vcc
	v_add_co_u32_e32 v48, vcc, s4, v38
	s_mov_b32 s4, 0x34000
	s_nop 0
	v_addc_co_u32_e32 v49, vcc, 0, v39, vcc
	v_add_co_u32_e32 v50, vcc, s4, v38
	s_mov_b32 s4, 0x38000
	s_nop 0
	v_addc_co_u32_e32 v51, vcc, 0, v39, vcc
	v_add_co_u32_e32 v52, vcc, s4, v38
	s_mov_b32 s4, 0x3c000
	s_nop 0
	v_addc_co_u32_e32 v53, vcc, 0, v39, vcc
	v_add_co_u32_e32 v54, vcc, s4, v38
	s_mov_b32 s4, 0x40000
	s_nop 0
	v_addc_co_u32_e32 v55, vcc, 0, v39, vcc
	global_load_dword v65, v[40:41], off nt
	global_load_dword v66, v[42:43], off nt
	global_load_dword v67, v[44:45], off nt
	global_load_dword v68, v[46:47], off nt
	global_load_dword v69, v[48:49], off nt
	global_load_dword v70, v[50:51], off nt
	global_load_dword v71, v[52:53], off nt
	global_load_dword v72, v[54:55], off nt
	v_add_co_u32_e32 v40, vcc, s4, v38
	s_mov_b32 s4, 0x44000
	s_nop 0
	v_addc_co_u32_e32 v41, vcc, 0, v39, vcc
	v_add_co_u32_e32 v42, vcc, s4, v38
	s_mov_b32 s4, 0x48000
	s_nop 0
	v_addc_co_u32_e32 v43, vcc, 0, v39, vcc
	v_add_co_u32_e32 v44, vcc, s4, v38
	s_mov_b32 s4, 0x4c000
	s_nop 0
	v_addc_co_u32_e32 v45, vcc, 0, v39, vcc
	v_add_co_u32_e32 v46, vcc, s4, v38
	s_mov_b32 s4, 0x50000
	s_nop 0
	v_addc_co_u32_e32 v47, vcc, 0, v39, vcc
	v_add_co_u32_e32 v48, vcc, s4, v38
	s_mov_b32 s4, 0x54000
	s_nop 0
	v_addc_co_u32_e32 v49, vcc, 0, v39, vcc
	v_add_co_u32_e32 v50, vcc, s4, v38
	s_mov_b32 s4, 0x58000
	s_nop 0
	v_addc_co_u32_e32 v51, vcc, 0, v39, vcc
	v_add_co_u32_e32 v52, vcc, s4, v38
	s_mov_b32 s4, 0x5c000
	s_nop 0
	v_addc_co_u32_e32 v53, vcc, 0, v39, vcc
	v_add_co_u32_e32 v54, vcc, s4, v38
	s_mov_b32 s4, 0x60000
	s_nop 0
	v_addc_co_u32_e32 v55, vcc, 0, v39, vcc
	global_load_dword v73, v[40:41], off nt
	global_load_dword v74, v[42:43], off nt
	global_load_dword v75, v[44:45], off nt
	global_load_dword v76, v[46:47], off nt
	global_load_dword v77, v[48:49], off nt
	global_load_dword v78, v[50:51], off nt
	global_load_dword v79, v[52:53], off nt
	global_load_dword v54, v[54:55], off nt
	v_add_co_u32_e32 v40, vcc, s4, v38
	s_mov_b32 s4, 0x64000
	s_nop 0
	v_addc_co_u32_e32 v41, vcc, 0, v39, vcc
	v_add_co_u32_e32 v42, vcc, s4, v38
	s_mov_b32 s4, 0x68000
	s_nop 0
	v_addc_co_u32_e32 v43, vcc, 0, v39, vcc
	v_add_co_u32_e32 v44, vcc, s4, v38
	s_mov_b32 s4, 0x6c000
	s_nop 0
	v_addc_co_u32_e32 v45, vcc, 0, v39, vcc
	v_add_co_u32_e32 v46, vcc, s4, v38
	s_mov_b32 s4, 0x70000
	s_nop 0
	v_addc_co_u32_e32 v47, vcc, 0, v39, vcc
	v_add_co_u32_e32 v48, vcc, s4, v38
	s_mov_b32 s4, 0x74000
	s_nop 0
	v_addc_co_u32_e32 v49, vcc, 0, v39, vcc
	v_add_co_u32_e32 v50, vcc, s4, v38
	s_mov_b32 s4, 0x78000
	s_nop 0
	v_addc_co_u32_e32 v51, vcc, 0, v39, vcc
	v_add_co_u32_e32 v52, vcc, s4, v38
	s_mov_b32 s4, 0x7c000
	s_nop 0
	v_addc_co_u32_e32 v53, vcc, 0, v39, vcc
	v_add_co_u32_e32 v38, vcc, s4, v38
	s_nop 1
	v_addc_co_u32_e32 v39, vcc, 0, v39, vcc
	global_load_dword v40, v[40:41], off nt
	global_load_dword v41, v[42:43], off nt
	global_load_dword v42, v[44:45], off nt
	global_load_dword v43, v[46:47], off nt
	global_load_dword v44, v[48:49], off nt
	global_load_dword v45, v[50:51], off nt
	global_load_dword v46, v[52:53], off nt
	global_load_dword v38, v[38:39], off nt
	v_add_u32_e32 v39, 0x400, v6
	s_waitcnt vmcnt(0)
; #define LAS __attribute__((address_space(3)))
; __device__ __forceinline__ unsigned cvt_pk_bf16(float lo, float hi) { unsigned r; asm volatile("v_cvt_pk_bf16_f32 %0, %1, %2" : "=v"(r) : "v"(lo), "v"(hi)); return r; }
; #define LDS_WAIT() asm volatile("s_waitcnt lgkmcnt(0)" ::: "memory")
; __device__ __forceinline__ void tr_item(const float* __restrict__ W, int K, int N, bf16_t* __restrict__ WT, int dst_row0, int src_col0, int k0, LAS float* scr, int lane) {
;     ...
;         for (int i = 0; i < 32; ++i) scr[(2 * i + (lane >> 5)) * 33 + (lane & 31)] = t[i];
;     } else {
; #pragma unroll 8
;         for (int i = 0; i < 32; ++i) { const int kk = 2 * i + (lane >> 5); scr[kk * 33 + (lane & 31)] = 0.f; }
;     }
;     LDS_WAIT(); asm volatile("" ::: "memory");
;     const int c = lane & 7;
; #pragma unroll
;     for (int j = 0; j < 4; ++j) { const int n = (lane >> 3) + 8 * j; const LAS float* s = scr + (8 * c) * 33 + n;
;         u32x4 o; o.x = cvt_pk_bf16(s[0 * 33], s[1 * 33]); o.y = cvt_pk_bf16(s[2 * 33], s[3 * 33]); o.z = cvt_pk_bf16(s[4 * 33], s[5 * 33]); o.w = cvt_pk_bf16(s[6 * 33], s[7 * 33]);
;         *(u32x4*)(WT + (size_t)(dst_row0 + n) * K + k0 + 8 * c) = o; }
;     LDS_WAIT(); asm volatile("" ::: "memory");
	ds_write2_b32 v6, v56, v57 offset1:66
	ds_write2_b32 v6, v59, v60 offset0:132 offset1:198
	ds_write2_b32 v39, v61, v62 offset0:8 offset1:74
	ds_write2_b32 v39, v63, v64 offset0:140 offset1:206
	v_add_u32_e32 v39, 0x800, v6
	ds_write2_b32 v39, v65, v66 offset0:16 offset1:82
	ds_write2_b32 v39, v67, v68 offset0:148 offset1:214
	v_add_u32_e32 v39, 0xc00, v6
	ds_write2_b32 v39, v69, v70 offset0:24 offset1:90
	ds_write2_b32 v39, v71, v72 offset0:156 offset1:222
	v_add_u32_e32 v39, 0x1000, v6
	ds_write2_b32 v39, v73, v74 offset0:32 offset1:98
	ds_write2_b32 v39, v75, v76 offset0:164 offset1:230
	v_add_u32_e32 v39, 0x1400, v6
	ds_write2_b32 v39, v77, v78 offset0:40 offset1:106
	ds_write2_b32 v39, v79, v54 offset0:172 offset1:238
	v_add_u32_e32 v39, 0x1800, v6
	ds_write2_b32 v39, v40, v41 offset0:48 offset1:114
	ds_write2_b32 v39, v42, v43 offset0:180 offset1:246
	v_add_u32_e32 v39, 0x1c00, v6
	ds_write2_b32 v39, v44, v45 offset0:56 offset1:122
	ds_write2_b32 v39, v46, v38 offset0:188 offset1:254
	s_waitcnt lgkmcnt(0)
	ds_read2_b32 v[56:57], v33 offset1:33
	ds_read2_b32 v[60:61], v33 offset0:66 offset1:99
	ds_read2_b32 v[62:63], v33 offset0:132 offset1:165
	ds_read2_b32 v[64:65], v33 offset0:198 offset1:231
	ds_read2_b32 v[66:67], v33 offset0:8 offset1:41
	ds_read2_b32 v[68:69], v33 offset0:74 offset1:107
	ds_read2_b32 v[70:71], v33 offset0:140 offset1:173
	ds_read2_b32 v[72:73], v33 offset0:206 offset1:239
	s_waitcnt lgkmcnt(7)
	v_cvt_pk_bf16_f32 v38, v56, v57
	s_waitcnt lgkmcnt(6)
	v_cvt_pk_bf16_f32 v39, v60, v61
	s_waitcnt lgkmcnt(5)
	v_cvt_pk_bf16_f32 v40, v62, v63
	s_waitcnt lgkmcnt(4)
	v_cvt_pk_bf16_f32 v41, v64, v65
	v_add_u32_e32 v42, s7, v31
	v_ashrrev_i32_e32 v43, 31, v42
	v_lshl_add_u64 v[44:45], v[16:17], 0, s[28:29]
	v_lshlrev_b64 v[42:43], 12, v[42:43]
	v_lshl_add_u64 v[42:43], v[44:45], 0, v[42:43]
	global_store_dwordx4 v[42:43], v[38:41], off
	s_nop 1
	s_waitcnt lgkmcnt(3)
	s_nop 0
	v_cvt_pk_bf16_f32 v38, v66, v67
	s_waitcnt lgkmcnt(2)
	v_cvt_pk_bf16_f32 v39, v68, v69
	s_waitcnt lgkmcnt(1)
	v_cvt_pk_bf16_f32 v40, v70, v71
	s_waitcnt lgkmcnt(0)
	v_cvt_pk_bf16_f32 v41, v72, v73
	v_add_u32_e32 v42, s7, v35
	v_ashrrev_i32_e32 v43, 31, v42
	v_lshlrev_b64 v[42:43], 12, v[42:43]
	v_lshl_add_u64 v[42:43], v[44:45], 0, v[42:43]
	ds_read2_b32 v[56:57], v33 offset0:16 offset1:49
	ds_read2_b32 v[60:61], v33 offset0:82 offset1:115
	ds_read2_b32 v[62:63], v33 offset0:148 offset1:181
	ds_read2_b32 v[64:65], v33 offset0:214 offset1:247
	ds_read2_b32 v[66:67], v33 offset0:24 offset1:57
	ds_read2_b32 v[68:69], v33 offset0:90 offset1:123
	ds_read2_b32 v[70:71], v33 offset0:156 offset1:189
	ds_read2_b32 v[72:73], v33 offset0:222 offset1:255
	global_store_dwordx4 v[42:43], v[38:41], off
	s_nop 1
	s_waitcnt lgkmcnt(7)
	s_nop 0
	v_cvt_pk_bf16_f32 v38, v56, v57
	s_waitcnt lgkmcnt(6)
	v_cvt_pk_bf16_f32 v39, v60, v61
	s_waitcnt lgkmcnt(5)
	v_cvt_pk_bf16_f32 v40, v62, v63
	s_waitcnt lgkmcnt(4)
	v_cvt_pk_bf16_f32 v41, v64, v65
	v_add_u32_e32 v42, s7, v36
	v_ashrrev_i32_e32 v43, 31, v42
	v_lshlrev_b64 v[42:43], 12, v[42:43]
	v_lshl_add_u64 v[42:43], v[44:45], 0, v[42:43]
	global_store_dwordx4 v[42:43], v[38:41], off
	s_nop 1
	s_waitcnt lgkmcnt(3)
	s_nop 0
	v_cvt_pk_bf16_f32 v38, v66, v67
	s_waitcnt lgkmcnt(2)
	v_cvt_pk_bf16_f32 v39, v68, v69
	s_waitcnt lgkmcnt(1)
	v_cvt_pk_bf16_f32 v40, v70, v71
	s_waitcnt lgkmcnt(0)
	v_cvt_pk_bf16_f32 v41, v72, v73
	v_add_u32_e32 v42, s7, v37
	v_ashrrev_i32_e32 v43, 31, v42
	v_lshlrev_b64 v[42:43], 12, v[42:43]
	v_lshl_add_u64 v[42:43], v[44:45], 0, v[42:43]
	global_store_dwordx4 v[42:43], v[38:41], off
	s_nop 1
	s_waitcnt lgkmcnt(0)
	s_mov_b32 s7, s13
	s_andn2_b64 vcc, exec, s[40:41]
	s_cbranch_vccnz .LBB0_911

; #define LAS __attribute__((address_space(3)))
; __device__ __forceinline__ void tr_item(const float* __restrict__ W, int K, int N, bf16_t* __restrict__ WT, int dst_row0, int src_col0, int k0, LAS float* scr, int lane) {
;     if (src_col0 >= 0) {
;         const float* wp = W + (size_t)(k0 + (lane >> 5)) * N + src_col0 + (lane & 31);
;         float t[32];
; #pragma unroll
;         for (int i = 0; i < 32; ++i) t[i] = __builtin_nontemporal_load(wp + (size_t)(2 * i) * N);
; #pragma unroll
;         for (int i = 0; i < 32; ++i) scr[(2 * i + (lane >> 5)) * 33 + (lane & 31)] = t[i];
.LBB0_910:
	s_and_b32 s7, s13, 0xffc0
	v_add_u32_e32 v38, s7, v0
	v_ashrrev_i32_e32 v39, 31, v38
	s_lshl_b32 s13, s13, 5
	v_lshlrev_b64 v[38:39], 13, v[38:39]
	s_and_b32 s40, s13, 0x7fe007e0
	v_lshl_add_u64 v[38:39], s[38:39], 0, v[38:39]
	s_mov_b32 s41, s12
	v_lshl_add_u64 v[38:39], s[40:41], 2, v[38:39]
	v_lshlrev_b32_e32 v144, 2, v2
	v_lshl_add_u64 v[38:39], v[38:39], 0, v[144:145]
	s_movk_i32 s4, 0x4000
	v_add_co_u32_e32 v40, vcc, s4, v38
	s_mov_b32 s4, 0x8000
	s_nop 0
	v_addc_co_u32_e32 v41, vcc, 0, v39, vcc
	v_add_co_u32_e32 v42, vcc, s4, v38
	s_mov_b32 s4, 0xc000
	s_nop 0
	v_addc_co_u32_e32 v43, vcc, 0, v39, vcc
	v_add_co_u32_e32 v44, vcc, s4, v38
	s_mov_b32 s4, 0x14000
	s_nop 0
	v_addc_co_u32_e32 v45, vcc, 0, v39, vcc
	v_add_co_u32_e32 v46, vcc, s52, v38
	s_lshl_b32 s28, s7, 1
	s_nop 0
	v_addc_co_u32_e32 v47, vcc, 0, v39, vcc
	s_waitcnt vmcnt(0)
	v_add_co_u32_e32 v48, vcc, s4, v38
	s_mov_b32 s4, 0x18000
	s_nop 0
	v_addc_co_u32_e32 v49, vcc, 0, v39, vcc
	v_add_co_u32_e32 v50, vcc, s4, v38
	s_mov_b32 s4, 0x1c000
	s_nop 0
	v_addc_co_u32_e32 v51, vcc, 0, v39, vcc
	v_add_co_u32_e32 v52, vcc, s4, v38
	s_mov_b32 s4, 0x20000
	s_nop 0
	v_addc_co_u32_e32 v53, vcc, 0, v39, vcc
	global_load_dword v56, v[38:39], off nt
	global_load_dword v57, v[40:41], off nt
	global_load_dword v59, v[42:43], off nt
	global_load_dword v60, v[44:45], off nt
	global_load_dword v61, v[46:47], off nt
	global_load_dword v62, v[48:49], off nt
	global_load_dword v63, v[50:51], off nt
	global_load_dword v64, v[52:53], off nt
	v_add_co_u32_e32 v40, vcc, s4, v38
	s_mov_b32 s4, 0x24000
	s_nop 0
	v_addc_co_u32_e32 v41, vcc, 0, v39, vcc
	v_add_co_u32_e32 v42, vcc, s4, v38
	s_mov_b32 s4, 0x28000
	s_nop 0
	v_addc_co_u32_e32 v43, vcc, 0, v39, vcc
	v_add_co_u32_e32 v44, vcc, s4, v38
	s_mov_b32 s4, 0x2c000
	s_nop 0
	v_addc_co_u32_e32 v45, vcc, 0, v39, vcc
	v_add_co_u32_e32 v46, vcc, s4, v38
	s_mov_b32 s4, 0x30000
	s_nop 0
	v_addc_co_u32_e32 v47, vcc, 0, v39, vcc
	v_add_co_u32_e32 v48, vcc, s4, v38
	s_mov_b32 s4, 0x34000
	s_nop 0
	v_addc_co_u32_e32 v49, vcc, 0, v39, vcc
	v_add_co_u32_e32 v50, vcc, s4, v38
	s_mov_b32 s4, 0x38000
	s_nop 0
	v_addc_co_u32_e32 v51, vcc, 0, v39, vcc
	v_add_co_u32_e32 v52, vcc, s4, v38
	s_mov_b32 s4, 0x3c000
	s_nop 0
	v_addc_co_u32_e32 v53, vcc, 0, v39, vcc
	v_add_co_u32_e32 v54, vcc, s4, v38
	s_mov_b32 s4, 0x40000
	s_nop 0
	v_addc_co_u32_e32 v55, vcc, 0, v39, vcc
	global_load_dword v65, v[40:41], off nt
	global_load_dword v66, v[42:43], off nt
	global_load_dword v67, v[44:45], off nt
	global_load_dword v68, v[46:47], off nt
	global_load_dword v69, v[48:49], off nt
	global_load_dword v70, v[50:51], off nt
	global_load_dword v71, v[52:53], off nt
	global_load_dword v72, v[54:55], off nt
	v_add_co_u32_e32 v40, vcc, s4, v38
	s_mov_b32 s4, 0x44000
	s_nop 0
	v_addc_co_u32_e32 v41, vcc, 0, v39, vcc
	v_add_co_u32_e32 v42, vcc, s4, v38
	s_mov_b32 s4, 0x48000
	s_nop 0
	v_addc_co_u32_e32 v43, vcc, 0, v39, vcc
	v_add_co_u32_e32 v44, vcc, s4, v38
	s_mov_b32 s4, 0x4c000
	s_nop 0
	v_addc_co_u32_e32 v45, vcc, 0, v39, vcc
	v_add_co_u32_e32 v46, vcc, s4, v38
	s_mov_b32 s4, 0x50000
	s_nop 0
	v_addc_co_u32_e32 v47, vcc, 0, v39, vcc
	v_add_co_u32_e32 v48, vcc, s4, v38
	s_mov_b32 s4, 0x54000
	s_nop 0
	v_addc_co_u32_e32 v49, vcc, 0, v39, vcc
	v_add_co_u32_e32 v50, vcc, s4, v38
	s_mov_b32 s4, 0x58000
	s_nop 0
	v_addc_co_u32_e32 v51, vcc, 0, v39, vcc
	v_add_co_u32_e32 v52, vcc, s4, v38
	s_mov_b32 s4, 0x5c000
	s_nop 0
	v_addc_co_u32_e32 v53, vcc, 0, v39, vcc
	v_add_co_u32_e32 v54, vcc, s4, v38
	s_mov_b32 s4, 0x60000
	s_nop 0
	v_addc_co_u32_e32 v55, vcc, 0, v39, vcc
	global_load_dword v73, v[40:41], off nt
	global_load_dword v74, v[42:43], off nt
	global_load_dword v75, v[44:45], off nt
	global_load_dword v76, v[46:47], off nt
	global_load_dword v77, v[48:49], off nt
	global_load_dword v78, v[50:51], off nt
	global_load_dword v79, v[52:53], off nt
	global_load_dword v54, v[54:55], off nt
	v_add_co_u32_e32 v40, vcc, s4, v38
	s_mov_b32 s4, 0x64000
	s_nop 0
	v_addc_co_u32_e32 v41, vcc, 0, v39, vcc
	v_add_co_u32_e32 v42, vcc, s4, v38
	s_mov_b32 s4, 0x68000
	s_nop 0
	v_addc_co_u32_e32 v43, vcc, 0, v39, vcc
	v_add_co_u32_e32 v44, vcc, s4, v38
	s_mov_b32 s4, 0x6c000
	s_nop 0
	v_addc_co_u32_e32 v45, vcc, 0, v39, vcc
	v_add_co_u32_e32 v46, vcc, s4, v38
	s_mov_b32 s4, 0x70000
	s_nop 0
	v_addc_co_u32_e32 v47, vcc, 0, v39, vcc
	v_add_co_u32_e32 v48, vcc, s4, v38
	s_mov_b32 s4, 0x74000
	s_nop 0
	v_addc_co_u32_e32 v49, vcc, 0, v39, vcc
	v_add_co_u32_e32 v50, vcc, s4, v38
	s_mov_b32 s4, 0x78000
	s_nop 0
	v_addc_co_u32_e32 v51, vcc, 0, v39, vcc
	v_add_co_u32_e32 v52, vcc, s4, v38
	s_mov_b32 s4, 0x7c000
	s_nop 0
	v_addc_co_u32_e32 v53, vcc, 0, v39, vcc
	v_add_co_u32_e32 v38, vcc, s4, v38
	s_mov_b32 s29, s12
	s_nop 0
	v_addc_co_u32_e32 v39, vcc, 0, v39, vcc
	global_load_dword v40, v[40:41], off nt
	global_load_dword v41, v[42:43], off nt
	global_load_dword v42, v[44:45], off nt
	global_load_dword v43, v[46:47], off nt
	global_load_dword v44, v[48:49], off nt
	global_load_dword v45, v[50:51], off nt
	global_load_dword v46, v[52:53], off nt
	global_load_dword v38, v[38:39], off nt
	v_add_u32_e32 v39, 0x400, v6
	s_waitcnt vmcnt(0)
; #define LAS __attribute__((address_space(3)))
; __device__ __forceinline__ unsigned cvt_pk_bf16(float lo, float hi) { unsigned r; asm volatile("v_cvt_pk_bf16_f32 %0, %1, %2" : "=v"(r) : "v"(lo), "v"(hi)); return r; }
; #define LDS_WAIT() asm volatile("s_waitcnt lgkmcnt(0)" ::: "memory")
; __device__ __forceinline__ void tr_item(const float* __restrict__ W, int K, int N, bf16_t* __restrict__ WT, int dst_row0, int src_col0, int k0, LAS float* scr, int lane) {
;     ...
;         for (int i = 0; i < 32; ++i) scr[(2 * i + (lane >> 5)) * 33 + (lane & 31)] = t[i];
;     } else {
; #pragma unroll 8
;         for (int i = 0; i < 32; ++i) { const int kk = 2 * i + (lane >> 5); scr[kk * 33 + (lane & 31)] = 0.f; }
;     }
;     LDS_WAIT(); asm volatile("" ::: "memory");
;     const int c = lane & 7;
; #pragma unroll
;     for (int j = 0; j < 4; ++j) { const int n = (lane >> 3) + 8 * j; const LAS float* s = scr + (8 * c) * 33 + n;
;         u32x4 o; o.x = cvt_pk_bf16(s[0 * 33], s[1 * 33]); o.y = cvt_pk_bf16(s[2 * 33], s[3 * 33]); o.z = cvt_pk_bf16(s[4 * 33], s[5 * 33]); o.w = cvt_pk_bf16(s[6 * 33], s[7 * 33]);
;         *(u32x4*)(WT + (size_t)(dst_row0 + n) * K + k0 + 8 * c) = o; }
;     LDS_WAIT(); asm volatile("" ::: "memory");
	ds_write2_b32 v6, v56, v57 offset1:66
	ds_write2_b32 v6, v59, v60 offset0:132 offset1:198
	ds_write2_b32 v39, v61, v62 offset0:8 offset1:74
	ds_write2_b32 v39, v63, v64 offset0:140 offset1:206
	v_add_u32_e32 v39, 0x800, v6
	ds_write2_b32 v39, v65, v66 offset0:16 offset1:82
	ds_write2_b32 v39, v67, v68 offset0:148 offset1:214
	v_add_u32_e32 v39, 0xc00, v6
	ds_write2_b32 v39, v69, v70 offset0:24 offset1:90
	ds_write2_b32 v39, v71, v72 offset0:156 offset1:222
	v_add_u32_e32 v39, 0x1000, v6
	ds_write2_b32 v39, v73, v74 offset0:32 offset1:98
	ds_write2_b32 v39, v75, v76 offset0:164 offset1:230
	v_add_u32_e32 v39, 0x1400, v6
	ds_write2_b32 v39, v77, v78 offset0:40 offset1:106
	ds_write2_b32 v39, v79, v54 offset0:172 offset1:238
	v_add_u32_e32 v39, 0x1800, v6
	ds_write2_b32 v39, v40, v41 offset0:48 offset1:114
	ds_write2_b32 v39, v42, v43 offset0:180 offset1:246
	v_add_u32_e32 v39, 0x1c00, v6
	ds_write2_b32 v39, v44, v45 offset0:56 offset1:122
	ds_write2_b32 v39, v46, v38 offset0:188 offset1:254
	s_waitcnt lgkmcnt(0)
	ds_read2_b32 v[56:57], v33 offset1:33
	ds_read2_b32 v[60:61], v33 offset0:66 offset1:99
	ds_read2_b32 v[62:63], v33 offset0:132 offset1:165
	ds_read2_b32 v[64:65], v33 offset0:198 offset1:231
	ds_read2_b32 v[66:67], v33 offset0:8 offset1:41
	ds_read2_b32 v[68:69], v33 offset0:74 offset1:107
	ds_read2_b32 v[70:71], v33 offset0:140 offset1:173
	ds_read2_b32 v[72:73], v33 offset0:206 offset1:239
	s_waitcnt lgkmcnt(7)
	v_cvt_pk_bf16_f32 v38, v56, v57
	s_waitcnt lgkmcnt(6)
	v_cvt_pk_bf16_f32 v39, v60, v61
	s_waitcnt lgkmcnt(5)
	v_cvt_pk_bf16_f32 v40, v62, v63
	s_waitcnt lgkmcnt(4)
	v_cvt_pk_bf16_f32 v41, v64, v65
	v_add_u32_e32 v42, s40, v31
	v_ashrrev_i32_e32 v43, 31, v42
	v_lshl_add_u64 v[44:45], v[20:21], 0, s[28:29]
	v_lshlrev_b64 v[42:43], 12, v[42:43]
	v_lshl_add_u64 v[42:43], v[44:45], 0, v[42:43]
	global_store_dwordx4 v[42:43], v[38:41], off
	s_nop 1
	s_waitcnt lgkmcnt(3)
	s_nop 0
	v_cvt_pk_bf16_f32 v38, v66, v67
	s_waitcnt lgkmcnt(2)
	v_cvt_pk_bf16_f32 v39, v68, v69
	s_waitcnt lgkmcnt(1)
	v_cvt_pk_bf16_f32 v40, v70, v71
	s_waitcnt lgkmcnt(0)
	v_cvt_pk_bf16_f32 v41, v72, v73
	v_add_u32_e32 v42, s40, v35
	v_ashrrev_i32_e32 v43, 31, v42
	v_lshlrev_b64 v[42:43], 12, v[42:43]
	v_lshl_add_u64 v[42:43], v[44:45], 0, v[42:43]
	ds_read2_b32 v[56:57], v33 offset0:16 offset1:49
	ds_read2_b32 v[60:61], v33 offset0:82 offset1:115
	ds_read2_b32 v[62:63], v33 offset0:148 offset1:181
	ds_read2_b32 v[64:65], v33 offset0:214 offset1:247
	ds_read2_b32 v[66:67], v33 offset0:24 offset1:57
	ds_read2_b32 v[68:69], v33 offset0:90 offset1:123
	ds_read2_b32 v[70:71], v33 offset0:156 offset1:189
	ds_read2_b32 v[72:73], v33 offset0:222 offset1:255
	global_store_dwordx4 v[42:43], v[38:41], off
	s_nop 1
	s_waitcnt lgkmcnt(7)
	s_nop 0
	v_cvt_pk_bf16_f32 v38, v56, v57
	s_waitcnt lgkmcnt(6)
	v_cvt_pk_bf16_f32 v39, v60, v61
	s_waitcnt lgkmcnt(5)
	v_cvt_pk_bf16_f32 v40, v62, v63
	s_waitcnt lgkmcnt(4)
	v_cvt_pk_bf16_f32 v41, v64, v65
	v_add_u32_e32 v42, s40, v36
	v_ashrrev_i32_e32 v43, 31, v42
	v_lshlrev_b64 v[42:43], 12, v[42:43]
	v_lshl_add_u64 v[42:43], v[44:45], 0, v[42:43]
	global_store_dwordx4 v[42:43], v[38:41], off
	s_nop 1
	s_waitcnt lgkmcnt(3)
	s_nop 0
	v_cvt_pk_bf16_f32 v38, v66, v67
	s_waitcnt lgkmcnt(2)
	v_cvt_pk_bf16_f32 v39, v68, v69
	s_waitcnt lgkmcnt(1)
	v_cvt_pk_bf16_f32 v40, v70, v71
	s_waitcnt lgkmcnt(0)
	v_cvt_pk_bf16_f32 v41, v72, v73
	v_add_u32_e32 v42, s40, v37
	v_ashrrev_i32_e32 v43, 31, v42
	v_lshlrev_b64 v[42:43], 12, v[42:43]
	v_lshl_add_u64 v[42:43], v[44:45], 0, v[42:43]
	global_store_dwordx4 v[42:43], v[38:41], off
	s_nop 1
	s_waitcnt lgkmcnt(0)

; #define LAS __attribute__((address_space(3)))
; __device__ __forceinline__ void tr_item(const float* __restrict__ W, int K, int N, bf16_t* __restrict__ WT, int dst_row0, int src_col0, int k0, LAS float* scr, int lane) {
;     if (src_col0 >= 0) {
;         const float* wp = W + (size_t)(k0 + (lane >> 5)) * N + src_col0 + (lane & 31);
;         float t[32];
; #pragma unroll
;         for (int i = 0; i < 32; ++i) t[i] = __builtin_nontemporal_load(wp + (size_t)(2 * i) * N);
; #pragma unroll
;         for (int i = 0; i < 32; ++i) scr[(2 * i + (lane >> 5)) * 33 + (lane & 31)] = t[i];
; __global__ void __launch_bounds__(512, 2) mk_fwd(Args a) {
;     ...
;                     if (it < items_in) { const int kb = it / nblk_in, nb = it - kb * nblk_in; const int j = nb * 32; int src;
;                         if (j < 2304) src = j; else if (j < 5376) src = j + 64; else if (j < 5440) src = 2304 + (j - 5376); else if (j < 5632) src = -1; else src = 5440 + (j - 5632);
;                         tr_item(win, DM, NIN, W0, j, src, kb * 64, scr, lane); continue; }
.LBB0_925:
	s_lshl_b32 s40, s13, 6
	s_and_b64 vcc, exec, s[46:47]
	s_cbranch_vccz .LBB0_877
	v_add_u32_e32 v40, s40, v0
	v_mov_b64_e32 v[38:39], s[0:1]
	s_mov_b32 s13, 0xb500
	v_mad_i64_i32 v[38:39], s[28:29], v40, s13, v[38:39]
	s_mov_b32 s45, s12
	v_lshl_add_u64 v[38:39], s[44:45], 2, v[38:39]
	v_lshlrev_b32_e32 v144, 2, v2
	v_lshl_add_u64 v[38:39], v[38:39], 0, v[144:145]
	v_add_co_u32_e32 v40, vcc, 0x16000, v38
	s_mov_b32 s4, 0xf8000
	s_nop 0
	v_addc_co_u32_e32 v41, vcc, 0, v39, vcc
	v_add_co_u32_e32 v42, vcc, 0x2d000, v38
	s_nop 1
	v_addc_co_u32_e32 v43, vcc, 0, v39, vcc
	v_add_co_u32_e32 v44, vcc, 0x43000, v38
	s_nop 1
	v_addc_co_u32_e32 v45, vcc, 0, v39, vcc
	v_add_co_u32_e32 v46, vcc, 0x5a000, v38
	s_nop 1
	v_addc_co_u32_e32 v47, vcc, 0, v39, vcc
	s_waitcnt vmcnt(0)
	v_add_co_u32_e32 v48, vcc, 0x71000, v38
	s_nop 1
	v_addc_co_u32_e32 v49, vcc, 0, v39, vcc
	v_add_co_u32_e32 v50, vcc, 0x87000, v38
	s_nop 1
	v_addc_co_u32_e32 v51, vcc, 0, v39, vcc
	v_add_co_u32_e32 v52, vcc, 0x9e000, v38
	s_nop 1
	v_addc_co_u32_e32 v53, vcc, 0, v39, vcc
	global_load_dword v56, v[38:39], off nt
	global_load_dword v57, v[40:41], off offset:2560 nt
	global_load_dword v59, v[42:43], off offset:1024 nt
	global_load_dword v60, v[44:45], off offset:3584 nt
	global_load_dword v61, v[46:47], off offset:2048 nt
	global_load_dword v62, v[48:49], off offset:512 nt
	global_load_dword v63, v[50:51], off offset:3072 nt
	global_load_dword v64, v[52:53], off offset:1536 nt
	v_add_co_u32_e32 v40, vcc, 0xb5000, v38
	s_nop 1
	v_addc_co_u32_e32 v41, vcc, 0, v39, vcc
	v_add_co_u32_e32 v42, vcc, 0xcb000, v38
	s_nop 1
	v_addc_co_u32_e32 v43, vcc, 0, v39, vcc
	v_add_co_u32_e32 v44, vcc, 0xe2000, v38
	s_nop 1
	v_addc_co_u32_e32 v45, vcc, 0, v39, vcc
	v_add_co_u32_e32 v46, vcc, s4, v38
	s_nop 1
	v_addc_co_u32_e32 v47, vcc, 0, v39, vcc
	v_add_co_u32_e32 v48, vcc, 0x10f000, v38
	s_nop 1
	v_addc_co_u32_e32 v49, vcc, 0, v39, vcc
	v_add_co_u32_e32 v50, vcc, 0x126000, v38
	s_nop 1
	v_addc_co_u32_e32 v51, vcc, 0, v39, vcc
	v_add_co_u32_e32 v52, vcc, 0x13c000, v38
	s_nop 1
	v_addc_co_u32_e32 v53, vcc, 0, v39, vcc
	v_add_co_u32_e32 v54, vcc, 0x153000, v38
	s_nop 1
	v_addc_co_u32_e32 v55, vcc, 0, v39, vcc
	global_load_dword v65, v[40:41], off nt
	global_load_dword v66, v[42:43], off offset:2560 nt
	global_load_dword v67, v[44:45], off offset:1024 nt
	global_load_dword v68, v[46:47], off offset:3584 nt
	global_load_dword v69, v[48:49], off offset:2048 nt
	global_load_dword v70, v[50:51], off offset:512 nt
	global_load_dword v71, v[52:53], off offset:3072 nt
	global_load_dword v72, v[54:55], off offset:1536 nt
	v_add_co_u32_e32 v40, vcc, 0x16a000, v38
	s_nop 1
	v_addc_co_u32_e32 v41, vcc, 0, v39, vcc
	v_add_co_u32_e32 v42, vcc, 0x180000, v38
	s_nop 1
	v_addc_co_u32_e32 v43, vcc, 0, v39, vcc
	v_add_co_u32_e32 v44, vcc, 0x197000, v38
	s_nop 1
	v_addc_co_u32_e32 v45, vcc, 0, v39, vcc
	v_add_co_u32_e32 v46, vcc, 0x1ad000, v38
	s_nop 1
	v_addc_co_u32_e32 v47, vcc, 0, v39, vcc
	v_add_co_u32_e32 v48, vcc, 0x1c4000, v38
	s_nop 1
	v_addc_co_u32_e32 v49, vcc, 0, v39, vcc
	v_add_co_u32_e32 v50, vcc, 0x1db000, v38
	s_nop 1
	v_addc_co_u32_e32 v51, vcc, 0, v39, vcc
	v_add_co_u32_e32 v52, vcc, 0x1f1000, v38
	s_nop 1
	v_addc_co_u32_e32 v53, vcc, 0, v39, vcc
	v_add_co_u32_e32 v54, vcc, 0x208000, v38
	s_nop 1
	v_addc_co_u32_e32 v55, vcc, 0, v39, vcc
	global_load_dword v73, v[40:41], off nt
	global_load_dword v74, v[42:43], off offset:2560 nt
	global_load_dword v75, v[44:45], off offset:1024 nt
	global_load_dword v76, v[46:47], off offset:3584 nt
	global_load_dword v77, v[48:49], off offset:2048 nt
	global_load_dword v78, v[50:51], off offset:512 nt
	global_load_dword v79, v[52:53], off offset:3072 nt
	global_load_dword v54, v[54:55], off offset:1536 nt
	v_add_co_u32_e32 v40, vcc, 0x21f000, v38
	s_nop 1
	v_addc_co_u32_e32 v41, vcc, 0, v39, vcc
	v_add_co_u32_e32 v42, vcc, 0x235000, v38
	s_nop 1
	v_addc_co_u32_e32 v43, vcc, 0, v39, vcc
	v_add_co_u32_e32 v44, vcc, 0x24c000, v38
	s_nop 1
	v_addc_co_u32_e32 v45, vcc, 0, v39, vcc
	v_add_co_u32_e32 v46, vcc, 0x262000, v38
	s_nop 1
	v_addc_co_u32_e32 v47, vcc, 0, v39, vcc
	v_add_co_u32_e32 v48, vcc, 0x279000, v38
	s_nop 1
	v_addc_co_u32_e32 v49, vcc, 0, v39, vcc
	v_add_co_u32_e32 v50, vcc, 0x290000, v38
	s_nop 1
	v_addc_co_u32_e32 v51, vcc, 0, v39, vcc
	v_add_co_u32_e32 v52, vcc, 0x2a6000, v38
	s_nop 1
	v_addc_co_u32_e32 v53, vcc, 0, v39, vcc
	v_add_co_u32_e32 v38, vcc, 0x2bd000, v38
	s_nop 1
	v_addc_co_u32_e32 v39, vcc, 0, v39, vcc
	global_load_dword v40, v[40:41], off nt
	global_load_dword v41, v[42:43], off offset:2560 nt
	global_load_dword v42, v[44:45], off offset:1024 nt
	global_load_dword v43, v[46:47], off offset:3584 nt
	global_load_dword v44, v[48:49], off offset:2048 nt
	global_load_dword v45, v[50:51], off offset:512 nt
	global_load_dword v46, v[52:53], off offset:3072 nt
	global_load_dword v38, v[38:39], off offset:1536 nt
	v_add_u32_e32 v39, 0x400, v6
	s_waitcnt vmcnt(0)
	ds_write2_b32 v6, v56, v57 offset1:66
	ds_write2_b32 v6, v59, v60 offset0:132 offset1:198
	ds_write2_b32 v39, v61, v62 offset0:8 offset1:74
	ds_write2_b32 v39, v63, v64 offset0:140 offset1:206
	v_add_u32_e32 v39, 0x800, v6
	ds_write2_b32 v39, v65, v66 offset0:16 offset1:82
	ds_write2_b32 v39, v67, v68 offset0:148 offset1:214
	v_add_u32_e32 v39, 0xc00, v6
	ds_write2_b32 v39, v69, v70 offset0:24 offset1:90
	ds_write2_b32 v39, v71, v72 offset0:156 offset1:222
	v_add_u32_e32 v39, 0x1000, v6
	ds_write2_b32 v39, v73, v74 offset0:32 offset1:98
	ds_write2_b32 v39, v75, v76 offset0:164 offset1:230
	v_add_u32_e32 v39, 0x1400, v6
	ds_write2_b32 v39, v77, v78 offset0:40 offset1:106
	ds_write2_b32 v39, v79, v54 offset0:172 offset1:238
	v_add_u32_e32 v39, 0x1800, v6
	ds_write2_b32 v39, v40, v41 offset0:48 offset1:114
	ds_write2_b32 v39, v42, v43 offset0:180 offset1:246
	v_add_u32_e32 v39, 0x1c00, v6
	ds_write2_b32 v39, v44, v45 offset0:56 offset1:122
	ds_write2_b32 v39, v46, v38 offset0:188 offset1:254
	s_branch .LBB0_877

; #define LAS __attribute__((address_space(3)))
; __device__ __forceinline__ void tr_item(const float* __restrict__ W, int K, int N, bf16_t* __restrict__ WT, int dst_row0, int src_col0, int k0, LAS float* scr, int lane) {
;     if (src_col0 >= 0) {
;         const float* wp = W + (size_t)(k0 + (lane >> 5)) * N + src_col0 + (lane & 31);
;         float t[32];
; #pragma unroll
;         for (int i = 0; i < 32; ++i) t[i] = __builtin_nontemporal_load(wp + (size_t)(2 * i) * N);
.LBB0_928:
	s_and_b32 s18, s7, 0x3c0
	v_add_u32_e32 v38, s18, v0
	s_lshl_b32 s13, s7, 5
	v_ashrrev_i32_e32 v39, 31, v38
	s_and_b32 s13, s13, 0x7e0
	v_lshlrev_b64 v[38:39], 13, v[38:39]
	v_lshl_add_u64 v[38:39], s[36:37], 0, v[38:39]
	s_lshl_b32 s28, s13, 2
	s_mov_b32 s29, s12
	v_lshl_add_u64 v[38:39], v[38:39], 0, s[28:29]
	v_lshlrev_b32_e32 v144, 2, v2
	v_lshl_add_u64 v[38:39], v[38:39], 0, v[144:145]
	s_movk_i32 s4, 0x4000
	v_add_co_u32_e32 v40, vcc, s4, v38
	s_mov_b32 s4, 0x8000
	s_nop 0
	v_addc_co_u32_e32 v41, vcc, 0, v39, vcc
	v_add_co_u32_e32 v42, vcc, s4, v38
	s_mov_b32 s4, 0xc000
	s_nop 0
	v_addc_co_u32_e32 v43, vcc, 0, v39, vcc
	v_add_co_u32_e32 v44, vcc, s4, v38
	s_mov_b32 s4, 0x14000
	s_nop 0
	v_addc_co_u32_e32 v45, vcc, 0, v39, vcc
	v_add_co_u32_e32 v46, vcc, s52, v38
	s_lshl_b32 s28, s18, 1
	s_nop 0
	v_addc_co_u32_e32 v47, vcc, 0, v39, vcc
	s_waitcnt vmcnt(0)
	v_add_co_u32_e32 v48, vcc, s4, v38
	s_mov_b32 s4, 0x18000
	s_nop 0
	v_addc_co_u32_e32 v49, vcc, 0, v39, vcc
	v_add_co_u32_e32 v50, vcc, s4, v38
	s_mov_b32 s4, 0x1c000
	s_nop 0
	v_addc_co_u32_e32 v51, vcc, 0, v39, vcc
	v_add_co_u32_e32 v52, vcc, s4, v38
	s_mov_b32 s4, 0x20000
	s_nop 0
	v_addc_co_u32_e32 v53, vcc, 0, v39, vcc
	global_load_dword v56, v[38:39], off nt
	global_load_dword v57, v[40:41], off nt
	global_load_dword v59, v[42:43], off nt
	global_load_dword v60, v[44:45], off nt
	global_load_dword v61, v[46:47], off nt
	global_load_dword v62, v[48:49], off nt
	global_load_dword v63, v[50:51], off nt
	global_load_dword v64, v[52:53], off nt
	v_add_co_u32_e32 v40, vcc, s4, v38
	s_mov_b32 s4, 0x24000
	s_nop 0
	v_addc_co_u32_e32 v41, vcc, 0, v39, vcc
	v_add_co_u32_e32 v42, vcc, s4, v38
	s_mov_b32 s4, 0x28000
	s_nop 0
	v_addc_co_u32_e32 v43, vcc, 0, v39, vcc
	v_add_co_u32_e32 v44, vcc, s4, v38
	s_mov_b32 s4, 0x2c000
	s_nop 0
	v_addc_co_u32_e32 v45, vcc, 0, v39, vcc
	v_add_co_u32_e32 v46, vcc, s4, v38
	s_mov_b32 s4, 0x30000
	s_nop 0
	v_addc_co_u32_e32 v47, vcc, 0, v39, vcc
	v_add_co_u32_e32 v48, vcc, s4, v38
	s_mov_b32 s4, 0x34000
	s_nop 0
	v_addc_co_u32_e32 v49, vcc, 0, v39, vcc
	v_add_co_u32_e32 v50, vcc, s4, v38
	s_mov_b32 s4, 0x38000
	s_nop 0
	v_addc_co_u32_e32 v51, vcc, 0, v39, vcc
	v_add_co_u32_e32 v52, vcc, s4, v38
	s_mov_b32 s4, 0x3c000
	s_nop 0
	v_addc_co_u32_e32 v53, vcc, 0, v39, vcc
	v_add_co_u32_e32 v54, vcc, s4, v38
	s_mov_b32 s4, 0x40000
	s_nop 0
	v_addc_co_u32_e32 v55, vcc, 0, v39, vcc
	global_load_dword v65, v[40:41], off nt
	global_load_dword v66, v[42:43], off nt
	global_load_dword v67, v[44:45], off nt
	global_load_dword v68, v[46:47], off nt
	global_load_dword v69, v[48:49], off nt
	global_load_dword v70, v[50:51], off nt
	global_load_dword v71, v[52:53], off nt
	global_load_dword v72, v[54:55], off nt
	v_add_co_u32_e32 v40, vcc, s4, v38
	s_mov_b32 s4, 0x44000
	s_nop 0
	v_addc_co_u32_e32 v41, vcc, 0, v39, vcc
	v_add_co_u32_e32 v42, vcc, s4, v38
	s_mov_b32 s4, 0x48000
	s_nop 0
	v_addc_co_u32_e32 v43, vcc, 0, v39, vcc
	v_add_co_u32_e32 v44, vcc, s4, v38
	s_mov_b32 s4, 0x4c000
	s_nop 0
	v_addc_co_u32_e32 v45, vcc, 0, v39, vcc
	v_add_co_u32_e32 v46, vcc, s4, v38
	s_mov_b32 s4, 0x50000
	s_nop 0
	v_addc_co_u32_e32 v47, vcc, 0, v39, vcc
	v_add_co_u32_e32 v48, vcc, s4, v38
	s_mov_b32 s4, 0x54000
	s_nop 0
	v_addc_co_u32_e32 v49, vcc, 0, v39, vcc
	v_add_co_u32_e32 v50, vcc, s4, v38
	s_mov_b32 s4, 0x58000
	s_nop 0
	v_addc_co_u32_e32 v51, vcc, 0, v39, vcc
	v_add_co_u32_e32 v52, vcc, s4, v38
	s_mov_b32 s4, 0x5c000
	s_nop 0
	v_addc_co_u32_e32 v53, vcc, 0, v39, vcc
	v_add_co_u32_e32 v54, vcc, s4, v38
	s_mov_b32 s4, 0x60000
	s_nop 0
	v_addc_co_u32_e32 v55, vcc, 0, v39, vcc
	global_load_dword v73, v[40:41], off nt
	global_load_dword v74, v[42:43], off nt
	global_load_dword v75, v[44:45], off nt
	global_load_dword v76, v[46:47], off nt
	global_load_dword v77, v[48:49], off nt
	global_load_dword v78, v[50:51], off nt
	global_load_dword v79, v[52:53], off nt
	global_load_dword v54, v[54:55], off nt
	v_add_co_u32_e32 v40, vcc, s4, v38
	s_mov_b32 s4, 0x64000
	s_nop 0
	v_addc_co_u32_e32 v41, vcc, 0, v39, vcc
	v_add_co_u32_e32 v42, vcc, s4, v38
	s_mov_b32 s4, 0x68000
	s_nop 0
	v_addc_co_u32_e32 v43, vcc, 0, v39, vcc
	v_add_co_u32_e32 v44, vcc, s4, v38
	s_mov_b32 s4, 0x6c000
	s_nop 0
	v_addc_co_u32_e32 v45, vcc, 0, v39, vcc
	v_add_co_u32_e32 v46, vcc, s4, v38
	s_mov_b32 s4, 0x70000
	s_nop 0
	v_addc_co_u32_e32 v47, vcc, 0, v39, vcc
	v_add_co_u32_e32 v48, vcc, s4, v38
	s_mov_b32 s4, 0x74000
	s_nop 0
	v_addc_co_u32_e32 v49, vcc, 0, v39, vcc
	v_add_co_u32_e32 v50, vcc, s4, v38
	s_mov_b32 s4, 0x78000
	s_nop 0
	v_addc_co_u32_e32 v51, vcc, 0, v39, vcc
	v_add_co_u32_e32 v52, vcc, s4, v38
	s_mov_b32 s4, 0x7c000
	s_nop 0
	v_addc_co_u32_e32 v53, vcc, 0, v39, vcc
	v_add_co_u32_e32 v38, vcc, s4, v38
	s_nop 1
	v_addc_co_u32_e32 v39, vcc, 0, v39, vcc
	global_load_dword v40, v[40:41], off nt
	global_load_dword v41, v[42:43], off nt
	global_load_dword v42, v[44:45], off nt
	global_load_dword v43, v[46:47], off nt
	global_load_dword v44, v[48:49], off nt
	global_load_dword v45, v[50:51], off nt
	global_load_dword v46, v[52:53], off nt
	global_load_dword v38, v[38:39], off nt
	v_add_u32_e32 v39, 0x400, v6
	s_waitcnt vmcnt(0)
; #define LAS __attribute__((address_space(3)))
; __device__ __forceinline__ unsigned cvt_pk_bf16(float lo, float hi) { unsigned r; asm volatile("v_cvt_pk_bf16_f32 %0, %1, %2" : "=v"(r) : "v"(lo), "v"(hi)); return r; }
; #define LDS_WAIT() asm volatile("s_waitcnt lgkmcnt(0)" ::: "memory")
; __device__ __forceinline__ void tr_item(const float* __restrict__ W, int K, int N, bf16_t* __restrict__ WT, int dst_row0, int src_col0, int k0, LAS float* scr, int lane) {
;     ...
;         for (int i = 0; i < 32; ++i) scr[(2 * i + (lane >> 5)) * 33 + (lane & 31)] = t[i];
;     } else {
; #pragma unroll 8
;         for (int i = 0; i < 32; ++i) { const int kk = 2 * i + (lane >> 5); scr[kk * 33 + (lane & 31)] = 0.f; }
;     }
;     LDS_WAIT(); asm volatile("" ::: "memory");
;     const int c = lane & 7;
; #pragma unroll
;     for (int j = 0; j < 4; ++j) { const int n = (lane >> 3) + 8 * j; const LAS float* s = scr + (8 * c) * 33 + n;
;         u32x4 o; o.x = cvt_pk_bf16(s[0 * 33], s[1 * 33]); o.y = cvt_pk_bf16(s[2 * 33], s[3 * 33]); o.z = cvt_pk_bf16(s[4 * 33], s[5 * 33]); o.w = cvt_pk_bf16(s[6 * 33], s[7 * 33]);
;         *(u32x4*)(WT + (size_t)(dst_row0 + n) * K + k0 + 8 * c) = o; }
;     LDS_WAIT(); asm volatile("" ::: "memory");
	ds_write2_b32 v6, v56, v57 offset1:66
	ds_write2_b32 v6, v59, v60 offset0:132 offset1:198
	ds_write2_b32 v39, v61, v62 offset0:8 offset1:74
	ds_write2_b32 v39, v63, v64 offset0:140 offset1:206
	v_add_u32_e32 v39, 0x800, v6
	ds_write2_b32 v39, v65, v66 offset0:16 offset1:82
	ds_write2_b32 v39, v67, v68 offset0:148 offset1:214
	v_add_u32_e32 v39, 0xc00, v6
	ds_write2_b32 v39, v69, v70 offset0:24 offset1:90
	ds_write2_b32 v39, v71, v72 offset0:156 offset1:222
	v_add_u32_e32 v39, 0x1000, v6
	ds_write2_b32 v39, v73, v74 offset0:32 offset1:98
	ds_write2_b32 v39, v75, v76 offset0:164 offset1:230
	v_add_u32_e32 v39, 0x1400, v6
	ds_write2_b32 v39, v77, v78 offset0:40 offset1:106
	ds_write2_b32 v39, v79, v54 offset0:172 offset1:238
	v_add_u32_e32 v39, 0x1800, v6
	ds_write2_b32 v39, v40, v41 offset0:48 offset1:114
	ds_write2_b32 v39, v42, v43 offset0:180 offset1:246
	v_add_u32_e32 v39, 0x1c00, v6
	ds_write2_b32 v39, v44, v45 offset0:56 offset1:122
	ds_write2_b32 v39, v46, v38 offset0:188 offset1:254
	s_waitcnt lgkmcnt(0)
	ds_read2_b32 v[56:57], v33 offset1:33
	ds_read2_b32 v[60:61], v33 offset0:66 offset1:99
	ds_read2_b32 v[62:63], v33 offset0:132 offset1:165
	ds_read2_b32 v[64:65], v33 offset0:198 offset1:231
	ds_read2_b32 v[66:67], v33 offset0:8 offset1:41
	ds_read2_b32 v[68:69], v33 offset0:74 offset1:107
	ds_read2_b32 v[70:71], v33 offset0:140 offset1:173
	ds_read2_b32 v[72:73], v33 offset0:206 offset1:239
	s_waitcnt lgkmcnt(7)
	v_cvt_pk_bf16_f32 v38, v56, v57
	s_waitcnt lgkmcnt(6)
	v_cvt_pk_bf16_f32 v39, v60, v61
	s_waitcnt lgkmcnt(5)
	v_cvt_pk_bf16_f32 v40, v62, v63
	s_waitcnt lgkmcnt(4)
	v_cvt_pk_bf16_f32 v41, v64, v65
	v_add_u32_e32 v42, s13, v31
	v_ashrrev_i32_e32 v43, 31, v42
	v_lshl_add_u64 v[44:45], v[18:19], 0, s[28:29]
	v_lshlrev_b64 v[42:43], 11, v[42:43]
	v_lshl_add_u64 v[42:43], v[44:45], 0, v[42:43]
	global_store_dwordx4 v[42:43], v[38:41], off
	s_nop 1
	s_waitcnt lgkmcnt(3)
	s_nop 0
	v_cvt_pk_bf16_f32 v38, v66, v67
	s_waitcnt lgkmcnt(2)
	v_cvt_pk_bf16_f32 v39, v68, v69
	s_waitcnt lgkmcnt(1)
	v_cvt_pk_bf16_f32 v40, v70, v71
	s_waitcnt lgkmcnt(0)
	v_cvt_pk_bf16_f32 v41, v72, v73
	v_add_u32_e32 v42, s13, v35
	v_ashrrev_i32_e32 v43, 31, v42
	v_lshlrev_b64 v[42:43], 11, v[42:43]
	v_lshl_add_u64 v[42:43], v[44:45], 0, v[42:43]
	ds_read2_b32 v[56:57], v33 offset0:16 offset1:49
	ds_read2_b32 v[60:61], v33 offset0:82 offset1:115
	ds_read2_b32 v[62:63], v33 offset0:148 offset1:181
	ds_read2_b32 v[64:65], v33 offset0:214 offset1:247
	ds_read2_b32 v[66:67], v33 offset0:24 offset1:57
	ds_read2_b32 v[68:69], v33 offset0:90 offset1:123
	ds_read2_b32 v[70:71], v33 offset0:156 offset1:189
	ds_read2_b32 v[72:73], v33 offset0:222 offset1:255
	global_store_dwordx4 v[42:43], v[38:41], off
	s_nop 1
	s_waitcnt lgkmcnt(7)
	s_nop 0
	v_cvt_pk_bf16_f32 v38, v56, v57
	s_waitcnt lgkmcnt(6)
	v_cvt_pk_bf16_f32 v39, v60, v61
	s_waitcnt lgkmcnt(5)
	v_cvt_pk_bf16_f32 v40, v62, v63
	s_waitcnt lgkmcnt(4)
	v_cvt_pk_bf16_f32 v41, v64, v65
	v_add_u32_e32 v42, s13, v36
	v_ashrrev_i32_e32 v43, 31, v42
	v_lshlrev_b64 v[42:43], 11, v[42:43]
	v_lshl_add_u64 v[42:43], v[44:45], 0, v[42:43]
	global_store_dwordx4 v[42:43], v[38:41], off
	s_nop 1
	s_waitcnt lgkmcnt(3)
	s_nop 0
	v_cvt_pk_bf16_f32 v38, v66, v67
	s_waitcnt lgkmcnt(2)
	v_cvt_pk_bf16_f32 v39, v68, v69
	s_waitcnt lgkmcnt(1)
	v_cvt_pk_bf16_f32 v40, v70, v71
	s_waitcnt lgkmcnt(0)
	v_cvt_pk_bf16_f32 v41, v72, v73
	v_add_u32_e32 v42, s13, v37
	v_ashrrev_i32_e32 v43, 31, v42
	v_lshlrev_b64 v[42:43], 11, v[42:43]
	v_lshl_add_u64 v[42:43], v[44:45], 0, v[42:43]
	global_store_dwordx4 v[42:43], v[38:41], off
	s_nop 1
	s_waitcnt lgkmcnt(0)
	s_mov_b32 s13, s7
	s_andn2_b64 vcc, exec, s[40:41]
	s_cbranch_vccz .LBB0_910
	s_branch .LBB0_911

; __device__ __forceinline__ u32x4 pack8(f32x4 v0, f32x4 v1) { u32x4 w; w.x = cvt_pk_bf16(v0[0], v0[1]); w.y = cvt_pk_bf16(v0[2], v0[3]); w.z = cvt_pk_bf16(v1[0], v1[1]); w.w = cvt_pk_bf16(v1[2], v1[3]); return w; }
; __global__ void __launch_bounds__(512, 2) mk_fwd(Args a) {
;     ...
;                 for (int r = gw; r < LSEQ; r += NGW) {
;                     f32x4 v[8]; float s = 0.f; const float* hr = H + (size_t)r * DM;
; #pragma unroll
;                     for (int j = 0; j < 8; ++j) { v[j] = *(const f32x4*)(hr + (lane + 64 * (j >> 1)) * 8 + (j & 1) * 4); s += (v[j].x * v[j].x + v[j].y * v[j].y) + (v[j].z * v[j].z + v[j].w * v[j].w); }
;                     const float rs = __builtin_amdgcn_rsqf(wave_sum(s, lane) * (1.f / DM) + EPS);
; #pragma unroll
;                     for (int j = 0; j < 4; ++j) { const int c = (lane + 64 * j) * 8; const f32x4 g0 = *(const f32x4*)(gm + c), g1 = *(const f32x4*)(gm + c + 4);
;                         *(u32x4*)(X + (size_t)r * DM + c) = pg8::pack8(v[2 * j] * rs * g0, v[2 * j + 1] * rs * g1); }
;                 }
.LBB0_931:
	s_waitcnt lgkmcnt(0)
	v_pk_mul_f32 v[6:7], v[38:39], v[38:39]
	v_pk_mul_f32 v[8:9], v[0:1], v[0:1]
	v_pk_mul_f32 v[4:5], v[2:3], v[2:3]
	v_mov_b32_e32 v10, v8
	v_mov_b32_e32 v11, v6
	v_mov_b32_e32 v6, v9
	v_pk_mul_f32 v[8:9], v[40:41], v[40:41]
	v_pk_add_f32 v[6:7], v[10:11], v[6:7]
	v_mov_b32_e32 v10, v4
	v_mov_b32_e32 v11, v8
	v_mov_b32_e32 v8, v5
	v_pk_add_f32 v[8:9], v[10:11], v[8:9]
	s_waitcnt vmcnt(0)
	v_pk_mul_f32 v[4:5], v[52:53], v[52:53]
	v_pk_mul_f32 v[10:11], v[50:51], v[50:51]
	v_pk_add_f32 v[6:7], v[6:7], v[8:9]
	v_pk_mov_b32 v[8:9], v[10:11], v[4:5] op_sel:[1,0]
	v_mov_b32_e32 v11, v5
	v_mul_f32_e32 v4, v54, v54
	v_pk_add_f32 v[18:19], v[6:7], v[6:7] op_sel:[0,1] op_sel_hi:[1,0]
	v_pk_add_f32 v[16:17], v[8:9], v[10:11]
	v_mov_b32_e32 v19, v4
	global_load_dwordx4 v[4:7], v[60:61], off
	global_load_dwordx4 v[8:11], v[60:61], off offset:16
	v_mul_f32_e32 v20, v55, v55
	v_pk_add_f32 v[16:17], v[16:17], v[16:17] op_sel:[0,1] op_sel_hi:[1,0]
	v_mul_f32_e32 v21, v56, v56
	v_mov_b32_e32 v17, v20
	v_pk_add_f32 v[16:17], v[18:19], v[16:17]
	v_mul_f32_e32 v18, v43, v43
	v_pk_fma_f32 v[18:19], v[42:43], v[42:43], v[18:19] op_sel_hi:[1,1,0]
	v_mul_f32_e32 v20, v45, v45
	v_mul_f32_e32 v22, v57, v57
	v_mov_b32_e32 v19, v21
	v_pk_fma_f32 v[20:21], v[44:45], v[44:45], v[20:21] op_sel_hi:[1,1,0]
	v_pk_mul_f32 v[12:13], v[48:49], v[48:49]
	v_mov_b32_e32 v21, v22
	v_pk_mul_f32 v[14:15], v[46:47], v[46:47]
	v_pk_add_f32 v[18:19], v[18:19], v[20:21]
	v_mul_f32_e32 v20, v32, v32
	v_pk_add_f32 v[16:17], v[16:17], v[18:19]
	v_pk_mov_b32 v[18:19], v[14:15], v[12:13] op_sel:[1,0]
	v_mov_b32_e32 v15, v13
	v_pk_add_f32 v[12:13], v[18:19], v[14:15]
	v_mul_f32_e32 v18, v30, v30
	v_mul_f32_e32 v19, v31, v31
	v_pk_add_f32 v[14:15], v[16:17], v[16:17] op_sel:[0,1] op_sel_hi:[1,0]
	v_pk_add_f32 v[12:13], v[12:13], v[12:13] op_sel:[0,1] op_sel_hi:[1,0]
	v_mov_b32_e32 v15, v18
	v_mov_b32_e32 v13, v19
	v_pk_add_f32 v[12:13], v[14:15], v[12:13]
	v_mul_f32_e32 v14, v35, v35
	v_mul_f32_e32 v16, v37, v37
	v_mul_f32_e32 v21, v33, v33
	v_pk_fma_f32 v[14:15], v[34:35], v[34:35], v[14:15] op_sel_hi:[1,1,0]
	v_pk_fma_f32 v[16:17], v[36:37], v[36:37], v[16:17] op_sel_hi:[1,1,0]
	v_mov_b32_e32 v15, v20
	v_mov_b32_e32 v17, v21
	v_pk_add_f32 v[14:15], v[14:15], v[16:17]
	s_add_i32 s6, s6, s72
	v_pk_add_f32 v[12:13], v[12:13], v[14:15]
	s_add_u32 s2, s2, s28
	v_add_f32_e32 v12, v12, v13
	ds_bpermute_b32 v13, v78, v12
	s_addc_u32 s3, s3, s29
	v_lshl_add_u64 v[72:73], v[72:73], 0, s[28:29]
	v_lshl_add_u64 v[74:75], v[74:75], 0, s[28:29]
	s_cmpk_gt_i32 s6, 0x200f
	s_waitcnt lgkmcnt(0)
	v_add_f32_e32 v12, v12, v13
	ds_bpermute_b32 v13, v79, v12
	v_lshl_add_u64 v[76:77], v[76:77], 0, s[28:29]
	s_waitcnt lgkmcnt(0)
	v_add_f32_e32 v12, v12, v13
	ds_bpermute_b32 v13, v80, v12
	s_waitcnt lgkmcnt(0)
	v_add_f32_e32 v12, v12, v13
	ds_bpermute_b32 v13, v81, v12
	s_waitcnt lgkmcnt(0)
	v_add_f32_e32 v12, v12, v13
	ds_bpermute_b32 v13, v82, v12
	s_waitcnt lgkmcnt(0)
	v_add_f32_e32 v12, v12, v13
	ds_bpermute_b32 v13, v83, v12
	s_waitcnt lgkmcnt(0)
	v_add_f32_e32 v12, v12, v13
	v_fmamk_f32 v12, v12, 0x3a000000, v202
	v_rsq_f32_e32 v12, v12
	s_nop 0
	v_pk_mul_f32 v[0:1], v[12:13], v[0:1] op_sel_hi:[0,1]
	v_pk_mul_f32 v[2:3], v[12:13], v[2:3] op_sel_hi:[0,1]
	v_pk_mul_f32 v[16:17], v[12:13], v[40:41] op_sel_hi:[0,1]
	v_pk_mul_f32 v[14:15], v[12:13], v[38:39] op_sel_hi:[0,1]
	s_waitcnt vmcnt(1)
	v_pk_mul_f32 v[2:3], v[2:3], v[6:7]
	v_pk_mul_f32 v[0:1], v[0:1], v[4:5]
	s_waitcnt vmcnt(0)
	v_pk_mul_f32 v[4:5], v[16:17], v[10:11]
	v_pk_mul_f32 v[6:7], v[14:15], v[8:9]
	v_cvt_pk_bf16_f32 v0, v0, v1
	v_cvt_pk_bf16_f32 v1, v2, v3
	v_pk_mul_f32 v[10:11], v[12:13], v[50:51] op_sel_hi:[0,1]
	v_cvt_pk_bf16_f32 v2, v6, v7
	v_cvt_pk_bf16_f32 v3, v4, v5
	v_lshl_add_u64 v[4:5], s[64:65], 0, v[70:71]
	v_add_co_u32_e32 v8, vcc, s7, v4
	v_pk_mul_f32 v[14:15], v[12:13], v[52:53] op_sel_hi:[0,1]
	s_nop 0
	v_addc_co_u32_e32 v9, vcc, 0, v5, vcc
	global_store_dwordx4 v[8:9], v[0:3], off
	global_load_dwordx4 v[0:3], v[60:61], off offset:2048
	global_load_dwordx4 v[4:7], v[60:61], off offset:2064
	v_pk_mul_f32 v[16:17], v[12:13], v[42:43] op_sel_hi:[0,1]
	v_pk_mul_f32 v[18:19], v[12:13], v[44:45] op_sel_hi:[0,1]
	v_lshl_add_u64 v[70:71], v[70:71], 0, s[4:5]
	s_waitcnt vmcnt(0)
	v_pk_mul_f32 v[2:3], v[14:15], v[2:3]
	v_pk_mul_f32 v[0:1], v[10:11], v[0:1]
	v_pk_mul_f32 v[6:7], v[18:19], v[6:7]
	v_pk_mul_f32 v[4:5], v[16:17], v[4:5]
	v_cvt_pk_bf16_f32 v0, v0, v1
	v_cvt_pk_bf16_f32 v1, v2, v3
	v_pk_mul_f32 v[10:11], v[12:13], v[54:55] op_sel_hi:[0,1]
	v_cvt_pk_bf16_f32 v2, v4, v5
	v_cvt_pk_bf16_f32 v3, v6, v7
	global_store_dwordx4 v[8:9], v[0:3], off offset:1024
	global_load_dwordx4 v[0:3], v[66:67], off
	global_load_dwordx4 v[4:7], v[66:67], off offset:16
	v_pk_mul_f32 v[14:15], v[12:13], v[56:57] op_sel_hi:[0,1]
	v_pk_mul_f32 v[16:17], v[12:13], v[46:47] op_sel_hi:[0,1]
	v_pk_mul_f32 v[18:19], v[12:13], v[48:49] op_sel_hi:[0,1]
	s_waitcnt vmcnt(0)
	v_pk_mul_f32 v[2:3], v[14:15], v[2:3]
	v_pk_mul_f32 v[0:1], v[10:11], v[0:1]
	v_pk_mul_f32 v[6:7], v[18:19], v[6:7]
	v_pk_mul_f32 v[4:5], v[16:17], v[4:5]
	v_cvt_pk_bf16_f32 v0, v0, v1
	v_cvt_pk_bf16_f32 v1, v2, v3
	v_pk_mul_f32 v[10:11], v[12:13], v[34:35] op_sel_hi:[0,1]
	v_cvt_pk_bf16_f32 v2, v4, v5
	v_cvt_pk_bf16_f32 v3, v6, v7
	global_store_dwordx4 v[8:9], v[0:3], off offset:2048
	global_load_dwordx4 v[0:3], v[68:69], off
	global_load_dwordx4 v[4:7], v[68:69], off offset:16
	v_pk_mul_f32 v[14:15], v[12:13], v[36:37] op_sel_hi:[0,1]
	v_pk_mul_f32 v[16:17], v[12:13], v[30:31] op_sel_hi:[0,1]
	v_pk_mul_f32 v[12:13], v[12:13], v[32:33] op_sel_hi:[0,1]
	s_waitcnt vmcnt(0)
	v_pk_mul_f32 v[2:3], v[14:15], v[2:3]
	v_pk_mul_f32 v[0:1], v[10:11], v[0:1]
	v_pk_mul_f32 v[6:7], v[12:13], v[6:7]
	v_pk_mul_f32 v[4:5], v[16:17], v[4:5]
	v_cvt_pk_bf16_f32 v0, v0, v1
	v_cvt_pk_bf16_f32 v1, v2, v3
	s_nop 0
	v_cvt_pk_bf16_f32 v2, v4, v5
	v_cvt_pk_bf16_f32 v3, v6, v7
	global_store_dwordx4 v[8:9], v[0:3], off offset:3072
	s_cbranch_scc1 .LBB0_7
